# GEMM K-loops: raise prio before the opening barrier and drop prio after the closing barrier (shorter MFMA hand-over between the two half-workgroups)
# baseline (speedup 1.0000x reference)
; #define PG8_STAGE(bufoff, gbase, voff) do { _Pragma("unroll") for (int _i = 0; _i < 2; ++_i) \
;         __builtin_amdgcn_global_load_lds((const unsigned*)((const char*)(gbase) + (voff)[_i]), (PG8_LAS unsigned*)(lds + (bufoff) + ldsw + _i * 8192), 16, 0, 0); } while (0)
; #define PG8_LDA(dst, b, h) do { _Pragma("unroll") for (int m = 0; m < 4; ++m) _Pragma("unroll") for (int k = 0; k < 2; ++k) dst[m][k] = *(const PG8_LAS bf16x8*)(lds + PG8_SA(b, h) + aoff + m * 2048 + k * 1024); } while (0)
; #define PG8_LDB(dst, b, h) do { _Pragma("unroll") for (int n = 0; n < 2; ++n) _Pragma("unroll") for (int k = 0; k < 2; ++k) dst[n][k] = *(const PG8_LAS bf16x8*)(lds + PG8_SB(b, h) + boff + n * 2048 + k * 1024); } while (0)
; #define PG8_MMA(ai, bj, At, Bt) do { __builtin_amdgcn_s_setprio(1); _Pragma("unroll") for (int m = 0; m < 4; ++m) _Pragma("unroll") for (int n = 0; n < 2; ++n) _Pragma("unroll") for (int k = 0; k < 2; ++k) \
;         acc[ai][bj][m][n] = __builtin_amdgcn_mfma_f32_16x16x32_bf16(Bt[n][k], At[m][k], acc[ai][bj][m][n], 0, 0, 0); __builtin_amdgcn_s_setprio(0); } while (0)
; #define PG8_WAIT_V(n) asm volatile("s_waitcnt vmcnt(" #n ")" ::: "memory")
; #define PG8_WAIT_L(n) asm volatile("s_waitcnt lgkmcnt(" #n ")" ::: "memory")
; #define PG8_BAR __builtin_amdgcn_s_barrier()
; #define PG8_SCHED __builtin_amdgcn_sched_barrier(0)
; template <class Epi, class Sched, bool ALIGN_EPI = false, bool SP2 = false>
; __device__ __forceinline__ void gemm_phase(PG8_LAS unsigned char* lds, const Gemm g, const Sched& S, const Epi& E, const int wid) {
;     ...
;             PG8_LDB(B0, 0, 0); PG8_LDB(B1, 0, 1); PG8_SCHED; PG8_LDA(At, 0, 0); PG8_STAGE(PG8_SA(1, 1), a1 + hsA, voffA);
;             PG8_WAIT_V(8); PG8_WAIT_L(0); PG8_BAR; PG8_MMA(0, 0, At, B0); PG8_MMA(0, 1, At, B1); PG8_BAR; PG8_SCHED;
;             PG8_LDA(At, 0, 1); PG8_STAGE(PG8_SB(0, 0), b2, voffB); PG8_STAGE(PG8_SB(0, 1), b2 + hsB, voffB); PG8_STAGE(PG8_SA(0, 0), a2, voffA);
.LBB0_418:
	ds_read_b128 v[144:147], v149
	ds_read_b128 v[152:155], v149 offset:1024
	ds_read_b128 v[156:159], v149 offset:2048
	ds_read_b128 v[160:163], v149 offset:3072
	ds_read_b128 v[164:167], v150
	ds_read_b128 v[168:171], v150 offset:1024
	ds_read_b128 v[172:175], v150 offset:2048
	ds_read_b128 v[176:179], v150 offset:3072
	s_add_u32 s26, s24, 0xfff80080
	s_addc_u32 s27, s25, -1
	s_cmp_eq_u32 s55, 28
	s_cselect_b32 s29, s17, s27
	s_cselect_b32 s28, s51, s26
	s_cselect_b32 s27, s15, s54
	s_cselect_b32 s26, s52, s53
	v_lshl_add_u64 v[212:213], s[24:25], 0, v[138:139]
	s_add_i32 m0, s23, 0xc000
	ds_read_b128 v[180:183], v151
	ds_read_b128 v[184:187], v151 offset:1024
	ds_read_b128 v[188:191], v151 offset:2048
	ds_read_b128 v[192:195], v151 offset:3072
	ds_read_b128 v[196:199], v151 offset:4096
	ds_read_b128 v[200:203], v151 offset:5120
	ds_read_b128 v[204:207], v151 offset:6144
	ds_read_b128 v[208:211], v151 offset:7168
	global_load_lds_dwordx4 v[212:213], off
	v_lshl_add_u64 v[212:213], s[24:25], 0, v[136:137]
	s_add_i32 m0, s23, 0xe000
	s_nop 0
	global_load_lds_dwordx4 v[212:213], off
	s_waitcnt vmcnt(8)
	s_waitcnt lgkmcnt(0)
	s_setprio 1
	s_barrier
	v_mfma_f32_16x16x32_bf16 v[124:127], v[144:147], v[180:183], v[124:127]
	v_mfma_f32_16x16x32_bf16 v[120:123], v[156:159], v[180:183], v[120:123]
	v_mfma_f32_16x16x32_bf16 v[108:111], v[144:147], v[188:191], v[108:111]
	v_mfma_f32_16x16x32_bf16 v[104:107], v[156:159], v[188:191], v[104:107]
	v_mfma_f32_16x16x32_bf16 v[92:95], v[144:147], v[196:199], v[92:95]
	v_mfma_f32_16x16x32_bf16 v[88:91], v[156:159], v[196:199], v[88:91]
	v_mfma_f32_16x16x32_bf16 v[76:79], v[144:147], v[204:207], v[76:79]
	v_mfma_f32_16x16x32_bf16 v[72:75], v[156:159], v[204:207], v[72:75]
	v_mfma_f32_16x16x32_bf16 v[124:127], v[152:155], v[184:187], v[124:127]
	v_mfma_f32_16x16x32_bf16 v[120:123], v[160:163], v[184:187], v[120:123]
	v_mfma_f32_16x16x32_bf16 v[108:111], v[152:155], v[192:195], v[108:111]
	v_mfma_f32_16x16x32_bf16 v[104:107], v[160:163], v[192:195], v[104:107]
	v_mfma_f32_16x16x32_bf16 v[92:95], v[152:155], v[200:203], v[92:95]
	v_mfma_f32_16x16x32_bf16 v[88:91], v[160:163], v[200:203], v[88:91]
	v_mfma_f32_16x16x32_bf16 v[76:79], v[152:155], v[208:211], v[76:79]
	v_mfma_f32_16x16x32_bf16 v[72:75], v[160:163], v[208:211], v[72:75]
	s_setprio 0
	s_setprio 1
	v_mfma_f32_16x16x32_bf16 v[116:119], v[164:167], v[180:183], v[116:119]
	v_mfma_f32_16x16x32_bf16 v[112:115], v[172:175], v[180:183], v[112:115]
	v_mfma_f32_16x16x32_bf16 v[100:103], v[164:167], v[188:191], v[100:103]
	v_mfma_f32_16x16x32_bf16 v[96:99], v[172:175], v[188:191], v[96:99]
	v_mfma_f32_16x16x32_bf16 v[84:87], v[164:167], v[196:199], v[84:87]
	v_mfma_f32_16x16x32_bf16 v[80:83], v[172:175], v[196:199], v[80:83]
	v_mfma_f32_16x16x32_bf16 v[68:71], v[164:167], v[204:207], v[68:71]
	v_mfma_f32_16x16x32_bf16 v[64:67], v[172:175], v[204:207], v[64:67]
	v_mfma_f32_16x16x32_bf16 v[116:119], v[168:171], v[184:187], v[116:119]
	v_mfma_f32_16x16x32_bf16 v[112:115], v[176:179], v[184:187], v[112:115]
	v_mfma_f32_16x16x32_bf16 v[100:103], v[168:171], v[192:195], v[100:103]
	v_mfma_f32_16x16x32_bf16 v[96:99], v[176:179], v[192:195], v[96:99]
	v_mfma_f32_16x16x32_bf16 v[84:87], v[168:171], v[200:203], v[84:87]
	v_mfma_f32_16x16x32_bf16 v[80:83], v[176:179], v[200:203], v[80:83]
	v_mfma_f32_16x16x32_bf16 v[68:71], v[168:171], v[208:211], v[68:71]
	v_mfma_f32_16x16x32_bf16 v[64:67], v[176:179], v[208:211], v[64:67]
	s_barrier
	s_setprio 0
	s_add_i32 s56, s47, s34
	v_lshl_add_u64 v[212:213], s[26:27], 0, v[132:133]
	s_mov_b32 m0, s56
	ds_read_b128 v[180:183], v151 offset:16384
	ds_read_b128 v[184:187], v151 offset:17408
	ds_read_b128 v[188:191], v151 offset:18432
	ds_read_b128 v[192:195], v151 offset:19456
	ds_read_b128 v[196:199], v151 offset:20480
	ds_read_b128 v[200:203], v151 offset:21504
	ds_read_b128 v[204:207], v151 offset:22528
	ds_read_b128 v[208:211], v151 offset:23552
	global_load_lds_dwordx4 v[212:213], off
	s_add_i32 m0, s56, 0x2000
	s_add_u32 s56, s26, 0x80000
	v_lshl_add_u64 v[214:215], s[26:27], 0, v[128:129]
	s_addc_u32 s57, s27, 0
	s_add_i32 s58, s48, s34
	global_load_lds_dwordx4 v[214:215], off
	v_lshl_add_u64 v[216:217], s[56:57], 0, v[132:133]
	s_mov_b32 m0, s58
	v_lshl_add_u64 v[218:219], s[28:29], 0, v[130:131]
	global_load_lds_dwordx4 v[216:217], off
	v_lshl_add_u64 v[216:217], s[56:57], 0, v[128:129]
	s_add_i32 m0, s58, 0x2000
	s_nop 0
	global_load_lds_dwordx4 v[216:217], off
	v_lshl_add_u64 v[216:217], s[28:29], 0, v[134:135]
	s_mov_b32 m0, s23
	s_nop 0
	global_load_lds_dwordx4 v[216:217], off
	s_mov_b32 m0, s37
	s_nop 0
	global_load_lds_dwordx4 v[218:219], off
	s_waitcnt vmcnt(8)
	s_waitcnt lgkmcnt(0)
	s_setprio 1
	s_barrier
; #define PG8_STAGE(bufoff, gbase, voff) do { _Pragma("unroll") for (int _i = 0; _i < 2; ++_i) \
;         __builtin_amdgcn_global_load_lds((const unsigned*)((const char*)(gbase) + (voff)[_i]), (PG8_LAS unsigned*)(lds + (bufoff) + ldsw + _i * 8192), 16, 0, 0); } while (0)
; #define PG8_LDA(dst, b, h) do { _Pragma("unroll") for (int m = 0; m < 4; ++m) _Pragma("unroll") for (int k = 0; k < 2; ++k) dst[m][k] = *(const PG8_LAS bf16x8*)(lds + PG8_SA(b, h) + aoff + m * 2048 + k * 1024); } while (0)
; #define PG8_LDB(dst, b, h) do { _Pragma("unroll") for (int n = 0; n < 2; ++n) _Pragma("unroll") for (int k = 0; k < 2; ++k) dst[n][k] = *(const PG8_LAS bf16x8*)(lds + PG8_SB(b, h) + boff + n * 2048 + k * 1024); } while (0)
; #define PG8_MMA(ai, bj, At, Bt) do { __builtin_amdgcn_s_setprio(1); _Pragma("unroll") for (int m = 0; m < 4; ++m) _Pragma("unroll") for (int n = 0; n < 2; ++n) _Pragma("unroll") for (int k = 0; k < 2; ++k) \
;         acc[ai][bj][m][n] = __builtin_amdgcn_mfma_f32_16x16x32_bf16(Bt[n][k], At[m][k], acc[ai][bj][m][n], 0, 0, 0); __builtin_amdgcn_s_setprio(0); } while (0)
; #define PG8_WAIT_V(n) asm volatile("s_waitcnt vmcnt(" #n ")" ::: "memory")
; #define PG8_WAIT_L(n) asm volatile("s_waitcnt lgkmcnt(" #n ")" ::: "memory")
; #define PG8_BAR __builtin_amdgcn_s_barrier()
; #define PG8_SCHED __builtin_amdgcn_sched_barrier(0)
; template <class Epi, class Sched, bool ALIGN_EPI = false, bool SP2 = false>
; __device__ __forceinline__ void gemm_phase(PG8_LAS unsigned char* lds, const Gemm g, const Sched& S, const Epi& E, const int wid) {
;     ...
;             PG8_WAIT_V(8); PG8_WAIT_L(0); PG8_BAR; PG8_MMA(1, 0, At, B0); PG8_MMA(1, 1, At, B1); PG8_BAR; PG8_SCHED;
;             PG8_LDB(B0, 1, 0); PG8_LDB(B1, 1, 1); PG8_SCHED; PG8_LDA(At, 1, 0); PG8_STAGE(PG8_SA(0, 1), a2 + hsA, voffA);
;             PG8_WAIT_V(8); PG8_WAIT_L(0); PG8_BAR; PG8_MMA(0, 0, At, B0); PG8_MMA(0, 1, At, B1); PG8_BAR; PG8_SCHED;
	v_mfma_f32_16x16x32_bf16 v[60:63], v[144:147], v[180:183], v[60:63]
	v_mfma_f32_16x16x32_bf16 v[56:59], v[156:159], v[180:183], v[56:59]
	v_mfma_f32_16x16x32_bf16 v[44:47], v[144:147], v[188:191], v[44:47]
	v_mfma_f32_16x16x32_bf16 v[40:43], v[156:159], v[188:191], v[40:43]
	v_mfma_f32_16x16x32_bf16 v[28:31], v[144:147], v[196:199], v[28:31]
	v_mfma_f32_16x16x32_bf16 v[24:27], v[156:159], v[196:199], v[24:27]
	v_mfma_f32_16x16x32_bf16 v[12:15], v[144:147], v[204:207], v[12:15]
	v_mfma_f32_16x16x32_bf16 v[8:11], v[156:159], v[204:207], v[8:11]
	v_mfma_f32_16x16x32_bf16 v[60:63], v[152:155], v[184:187], v[60:63]
	v_mfma_f32_16x16x32_bf16 v[56:59], v[160:163], v[184:187], v[56:59]
	v_mfma_f32_16x16x32_bf16 v[44:47], v[152:155], v[192:195], v[44:47]
	v_mfma_f32_16x16x32_bf16 v[40:43], v[160:163], v[192:195], v[40:43]
	v_mfma_f32_16x16x32_bf16 v[28:31], v[152:155], v[200:203], v[28:31]
	v_mfma_f32_16x16x32_bf16 v[24:27], v[160:163], v[200:203], v[24:27]
	v_mfma_f32_16x16x32_bf16 v[12:15], v[152:155], v[208:211], v[12:15]
	v_mfma_f32_16x16x32_bf16 v[8:11], v[160:163], v[208:211], v[8:11]
	s_setprio 0
	s_setprio 1
	v_mfma_f32_16x16x32_bf16 v[52:55], v[164:167], v[180:183], v[52:55]
	v_mfma_f32_16x16x32_bf16 v[48:51], v[172:175], v[180:183], v[48:51]
	v_mfma_f32_16x16x32_bf16 v[36:39], v[164:167], v[188:191], v[36:39]
	v_mfma_f32_16x16x32_bf16 v[32:35], v[172:175], v[188:191], v[32:35]
	v_mfma_f32_16x16x32_bf16 v[20:23], v[164:167], v[196:199], v[20:23]
	v_mfma_f32_16x16x32_bf16 v[16:19], v[172:175], v[196:199], v[16:19]
	v_mfma_f32_16x16x32_bf16 v[4:7], v[164:167], v[204:207], v[4:7]
	v_mfma_f32_16x16x32_bf16 v[0:3], v[172:175], v[204:207], v[0:3]
	v_mfma_f32_16x16x32_bf16 v[52:55], v[168:171], v[184:187], v[52:55]
	v_mfma_f32_16x16x32_bf16 v[48:51], v[176:179], v[184:187], v[48:51]
	v_mfma_f32_16x16x32_bf16 v[36:39], v[168:171], v[192:195], v[36:39]
	v_mfma_f32_16x16x32_bf16 v[32:35], v[176:179], v[192:195], v[32:35]
	v_mfma_f32_16x16x32_bf16 v[20:23], v[168:171], v[200:203], v[20:23]
	v_mfma_f32_16x16x32_bf16 v[16:19], v[176:179], v[200:203], v[16:19]
	v_mfma_f32_16x16x32_bf16 v[4:7], v[168:171], v[208:211], v[4:7]
	v_mfma_f32_16x16x32_bf16 v[0:3], v[176:179], v[208:211], v[0:3]
	s_barrier
	s_setprio 0
	s_add_i32 s56, 0, 0x18000
	s_add_i32 s57, 0, 0x1c000
	v_add_u32_e32 v160, s56, v148
	v_add_u32_e32 v176, s57, v148
	ds_read_b128 v[144:147], v160
	ds_read_b128 v[152:155], v160 offset:1024
	ds_read_b128 v[156:159], v160 offset:2048
	ds_read_b128 v[160:163], v160 offset:3072
	ds_read_b128 v[164:167], v176
	ds_read_b128 v[168:171], v176 offset:1024
	ds_read_b128 v[172:175], v176 offset:2048
	ds_read_b128 v[176:179], v176 offset:3072
	s_add_u32 s28, s28, 0x80000
	s_addc_u32 s29, s29, 0
	s_mov_b32 m0, s38
	v_lshl_add_u64 v[220:221], s[28:29], 0, v[134:135]
	ds_read_b128 v[180:183], v151 offset:32768
	ds_read_b128 v[184:187], v151 offset:33792
	ds_read_b128 v[188:191], v151 offset:34816
	ds_read_b128 v[192:195], v151 offset:35840
	ds_read_b128 v[196:199], v151 offset:36864
	ds_read_b128 v[200:203], v151 offset:37888
	ds_read_b128 v[204:207], v151 offset:38912
	ds_read_b128 v[208:211], v151 offset:39936
	global_load_lds_dwordx4 v[220:221], off
	v_lshl_add_u64 v[220:221], s[28:29], 0, v[130:131]
	s_mov_b32 m0, s39
	s_nop 0
	global_load_lds_dwordx4 v[220:221], off
	s_waitcnt vmcnt(8)
	s_waitcnt lgkmcnt(0)
	s_setprio 1
	s_barrier
	v_mfma_f32_16x16x32_bf16 v[124:127], v[144:147], v[180:183], v[124:127]
	v_mfma_f32_16x16x32_bf16 v[120:123], v[156:159], v[180:183], v[120:123]
	v_mfma_f32_16x16x32_bf16 v[108:111], v[144:147], v[188:191], v[108:111]
	v_mfma_f32_16x16x32_bf16 v[104:107], v[156:159], v[188:191], v[104:107]
	v_mfma_f32_16x16x32_bf16 v[92:95], v[144:147], v[196:199], v[92:95]
	v_mfma_f32_16x16x32_bf16 v[88:91], v[156:159], v[196:199], v[88:91]
	v_mfma_f32_16x16x32_bf16 v[76:79], v[144:147], v[204:207], v[76:79]
	v_mfma_f32_16x16x32_bf16 v[72:75], v[156:159], v[204:207], v[72:75]
	v_mfma_f32_16x16x32_bf16 v[124:127], v[152:155], v[184:187], v[124:127]
	v_mfma_f32_16x16x32_bf16 v[120:123], v[160:163], v[184:187], v[120:123]
	v_mfma_f32_16x16x32_bf16 v[108:111], v[152:155], v[192:195], v[108:111]
	v_mfma_f32_16x16x32_bf16 v[104:107], v[160:163], v[192:195], v[104:107]
	v_mfma_f32_16x16x32_bf16 v[92:95], v[152:155], v[200:203], v[92:95]
	v_mfma_f32_16x16x32_bf16 v[88:91], v[160:163], v[200:203], v[88:91]
	v_mfma_f32_16x16x32_bf16 v[76:79], v[152:155], v[208:211], v[76:79]
	v_mfma_f32_16x16x32_bf16 v[72:75], v[160:163], v[208:211], v[72:75]
	s_setprio 0
	s_setprio 1
	v_mfma_f32_16x16x32_bf16 v[116:119], v[164:167], v[180:183], v[116:119]
	v_mfma_f32_16x16x32_bf16 v[112:115], v[172:175], v[180:183], v[112:115]
	v_mfma_f32_16x16x32_bf16 v[100:103], v[164:167], v[188:191], v[100:103]
	v_mfma_f32_16x16x32_bf16 v[96:99], v[172:175], v[188:191], v[96:99]
	v_mfma_f32_16x16x32_bf16 v[84:87], v[164:167], v[196:199], v[84:87]
	v_mfma_f32_16x16x32_bf16 v[80:83], v[172:175], v[196:199], v[80:83]
	v_mfma_f32_16x16x32_bf16 v[68:71], v[164:167], v[204:207], v[68:71]
	v_mfma_f32_16x16x32_bf16 v[64:67], v[172:175], v[204:207], v[64:67]
	v_mfma_f32_16x16x32_bf16 v[116:119], v[168:171], v[184:187], v[116:119]
	v_mfma_f32_16x16x32_bf16 v[112:115], v[176:179], v[184:187], v[112:115]
	v_mfma_f32_16x16x32_bf16 v[100:103], v[168:171], v[192:195], v[100:103]
	v_mfma_f32_16x16x32_bf16 v[96:99], v[176:179], v[192:195], v[96:99]
	v_mfma_f32_16x16x32_bf16 v[84:87], v[168:171], v[200:203], v[84:87]
	v_mfma_f32_16x16x32_bf16 v[80:83], v[176:179], v[200:203], v[80:83]
	v_mfma_f32_16x16x32_bf16 v[68:71], v[168:171], v[208:211], v[68:71]
	v_mfma_f32_16x16x32_bf16 v[64:67], v[176:179], v[208:211], v[64:67]
	s_barrier
; #define PG8_STAGE(bufoff, gbase, voff) do { _Pragma("unroll") for (int _i = 0; _i < 2; ++_i) \
;         __builtin_amdgcn_global_load_lds((const unsigned*)((const char*)(gbase) + (voff)[_i]), (PG8_LAS unsigned*)(lds + (bufoff) + ldsw + _i * 8192), 16, 0, 0); } while (0)
; #define PG8_LDA(dst, b, h) do { _Pragma("unroll") for (int m = 0; m < 4; ++m) _Pragma("unroll") for (int k = 0; k < 2; ++k) dst[m][k] = *(const PG8_LAS bf16x8*)(lds + PG8_SA(b, h) + aoff + m * 2048 + k * 1024); } while (0)
; #define PG8_MMA(ai, bj, At, Bt) do { __builtin_amdgcn_s_setprio(1); _Pragma("unroll") for (int m = 0; m < 4; ++m) _Pragma("unroll") for (int n = 0; n < 2; ++n) _Pragma("unroll") for (int k = 0; k < 2; ++k) \
;         acc[ai][bj][m][n] = __builtin_amdgcn_mfma_f32_16x16x32_bf16(Bt[n][k], At[m][k], acc[ai][bj][m][n], 0, 0, 0); __builtin_amdgcn_s_setprio(0); } while (0)
; #define PG8_WAIT_V(n) asm volatile("s_waitcnt vmcnt(" #n ")" ::: "memory")
; #define PG8_WAIT_L(n) asm volatile("s_waitcnt lgkmcnt(" #n ")" ::: "memory")
; #define PG8_BAR __builtin_amdgcn_s_barrier()
; #define PG8_SCHED __builtin_amdgcn_sched_barrier(0)
; template <class Epi, class Sched, bool ALIGN_EPI = false, bool SP2 = false>
; __device__ __forceinline__ void gemm_phase(PG8_LAS unsigned char* lds, const Gemm g, const Sched& S, const Epi& E, const int wid) {
;     ...
;             PG8_LDA(At, 1, 1); PG8_STAGE(PG8_SB(1, 0), b3, voffB); PG8_STAGE(PG8_SB(1, 1), b3 + hsB, voffB); PG8_STAGE(PG8_SA(1, 0), a3, voffA);
;             PG8_WAIT_V(8); PG8_WAIT_L(0); PG8_BAR; PG8_MMA(1, 0, At, B0); PG8_MMA(1, 1, At, B1); PG8_BAR; PG8_SCHED;
;     ...
;         if constexpr (ALIGN_EPI) { if (wr == 0) PG8_BAR; }
	s_setprio 0
	s_add_i32 s28, s56, s34
	v_lshl_add_u64 v[212:213], v[212:213], 0, s[10:11]
	s_mov_b32 m0, s28
	ds_read_b128 v[180:183], v151 offset:49152
	ds_read_b128 v[184:187], v151 offset:50176
	ds_read_b128 v[188:191], v151 offset:51200
	ds_read_b128 v[192:195], v151 offset:52224
	ds_read_b128 v[196:199], v151 offset:53248
	ds_read_b128 v[200:203], v151 offset:54272
	ds_read_b128 v[204:207], v151 offset:55296
	ds_read_b128 v[208:211], v151 offset:56320
	global_load_lds_dwordx4 v[212:213], off
	s_add_i32 m0, s28, 0x2000
	s_add_u32 s26, s26, 0x80080
	v_lshl_add_u64 v[212:213], v[214:215], 0, s[10:11]
	s_addc_u32 s27, s27, 0
	s_add_i32 s28, s57, s34
	global_load_lds_dwordx4 v[212:213], off
	v_lshl_add_u64 v[212:213], s[26:27], 0, v[132:133]
	s_mov_b32 m0, s28
	s_nop 0
	global_load_lds_dwordx4 v[212:213], off
	v_lshl_add_u64 v[212:213], s[26:27], 0, v[128:129]
	s_add_i32 m0, s28, 0x2000
	s_nop 0
	global_load_lds_dwordx4 v[212:213], off
	v_lshl_add_u64 v[212:213], v[216:217], 0, s[10:11]
	s_mov_b32 m0, s42
	s_nop 0
	global_load_lds_dwordx4 v[212:213], off
	v_lshl_add_u64 v[212:213], v[218:219], 0, s[10:11]
	s_mov_b32 m0, s43
	s_nop 0
	global_load_lds_dwordx4 v[212:213], off
	s_waitcnt vmcnt(8)
	s_waitcnt lgkmcnt(0)
	s_setprio 1
	s_barrier
	v_mfma_f32_16x16x32_bf16 v[60:63], v[144:147], v[180:183], v[60:63]
	v_mfma_f32_16x16x32_bf16 v[56:59], v[156:159], v[180:183], v[56:59]
	v_mfma_f32_16x16x32_bf16 v[44:47], v[144:147], v[188:191], v[44:47]
	v_mfma_f32_16x16x32_bf16 v[40:43], v[156:159], v[188:191], v[40:43]
	v_mfma_f32_16x16x32_bf16 v[28:31], v[144:147], v[196:199], v[28:31]
	v_mfma_f32_16x16x32_bf16 v[24:27], v[156:159], v[196:199], v[24:27]
	v_mfma_f32_16x16x32_bf16 v[12:15], v[144:147], v[204:207], v[12:15]
	v_mfma_f32_16x16x32_bf16 v[8:11], v[156:159], v[204:207], v[8:11]
	v_mfma_f32_16x16x32_bf16 v[60:63], v[152:155], v[184:187], v[60:63]
	v_mfma_f32_16x16x32_bf16 v[56:59], v[160:163], v[184:187], v[56:59]
	v_mfma_f32_16x16x32_bf16 v[44:47], v[152:155], v[192:195], v[44:47]
	v_mfma_f32_16x16x32_bf16 v[40:43], v[160:163], v[192:195], v[40:43]
	v_mfma_f32_16x16x32_bf16 v[28:31], v[152:155], v[200:203], v[28:31]
	v_mfma_f32_16x16x32_bf16 v[24:27], v[160:163], v[200:203], v[24:27]
	v_mfma_f32_16x16x32_bf16 v[12:15], v[152:155], v[208:211], v[12:15]
	v_mfma_f32_16x16x32_bf16 v[8:11], v[160:163], v[208:211], v[8:11]
	s_setprio 0
	s_setprio 1
	v_mfma_f32_16x16x32_bf16 v[52:55], v[164:167], v[180:183], v[52:55]
	v_mfma_f32_16x16x32_bf16 v[48:51], v[172:175], v[180:183], v[48:51]
	v_mfma_f32_16x16x32_bf16 v[36:39], v[164:167], v[188:191], v[36:39]
	v_mfma_f32_16x16x32_bf16 v[32:35], v[172:175], v[188:191], v[32:35]
	v_mfma_f32_16x16x32_bf16 v[20:23], v[164:167], v[196:199], v[20:23]
	v_mfma_f32_16x16x32_bf16 v[16:19], v[172:175], v[196:199], v[16:19]
	v_mfma_f32_16x16x32_bf16 v[4:7], v[164:167], v[204:207], v[4:7]
	v_mfma_f32_16x16x32_bf16 v[0:3], v[172:175], v[204:207], v[0:3]
	v_mfma_f32_16x16x32_bf16 v[52:55], v[168:171], v[184:187], v[52:55]
	v_mfma_f32_16x16x32_bf16 v[48:51], v[176:179], v[184:187], v[48:51]
	v_mfma_f32_16x16x32_bf16 v[36:39], v[168:171], v[192:195], v[36:39]
	v_mfma_f32_16x16x32_bf16 v[32:35], v[176:179], v[192:195], v[32:35]
	v_mfma_f32_16x16x32_bf16 v[20:23], v[168:171], v[200:203], v[20:23]
	v_mfma_f32_16x16x32_bf16 v[16:19], v[176:179], v[200:203], v[16:19]
	v_mfma_f32_16x16x32_bf16 v[4:7], v[168:171], v[208:211], v[4:7]
	v_mfma_f32_16x16x32_bf16 v[0:3], v[176:179], v[208:211], v[0:3]
	s_barrier
	s_setprio 0
	s_add_i32 s55, s55, 2
	s_add_u32 s53, s53, 0x100
	s_addc_u32 s54, s54, 0
	s_add_u32 s24, s24, 0x100
	s_addc_u32 s25, s25, 0
	s_cmp_gt_u32 s55, 29
	s_cbranch_scc0 .LBB0_418
	s_and_b64 vcc, exec, s[12:13]
	s_cbranch_vccz .LBB0_421
	s_barrier

; #define PG8_STAGE(bufoff, gbase, voff) do { _Pragma("unroll") for (int _i = 0; _i < 2; ++_i) \
;         __builtin_amdgcn_global_load_lds((const unsigned*)((const char*)(gbase) + (voff)[_i]), (PG8_LAS unsigned*)(lds + (bufoff) + ldsw + _i * 8192), 16, 0, 0); } while (0)
; #define PG8_LDA(dst, b, h) do { _Pragma("unroll") for (int m = 0; m < 4; ++m) _Pragma("unroll") for (int k = 0; k < 2; ++k) dst[m][k] = *(const PG8_LAS bf16x8*)(lds + PG8_SA(b, h) + aoff + m * 2048 + k * 1024); } while (0)
; #define PG8_LDB(dst, b, h) do { _Pragma("unroll") for (int n = 0; n < 2; ++n) _Pragma("unroll") for (int k = 0; k < 2; ++k) dst[n][k] = *(const PG8_LAS bf16x8*)(lds + PG8_SB(b, h) + boff + n * 2048 + k * 1024); } while (0)
; #define PG8_MMA(ai, bj, At, Bt) do { __builtin_amdgcn_s_setprio(1); _Pragma("unroll") for (int m = 0; m < 4; ++m) _Pragma("unroll") for (int n = 0; n < 2; ++n) _Pragma("unroll") for (int k = 0; k < 2; ++k) \
;         acc[ai][bj][m][n] = __builtin_amdgcn_mfma_f32_16x16x32_bf16(Bt[n][k], At[m][k], acc[ai][bj][m][n], 0, 0, 0); __builtin_amdgcn_s_setprio(0); } while (0)
; #define PG8_WAIT_V(n) asm volatile("s_waitcnt vmcnt(" #n ")" ::: "memory")
; #define PG8_WAIT_L(n) asm volatile("s_waitcnt lgkmcnt(" #n ")" ::: "memory")
; #define PG8_BAR __builtin_amdgcn_s_barrier()
; #define PG8_SCHED __builtin_amdgcn_sched_barrier(0)
; template <class Epi, class Sched, bool ALIGN_EPI = false, bool SP2 = false>
; __device__ __forceinline__ void gemm_phase(PG8_LAS unsigned char* lds, const Gemm g, const Sched& S, const Epi& E, const int wid) {
;     ...
;             PG8_LDB(B0, 0, 0); PG8_LDB(B1, 0, 1); PG8_SCHED; PG8_LDA(At, 0, 0); PG8_STAGE(PG8_SA(1, 1), a1 + hsA, voffA);
;             PG8_WAIT_V(8); PG8_WAIT_L(0); PG8_BAR; PG8_MMA(0, 0, At, B0); PG8_MMA(0, 1, At, B1); PG8_BAR; PG8_SCHED;
;             PG8_LDA(At, 0, 1); PG8_STAGE(PG8_SB(0, 0), b2, voffB); PG8_STAGE(PG8_SB(0, 1), b2 + hsB, voffB); PG8_STAGE(PG8_SA(0, 0), a2, voffA);
.LBB0_497:
	ds_read_b128 v[64:67], v197
	ds_read_b128 v[72:75], v197 offset:1024
	ds_read_b128 v[80:83], v197 offset:2048
	ds_read_b128 v[84:87], v197 offset:3072
	ds_read_b128 v[88:91], v198
	ds_read_b128 v[92:95], v198 offset:1024
	ds_read_b128 v[100:103], v198 offset:2048
	ds_read_b128 v[104:107], v198 offset:3072
	s_add_u32 s4, s30, 0x100
	s_addc_u32 s5, s31, 0
	s_cmpk_eq_i32 s61, 0x54
	s_cselect_b32 s37, s27, s5
	s_cselect_b32 s36, s26, s4
	s_cselect_b32 s35, s29, s60
	s_cselect_b32 s34, s28, s59
	v_lshl_add_u64 v[210:211], s[30:31], 0, v[182:183]
	s_add_i32 m0, s41, 0xc000
	ds_read_b128 v[160:163], v199
	ds_read_b128 v[164:167], v199 offset:1024
	ds_read_b128 v[168:171], v199 offset:2048
	ds_read_b128 v[172:175], v199 offset:3072
	ds_read_b128 v[188:191], v199 offset:4096
	ds_read_b128 v[192:195], v199 offset:5120
	ds_read_b128 v[202:205], v199 offset:6144
	ds_read_b128 v[206:209], v199 offset:7168
	global_load_lds_dwordx4 v[210:211], off
	v_lshl_add_u64 v[210:211], s[30:31], 0, v[180:181]
	s_add_i32 m0, s41, 0xe000
	s_nop 0
	global_load_lds_dwordx4 v[210:211], off
	s_waitcnt vmcnt(8)
	s_waitcnt lgkmcnt(0)
	s_setprio 1
	s_barrier
	v_mfma_f32_16x16x32_bf16 v[156:159], v[64:67], v[160:163], v[156:159]
	v_mfma_f32_16x16x32_bf16 v[152:155], v[80:83], v[160:163], v[152:155]
	v_mfma_f32_16x16x32_bf16 v[140:143], v[64:67], v[168:171], v[140:143]
	v_mfma_f32_16x16x32_bf16 v[136:139], v[80:83], v[168:171], v[136:139]
	v_mfma_f32_16x16x32_bf16 v[124:127], v[64:67], v[188:191], v[124:127]
	v_mfma_f32_16x16x32_bf16 v[120:123], v[80:83], v[188:191], v[120:123]
	v_mfma_f32_16x16x32_bf16 v[108:111], v[64:67], v[202:205], v[108:111]
	v_mfma_f32_16x16x32_bf16 v[96:99], v[80:83], v[202:205], v[96:99]
	v_mfma_f32_16x16x32_bf16 v[156:159], v[72:75], v[164:167], v[156:159]
	v_mfma_f32_16x16x32_bf16 v[152:155], v[84:87], v[164:167], v[152:155]
	v_mfma_f32_16x16x32_bf16 v[140:143], v[72:75], v[172:175], v[140:143]
	v_mfma_f32_16x16x32_bf16 v[136:139], v[84:87], v[172:175], v[136:139]
	v_mfma_f32_16x16x32_bf16 v[124:127], v[72:75], v[192:195], v[124:127]
	v_mfma_f32_16x16x32_bf16 v[120:123], v[84:87], v[192:195], v[120:123]
	v_mfma_f32_16x16x32_bf16 v[108:111], v[72:75], v[206:209], v[108:111]
	v_mfma_f32_16x16x32_bf16 v[96:99], v[84:87], v[206:209], v[96:99]
	s_setprio 0
	s_setprio 1
	v_mfma_f32_16x16x32_bf16 v[148:151], v[88:91], v[160:163], v[148:151]
	v_mfma_f32_16x16x32_bf16 v[144:147], v[100:103], v[160:163], v[144:147]
	v_mfma_f32_16x16x32_bf16 v[132:135], v[88:91], v[168:171], v[132:135]
	v_mfma_f32_16x16x32_bf16 v[128:131], v[100:103], v[168:171], v[128:131]
	v_mfma_f32_16x16x32_bf16 v[116:119], v[88:91], v[188:191], v[116:119]
	v_mfma_f32_16x16x32_bf16 v[112:115], v[100:103], v[188:191], v[112:115]
	v_mfma_f32_16x16x32_bf16 v[76:79], v[88:91], v[202:205], v[76:79]
	v_mfma_f32_16x16x32_bf16 v[68:71], v[100:103], v[202:205], v[68:71]
	v_mfma_f32_16x16x32_bf16 v[148:151], v[92:95], v[164:167], v[148:151]
	v_mfma_f32_16x16x32_bf16 v[144:147], v[104:107], v[164:167], v[144:147]
	v_mfma_f32_16x16x32_bf16 v[132:135], v[92:95], v[172:175], v[132:135]
	v_mfma_f32_16x16x32_bf16 v[128:131], v[104:107], v[172:175], v[128:131]
	v_mfma_f32_16x16x32_bf16 v[116:119], v[92:95], v[192:195], v[116:119]
	v_mfma_f32_16x16x32_bf16 v[112:115], v[104:107], v[192:195], v[112:115]
	v_mfma_f32_16x16x32_bf16 v[76:79], v[92:95], v[206:209], v[76:79]
	v_mfma_f32_16x16x32_bf16 v[68:71], v[104:107], v[206:209], v[68:71]
	s_barrier
	s_setprio 0
	s_add_i32 s30, s53, s40
	v_lshl_add_u64 v[210:211], s[34:35], 0, v[176:177]
	s_mov_b32 m0, s30
	ds_read_b128 v[160:163], v199 offset:16384
	ds_read_b128 v[164:167], v199 offset:17408
	ds_read_b128 v[168:171], v199 offset:18432
	ds_read_b128 v[172:175], v199 offset:19456
	ds_read_b128 v[188:191], v199 offset:20480
	ds_read_b128 v[192:195], v199 offset:21504
	ds_read_b128 v[202:205], v199 offset:22528
	ds_read_b128 v[206:209], v199 offset:23552
	global_load_lds_dwordx4 v[210:211], off
	s_add_i32 m0, s30, 0x2000
	s_add_u32 s30, s34, 0x160000
	v_lshl_add_u64 v[212:213], s[34:35], 0, v[178:179]
	s_addc_u32 s31, s35, 0
	s_add_i32 s62, s54, s40
	global_load_lds_dwordx4 v[212:213], off
	v_lshl_add_u64 v[214:215], s[30:31], 0, v[176:177]
	s_mov_b32 m0, s62
	v_lshl_add_u64 v[216:217], s[36:37], 0, v[178:179]
	global_load_lds_dwordx4 v[214:215], off
	v_lshl_add_u64 v[214:215], s[30:31], 0, v[178:179]
	s_add_i32 m0, s62, 0x2000
	s_nop 0
	global_load_lds_dwordx4 v[214:215], off
	v_lshl_add_u64 v[214:215], s[36:37], 0, v[176:177]
	s_mov_b32 m0, s41
	s_nop 0
	global_load_lds_dwordx4 v[214:215], off
	s_mov_b32 m0, s42
	s_nop 0
	global_load_lds_dwordx4 v[216:217], off
	s_waitcnt vmcnt(8)
	s_waitcnt lgkmcnt(0)
	s_setprio 1
	s_barrier
; #define PG8_STAGE(bufoff, gbase, voff) do { _Pragma("unroll") for (int _i = 0; _i < 2; ++_i) \
;         __builtin_amdgcn_global_load_lds((const unsigned*)((const char*)(gbase) + (voff)[_i]), (PG8_LAS unsigned*)(lds + (bufoff) + ldsw + _i * 8192), 16, 0, 0); } while (0)
; #define PG8_LDA(dst, b, h) do { _Pragma("unroll") for (int m = 0; m < 4; ++m) _Pragma("unroll") for (int k = 0; k < 2; ++k) dst[m][k] = *(const PG8_LAS bf16x8*)(lds + PG8_SA(b, h) + aoff + m * 2048 + k * 1024); } while (0)
; #define PG8_LDB(dst, b, h) do { _Pragma("unroll") for (int n = 0; n < 2; ++n) _Pragma("unroll") for (int k = 0; k < 2; ++k) dst[n][k] = *(const PG8_LAS bf16x8*)(lds + PG8_SB(b, h) + boff + n * 2048 + k * 1024); } while (0)
; #define PG8_MMA(ai, bj, At, Bt) do { __builtin_amdgcn_s_setprio(1); _Pragma("unroll") for (int m = 0; m < 4; ++m) _Pragma("unroll") for (int n = 0; n < 2; ++n) _Pragma("unroll") for (int k = 0; k < 2; ++k) \
;         acc[ai][bj][m][n] = __builtin_amdgcn_mfma_f32_16x16x32_bf16(Bt[n][k], At[m][k], acc[ai][bj][m][n], 0, 0, 0); __builtin_amdgcn_s_setprio(0); } while (0)
; #define PG8_WAIT_V(n) asm volatile("s_waitcnt vmcnt(" #n ")" ::: "memory")
; #define PG8_WAIT_L(n) asm volatile("s_waitcnt lgkmcnt(" #n ")" ::: "memory")
; #define PG8_BAR __builtin_amdgcn_s_barrier()
; #define PG8_SCHED __builtin_amdgcn_sched_barrier(0)
; template <class Epi, class Sched, bool ALIGN_EPI = false, bool SP2 = false>
; __device__ __forceinline__ void gemm_phase(PG8_LAS unsigned char* lds, const Gemm g, const Sched& S, const Epi& E, const int wid) {
;     ...
;             PG8_WAIT_V(8); PG8_WAIT_L(0); PG8_BAR; PG8_MMA(1, 0, At, B0); PG8_MMA(1, 1, At, B1); PG8_BAR; PG8_SCHED;
;             PG8_LDB(B0, 1, 0); PG8_LDB(B1, 1, 1); PG8_SCHED; PG8_LDA(At, 1, 0); PG8_STAGE(PG8_SA(0, 1), a2 + hsA, voffA);
;             PG8_WAIT_V(8); PG8_WAIT_L(0); PG8_BAR; PG8_MMA(0, 0, At, B0); PG8_MMA(0, 1, At, B1); PG8_BAR; PG8_SCHED;
	v_mfma_f32_16x16x32_bf16 v[60:63], v[64:67], v[160:163], v[60:63]
	v_mfma_f32_16x16x32_bf16 v[56:59], v[80:83], v[160:163], v[56:59]
	v_mfma_f32_16x16x32_bf16 v[44:47], v[64:67], v[168:171], v[44:47]
	v_mfma_f32_16x16x32_bf16 v[40:43], v[80:83], v[168:171], v[40:43]
	v_mfma_f32_16x16x32_bf16 v[28:31], v[64:67], v[188:191], v[28:31]
	v_mfma_f32_16x16x32_bf16 v[24:27], v[80:83], v[188:191], v[24:27]
	v_mfma_f32_16x16x32_bf16 v[12:15], v[64:67], v[202:205], v[12:15]
	v_mfma_f32_16x16x32_bf16 v[8:11], v[80:83], v[202:205], v[8:11]
	v_mfma_f32_16x16x32_bf16 v[60:63], v[72:75], v[164:167], v[60:63]
	v_mfma_f32_16x16x32_bf16 v[56:59], v[84:87], v[164:167], v[56:59]
	v_mfma_f32_16x16x32_bf16 v[44:47], v[72:75], v[172:175], v[44:47]
	v_mfma_f32_16x16x32_bf16 v[40:43], v[84:87], v[172:175], v[40:43]
	v_mfma_f32_16x16x32_bf16 v[28:31], v[72:75], v[192:195], v[28:31]
	v_mfma_f32_16x16x32_bf16 v[24:27], v[84:87], v[192:195], v[24:27]
	v_mfma_f32_16x16x32_bf16 v[12:15], v[72:75], v[206:209], v[12:15]
	v_mfma_f32_16x16x32_bf16 v[8:11], v[84:87], v[206:209], v[8:11]
	s_setprio 0
	s_setprio 1
	v_mfma_f32_16x16x32_bf16 v[52:55], v[88:91], v[160:163], v[52:55]
	v_mfma_f32_16x16x32_bf16 v[48:51], v[100:103], v[160:163], v[48:51]
	v_mfma_f32_16x16x32_bf16 v[36:39], v[88:91], v[168:171], v[36:39]
	v_mfma_f32_16x16x32_bf16 v[32:35], v[100:103], v[168:171], v[32:35]
	v_mfma_f32_16x16x32_bf16 v[20:23], v[88:91], v[188:191], v[20:23]
	v_mfma_f32_16x16x32_bf16 v[16:19], v[100:103], v[188:191], v[16:19]
	v_mfma_f32_16x16x32_bf16 v[4:7], v[88:91], v[202:205], v[4:7]
	v_mfma_f32_16x16x32_bf16 v[0:3], v[100:103], v[202:205], v[0:3]
	v_mfma_f32_16x16x32_bf16 v[52:55], v[92:95], v[164:167], v[52:55]
	v_mfma_f32_16x16x32_bf16 v[48:51], v[104:107], v[164:167], v[48:51]
	v_mfma_f32_16x16x32_bf16 v[36:39], v[92:95], v[172:175], v[36:39]
	v_mfma_f32_16x16x32_bf16 v[32:35], v[104:107], v[172:175], v[32:35]
	v_mfma_f32_16x16x32_bf16 v[20:23], v[92:95], v[192:195], v[20:23]
	v_mfma_f32_16x16x32_bf16 v[16:19], v[104:107], v[192:195], v[16:19]
	v_mfma_f32_16x16x32_bf16 v[4:7], v[92:95], v[206:209], v[4:7]
	v_mfma_f32_16x16x32_bf16 v[0:3], v[104:107], v[206:209], v[0:3]
	s_barrier
	s_setprio 0
	s_add_i32 s62, 0, 0x18000
	s_add_i32 s63, 0, 0x1c000
	v_add_u32_e32 v84, s62, v196
	v_add_u32_e32 v104, s63, v196
	ds_read_b128 v[64:67], v84
	ds_read_b128 v[72:75], v84 offset:1024
	ds_read_b128 v[80:83], v84 offset:2048
	ds_read_b128 v[84:87], v84 offset:3072
	ds_read_b128 v[88:91], v104
	ds_read_b128 v[92:95], v104 offset:1024
	ds_read_b128 v[100:103], v104 offset:2048
	ds_read_b128 v[104:107], v104 offset:3072
	s_add_u32 s30, s36, 0x160000
	s_addc_u32 s31, s37, 0
	s_mov_b32 m0, s43
	v_lshl_add_u64 v[218:219], s[30:31], 0, v[176:177]
	ds_read_b128 v[160:163], v199 offset:32768
	ds_read_b128 v[164:167], v199 offset:33792
	ds_read_b128 v[168:171], v199 offset:34816
	ds_read_b128 v[172:175], v199 offset:35840
	ds_read_b128 v[188:191], v199 offset:36864
	ds_read_b128 v[192:195], v199 offset:37888
	ds_read_b128 v[202:205], v199 offset:38912
	ds_read_b128 v[206:209], v199 offset:39936
	global_load_lds_dwordx4 v[218:219], off
	v_lshl_add_u64 v[218:219], s[30:31], 0, v[178:179]
	s_mov_b32 m0, s44
	s_nop 0
	global_load_lds_dwordx4 v[218:219], off
	s_waitcnt vmcnt(8)
	s_waitcnt lgkmcnt(0)
	s_setprio 1
	s_barrier
	v_mfma_f32_16x16x32_bf16 v[156:159], v[64:67], v[160:163], v[156:159]
	v_mfma_f32_16x16x32_bf16 v[152:155], v[80:83], v[160:163], v[152:155]
	v_mfma_f32_16x16x32_bf16 v[140:143], v[64:67], v[168:171], v[140:143]
	v_mfma_f32_16x16x32_bf16 v[136:139], v[80:83], v[168:171], v[136:139]
	v_mfma_f32_16x16x32_bf16 v[124:127], v[64:67], v[188:191], v[124:127]
	v_mfma_f32_16x16x32_bf16 v[120:123], v[80:83], v[188:191], v[120:123]
	v_mfma_f32_16x16x32_bf16 v[108:111], v[64:67], v[202:205], v[108:111]
	v_mfma_f32_16x16x32_bf16 v[96:99], v[80:83], v[202:205], v[96:99]
	v_mfma_f32_16x16x32_bf16 v[156:159], v[72:75], v[164:167], v[156:159]
	v_mfma_f32_16x16x32_bf16 v[152:155], v[84:87], v[164:167], v[152:155]
	v_mfma_f32_16x16x32_bf16 v[140:143], v[72:75], v[172:175], v[140:143]
	v_mfma_f32_16x16x32_bf16 v[136:139], v[84:87], v[172:175], v[136:139]
	v_mfma_f32_16x16x32_bf16 v[124:127], v[72:75], v[192:195], v[124:127]
	v_mfma_f32_16x16x32_bf16 v[120:123], v[84:87], v[192:195], v[120:123]
	v_mfma_f32_16x16x32_bf16 v[108:111], v[72:75], v[206:209], v[108:111]
	v_mfma_f32_16x16x32_bf16 v[96:99], v[84:87], v[206:209], v[96:99]
	s_setprio 0
	s_setprio 1
	v_mfma_f32_16x16x32_bf16 v[148:151], v[88:91], v[160:163], v[148:151]
	v_mfma_f32_16x16x32_bf16 v[144:147], v[100:103], v[160:163], v[144:147]
	v_mfma_f32_16x16x32_bf16 v[132:135], v[88:91], v[168:171], v[132:135]
	v_mfma_f32_16x16x32_bf16 v[128:131], v[100:103], v[168:171], v[128:131]
	v_mfma_f32_16x16x32_bf16 v[116:119], v[88:91], v[188:191], v[116:119]
	v_mfma_f32_16x16x32_bf16 v[112:115], v[100:103], v[188:191], v[112:115]
	v_mfma_f32_16x16x32_bf16 v[76:79], v[88:91], v[202:205], v[76:79]
	v_mfma_f32_16x16x32_bf16 v[68:71], v[100:103], v[202:205], v[68:71]
	v_mfma_f32_16x16x32_bf16 v[148:151], v[92:95], v[164:167], v[148:151]
	v_mfma_f32_16x16x32_bf16 v[144:147], v[104:107], v[164:167], v[144:147]
	v_mfma_f32_16x16x32_bf16 v[132:135], v[92:95], v[172:175], v[132:135]
	v_mfma_f32_16x16x32_bf16 v[128:131], v[104:107], v[172:175], v[128:131]
	v_mfma_f32_16x16x32_bf16 v[116:119], v[92:95], v[192:195], v[116:119]
	v_mfma_f32_16x16x32_bf16 v[112:115], v[104:107], v[192:195], v[112:115]
	v_mfma_f32_16x16x32_bf16 v[76:79], v[92:95], v[206:209], v[76:79]
	v_mfma_f32_16x16x32_bf16 v[68:71], v[104:107], v[206:209], v[68:71]
	s_barrier
; #define PG8_STAGE(bufoff, gbase, voff) do { _Pragma("unroll") for (int _i = 0; _i < 2; ++_i) \
;         __builtin_amdgcn_global_load_lds((const unsigned*)((const char*)(gbase) + (voff)[_i]), (PG8_LAS unsigned*)(lds + (bufoff) + ldsw + _i * 8192), 16, 0, 0); } while (0)
; #define PG8_LDA(dst, b, h) do { _Pragma("unroll") for (int m = 0; m < 4; ++m) _Pragma("unroll") for (int k = 0; k < 2; ++k) dst[m][k] = *(const PG8_LAS bf16x8*)(lds + PG8_SA(b, h) + aoff + m * 2048 + k * 1024); } while (0)
; #define PG8_MMA(ai, bj, At, Bt) do { __builtin_amdgcn_s_setprio(1); _Pragma("unroll") for (int m = 0; m < 4; ++m) _Pragma("unroll") for (int n = 0; n < 2; ++n) _Pragma("unroll") for (int k = 0; k < 2; ++k) \
;         acc[ai][bj][m][n] = __builtin_amdgcn_mfma_f32_16x16x32_bf16(Bt[n][k], At[m][k], acc[ai][bj][m][n], 0, 0, 0); __builtin_amdgcn_s_setprio(0); } while (0)
; #define PG8_WAIT_V(n) asm volatile("s_waitcnt vmcnt(" #n ")" ::: "memory")
; #define PG8_WAIT_L(n) asm volatile("s_waitcnt lgkmcnt(" #n ")" ::: "memory")
; #define PG8_BAR __builtin_amdgcn_s_barrier()
; #define PG8_SCHED __builtin_amdgcn_sched_barrier(0)
; template <class Epi, class Sched, bool ALIGN_EPI = false, bool SP2 = false>
; __device__ __forceinline__ void gemm_phase(PG8_LAS unsigned char* lds, const Gemm g, const Sched& S, const Epi& E, const int wid) {
;     ...
;             PG8_LDA(At, 1, 1); PG8_STAGE(PG8_SB(1, 0), b3, voffB); PG8_STAGE(PG8_SB(1, 1), b3 + hsB, voffB); PG8_STAGE(PG8_SA(1, 0), a3, voffA);
;             PG8_WAIT_V(8); PG8_WAIT_L(0); PG8_BAR; PG8_MMA(1, 0, At, B0); PG8_MMA(1, 1, At, B1); PG8_BAR; PG8_SCHED;
;     ...
;         if constexpr (ALIGN_EPI) { if (wr == 0) PG8_BAR; }
	s_setprio 0
	s_add_i32 s30, s62, s40
	v_lshl_add_u64 v[210:211], v[210:211], 0, s[22:23]
	s_mov_b32 m0, s30
	ds_read_b128 v[160:163], v199 offset:49152
	ds_read_b128 v[164:167], v199 offset:50176
	ds_read_b128 v[168:171], v199 offset:51200
	ds_read_b128 v[172:175], v199 offset:52224
	ds_read_b128 v[188:191], v199 offset:53248
	ds_read_b128 v[192:195], v199 offset:54272
	ds_read_b128 v[202:205], v199 offset:55296
	ds_read_b128 v[206:209], v199 offset:56320
	global_load_lds_dwordx4 v[210:211], off
	s_add_i32 m0, s30, 0x2000
	s_add_u32 s30, s34, 0x160080
	v_lshl_add_u64 v[210:211], v[212:213], 0, s[22:23]
	s_addc_u32 s31, s35, 0
	s_add_i32 s34, s63, s40
	global_load_lds_dwordx4 v[210:211], off
	v_lshl_add_u64 v[210:211], s[30:31], 0, v[176:177]
	s_mov_b32 m0, s34
	s_nop 0
	global_load_lds_dwordx4 v[210:211], off
	v_lshl_add_u64 v[210:211], s[30:31], 0, v[178:179]
	s_add_i32 m0, s34, 0x2000
	s_nop 0
	global_load_lds_dwordx4 v[210:211], off
	v_lshl_add_u64 v[210:211], v[214:215], 0, s[22:23]
	s_mov_b32 m0, s48
	s_nop 0
	global_load_lds_dwordx4 v[210:211], off
	v_lshl_add_u64 v[210:211], v[216:217], 0, s[22:23]
	s_mov_b32 m0, s49
	s_nop 0
	global_load_lds_dwordx4 v[210:211], off
	s_waitcnt vmcnt(8)
	s_waitcnt lgkmcnt(0)
	s_setprio 1
	s_barrier
	v_mfma_f32_16x16x32_bf16 v[60:63], v[64:67], v[160:163], v[60:63]
	v_mfma_f32_16x16x32_bf16 v[56:59], v[80:83], v[160:163], v[56:59]
	v_mfma_f32_16x16x32_bf16 v[44:47], v[64:67], v[168:171], v[44:47]
	v_mfma_f32_16x16x32_bf16 v[40:43], v[80:83], v[168:171], v[40:43]
	v_mfma_f32_16x16x32_bf16 v[28:31], v[64:67], v[188:191], v[28:31]
	v_mfma_f32_16x16x32_bf16 v[24:27], v[80:83], v[188:191], v[24:27]
	v_mfma_f32_16x16x32_bf16 v[12:15], v[64:67], v[202:205], v[12:15]
	v_mfma_f32_16x16x32_bf16 v[8:11], v[80:83], v[202:205], v[8:11]
	v_mfma_f32_16x16x32_bf16 v[60:63], v[72:75], v[164:167], v[60:63]
	v_mfma_f32_16x16x32_bf16 v[56:59], v[84:87], v[164:167], v[56:59]
	v_mfma_f32_16x16x32_bf16 v[44:47], v[72:75], v[172:175], v[44:47]
	v_mfma_f32_16x16x32_bf16 v[40:43], v[84:87], v[172:175], v[40:43]
	v_mfma_f32_16x16x32_bf16 v[28:31], v[72:75], v[192:195], v[28:31]
	v_mfma_f32_16x16x32_bf16 v[24:27], v[84:87], v[192:195], v[24:27]
	v_mfma_f32_16x16x32_bf16 v[12:15], v[72:75], v[206:209], v[12:15]
	v_mfma_f32_16x16x32_bf16 v[8:11], v[84:87], v[206:209], v[8:11]
	s_setprio 0
	s_setprio 1
	v_mfma_f32_16x16x32_bf16 v[52:55], v[88:91], v[160:163], v[52:55]
	v_mfma_f32_16x16x32_bf16 v[48:51], v[100:103], v[160:163], v[48:51]
	v_mfma_f32_16x16x32_bf16 v[36:39], v[88:91], v[168:171], v[36:39]
	v_mfma_f32_16x16x32_bf16 v[32:35], v[100:103], v[168:171], v[32:35]
	v_mfma_f32_16x16x32_bf16 v[20:23], v[88:91], v[188:191], v[20:23]
	v_mfma_f32_16x16x32_bf16 v[16:19], v[100:103], v[188:191], v[16:19]
	v_mfma_f32_16x16x32_bf16 v[4:7], v[88:91], v[202:205], v[4:7]
	v_mfma_f32_16x16x32_bf16 v[0:3], v[100:103], v[202:205], v[0:3]
	v_mfma_f32_16x16x32_bf16 v[52:55], v[92:95], v[164:167], v[52:55]
	v_mfma_f32_16x16x32_bf16 v[48:51], v[104:107], v[164:167], v[48:51]
	v_mfma_f32_16x16x32_bf16 v[36:39], v[92:95], v[172:175], v[36:39]
	v_mfma_f32_16x16x32_bf16 v[32:35], v[104:107], v[172:175], v[32:35]
	v_mfma_f32_16x16x32_bf16 v[20:23], v[92:95], v[192:195], v[20:23]
	v_mfma_f32_16x16x32_bf16 v[16:19], v[104:107], v[192:195], v[16:19]
	v_mfma_f32_16x16x32_bf16 v[4:7], v[92:95], v[206:209], v[4:7]
	v_mfma_f32_16x16x32_bf16 v[0:3], v[104:107], v[206:209], v[0:3]
	s_barrier
	s_setprio 0
	s_add_i32 s61, s61, 2
	s_add_u32 s59, s59, 0x100
	s_addc_u32 s60, s60, 0
	s_cmpk_gt_u32 s61, 0x55
	s_mov_b64 s[30:31], s[4:5]
	s_cbranch_scc0 .LBB0_497
	s_and_b64 vcc, exec, s[24:25]
	s_cbranch_vccz .LBB0_500
	s_barrier

; #define PG8_STAGE(bufoff, gbase, voff) do { _Pragma("unroll") for (int _i = 0; _i < 2; ++_i) \
;         __builtin_amdgcn_global_load_lds((const unsigned*)((const char*)(gbase) + (voff)[_i]), (PG8_LAS unsigned*)(lds + (bufoff) + ldsw + _i * 8192), 16, 0, 0); } while (0)
; #define PG8_LDA(dst, b, h) do { _Pragma("unroll") for (int m = 0; m < 4; ++m) _Pragma("unroll") for (int k = 0; k < 2; ++k) dst[m][k] = *(const PG8_LAS bf16x8*)(lds + PG8_SA(b, h) + aoff + m * 2048 + k * 1024); } while (0)
; #define PG8_LDB(dst, b, h) do { _Pragma("unroll") for (int n = 0; n < 2; ++n) _Pragma("unroll") for (int k = 0; k < 2; ++k) dst[n][k] = *(const PG8_LAS bf16x8*)(lds + PG8_SB(b, h) + boff + n * 2048 + k * 1024); } while (0)
; #define PG8_MMA(ai, bj, At, Bt) do { __builtin_amdgcn_s_setprio(1); _Pragma("unroll") for (int m = 0; m < 4; ++m) _Pragma("unroll") for (int n = 0; n < 2; ++n) _Pragma("unroll") for (int k = 0; k < 2; ++k) \
;         acc[ai][bj][m][n] = __builtin_amdgcn_mfma_f32_16x16x32_bf16(Bt[n][k], At[m][k], acc[ai][bj][m][n], 0, 0, 0); __builtin_amdgcn_s_setprio(0); } while (0)
; #define PG8_WAIT_V(n) asm volatile("s_waitcnt vmcnt(" #n ")" ::: "memory")
; #define PG8_WAIT_L(n) asm volatile("s_waitcnt lgkmcnt(" #n ")" ::: "memory")
; #define PG8_BAR __builtin_amdgcn_s_barrier()
; #define PG8_SCHED __builtin_amdgcn_sched_barrier(0)
; template <class Epi, class Sched, bool ALIGN_EPI = false, bool SP2 = false>
; __device__ __forceinline__ void gemm_phase(PG8_LAS unsigned char* lds, const Gemm g, const Sched& S, const Epi& E, const int wid) {
;     ...
;             PG8_LDB(B0, 0, 0); PG8_LDB(B1, 0, 1); PG8_SCHED; PG8_LDA(At, 0, 0); PG8_STAGE(PG8_SA(1, 1), a1 + hsA, voffA);
;             PG8_WAIT_V(8); PG8_WAIT_L(0); PG8_BAR; PG8_MMA(0, 0, At, B0); PG8_MMA(0, 1, At, B1); PG8_BAR; PG8_SCHED;
;             PG8_LDA(At, 0, 1); PG8_STAGE(PG8_SB(0, 0), b2, voffB); PG8_STAGE(PG8_SB(0, 1), b2 + hsB, voffB); PG8_STAGE(PG8_SA(0, 0), a2, voffA);
.LBB0_588:
	ds_read_b128 v[128:131], v237
	ds_read_b128 v[132:135], v237 offset:1024
	ds_read_b128 v[136:139], v237 offset:2048
	ds_read_b128 v[140:143], v237 offset:3072
	ds_read_b128 v[144:147], v238
	ds_read_b128 v[148:151], v238 offset:1024
	ds_read_b128 v[152:155], v238 offset:2048
	ds_read_b128 v[156:159], v238 offset:3072
	s_add_u32 s8, s6, 0xfff80080
	s_addc_u32 s9, s7, -1
	s_cmp_eq_u32 s87, 28
	s_cselect_b32 s53, s5, s9
	s_cselect_b32 s52, s47, s8
	s_cselect_b32 s9, s45, s86
	s_cselect_b32 s8, s54, s55
	v_lshl_add_u64 v[210:211], s[6:7], 0, v[180:181]
	s_add_i32 m0, s59, 0xc000
	ds_read_b128 v[160:163], v239
	ds_read_b128 v[164:167], v239 offset:1024
	ds_read_b128 v[186:189], v239 offset:2048
	ds_read_b128 v[190:193], v239 offset:3072
	ds_read_b128 v[194:197], v239 offset:4096
	ds_read_b128 v[198:201], v239 offset:5120
	ds_read_b128 v[202:205], v239 offset:6144
	ds_read_b128 v[206:209], v239 offset:7168
	global_load_lds_dwordx4 v[210:211], off
	v_lshl_add_u64 v[210:211], s[6:7], 0, v[178:179]
	s_add_i32 m0, s59, 0xe000
	s_nop 0
	global_load_lds_dwordx4 v[210:211], off
	s_waitcnt vmcnt(8)
	s_waitcnt lgkmcnt(0)
	s_setprio 1
	s_barrier
	v_mfma_f32_16x16x32_bf16 v[124:127], v[128:131], v[160:163], v[124:127]
	v_mfma_f32_16x16x32_bf16 v[120:123], v[136:139], v[160:163], v[120:123]
	v_mfma_f32_16x16x32_bf16 v[108:111], v[128:131], v[186:189], v[108:111]
	v_mfma_f32_16x16x32_bf16 v[104:107], v[136:139], v[186:189], v[104:107]
	v_mfma_f32_16x16x32_bf16 v[92:95], v[128:131], v[194:197], v[92:95]
	v_mfma_f32_16x16x32_bf16 v[88:91], v[136:139], v[194:197], v[88:91]
	v_mfma_f32_16x16x32_bf16 v[76:79], v[128:131], v[202:205], v[76:79]
	v_mfma_f32_16x16x32_bf16 v[72:75], v[136:139], v[202:205], v[72:75]
	v_mfma_f32_16x16x32_bf16 v[124:127], v[132:135], v[164:167], v[124:127]
	v_mfma_f32_16x16x32_bf16 v[120:123], v[140:143], v[164:167], v[120:123]
	v_mfma_f32_16x16x32_bf16 v[108:111], v[132:135], v[190:193], v[108:111]
	v_mfma_f32_16x16x32_bf16 v[104:107], v[140:143], v[190:193], v[104:107]
	v_mfma_f32_16x16x32_bf16 v[92:95], v[132:135], v[198:201], v[92:95]
	v_mfma_f32_16x16x32_bf16 v[88:91], v[140:143], v[198:201], v[88:91]
	v_mfma_f32_16x16x32_bf16 v[76:79], v[132:135], v[206:209], v[76:79]
	v_mfma_f32_16x16x32_bf16 v[72:75], v[140:143], v[206:209], v[72:75]
	s_setprio 0
	s_setprio 1
	v_mfma_f32_16x16x32_bf16 v[116:119], v[144:147], v[160:163], v[116:119]
	v_mfma_f32_16x16x32_bf16 v[112:115], v[152:155], v[160:163], v[112:115]
	v_mfma_f32_16x16x32_bf16 v[100:103], v[144:147], v[186:189], v[100:103]
	v_mfma_f32_16x16x32_bf16 v[96:99], v[152:155], v[186:189], v[96:99]
	v_mfma_f32_16x16x32_bf16 v[84:87], v[144:147], v[194:197], v[84:87]
	v_mfma_f32_16x16x32_bf16 v[80:83], v[152:155], v[194:197], v[80:83]
	v_mfma_f32_16x16x32_bf16 v[68:71], v[144:147], v[202:205], v[68:71]
	v_mfma_f32_16x16x32_bf16 v[64:67], v[152:155], v[202:205], v[64:67]
	v_mfma_f32_16x16x32_bf16 v[116:119], v[148:151], v[164:167], v[116:119]
	v_mfma_f32_16x16x32_bf16 v[112:115], v[156:159], v[164:167], v[112:115]
	v_mfma_f32_16x16x32_bf16 v[100:103], v[148:151], v[190:193], v[100:103]
	v_mfma_f32_16x16x32_bf16 v[96:99], v[156:159], v[190:193], v[96:99]
	v_mfma_f32_16x16x32_bf16 v[84:87], v[148:151], v[198:201], v[84:87]
	v_mfma_f32_16x16x32_bf16 v[80:83], v[156:159], v[198:201], v[80:83]
	v_mfma_f32_16x16x32_bf16 v[68:71], v[148:151], v[206:209], v[68:71]
	v_mfma_f32_16x16x32_bf16 v[64:67], v[156:159], v[206:209], v[64:67]
	s_barrier
	s_setprio 0
	s_add_i32 s88, s81, s58
	v_lshl_add_u64 v[210:211], s[8:9], 0, v[170:171]
	s_mov_b32 m0, s88
	ds_read_b128 v[160:163], v239 offset:16384
	ds_read_b128 v[164:167], v239 offset:17408
	ds_read_b128 v[186:189], v239 offset:18432
	ds_read_b128 v[190:193], v239 offset:19456
	ds_read_b128 v[194:197], v239 offset:20480
	ds_read_b128 v[198:201], v239 offset:21504
	ds_read_b128 v[202:205], v239 offset:22528
	ds_read_b128 v[206:209], v239 offset:23552
	global_load_lds_dwordx4 v[210:211], off
	s_add_i32 m0, s88, 0x2000
	s_add_u32 s88, s8, 0x80000
	v_lshl_add_u64 v[212:213], s[8:9], 0, v[174:175]
	s_addc_u32 s89, s9, 0
	s_add_i32 s90, s82, s58
	global_load_lds_dwordx4 v[212:213], off
	v_lshl_add_u64 v[214:215], s[88:89], 0, v[170:171]
	s_mov_b32 m0, s90
	v_lshl_add_u64 v[216:217], s[52:53], 0, v[172:173]
	global_load_lds_dwordx4 v[214:215], off
	v_lshl_add_u64 v[214:215], s[88:89], 0, v[174:175]
	s_add_i32 m0, s90, 0x2000
	s_nop 0
	global_load_lds_dwordx4 v[214:215], off
	v_lshl_add_u64 v[214:215], s[52:53], 0, v[168:169]
	s_mov_b32 m0, s59
	s_nop 0
	global_load_lds_dwordx4 v[214:215], off
	s_mov_b32 m0, s60
	s_nop 0
	global_load_lds_dwordx4 v[216:217], off
	s_waitcnt vmcnt(8)
	s_waitcnt lgkmcnt(0)
	s_setprio 1
	s_barrier
; #define PG8_STAGE(bufoff, gbase, voff) do { _Pragma("unroll") for (int _i = 0; _i < 2; ++_i) \
;         __builtin_amdgcn_global_load_lds((const unsigned*)((const char*)(gbase) + (voff)[_i]), (PG8_LAS unsigned*)(lds + (bufoff) + ldsw + _i * 8192), 16, 0, 0); } while (0)
; #define PG8_LDA(dst, b, h) do { _Pragma("unroll") for (int m = 0; m < 4; ++m) _Pragma("unroll") for (int k = 0; k < 2; ++k) dst[m][k] = *(const PG8_LAS bf16x8*)(lds + PG8_SA(b, h) + aoff + m * 2048 + k * 1024); } while (0)
; #define PG8_LDB(dst, b, h) do { _Pragma("unroll") for (int n = 0; n < 2; ++n) _Pragma("unroll") for (int k = 0; k < 2; ++k) dst[n][k] = *(const PG8_LAS bf16x8*)(lds + PG8_SB(b, h) + boff + n * 2048 + k * 1024); } while (0)
; #define PG8_MMA(ai, bj, At, Bt) do { __builtin_amdgcn_s_setprio(1); _Pragma("unroll") for (int m = 0; m < 4; ++m) _Pragma("unroll") for (int n = 0; n < 2; ++n) _Pragma("unroll") for (int k = 0; k < 2; ++k) \
;         acc[ai][bj][m][n] = __builtin_amdgcn_mfma_f32_16x16x32_bf16(Bt[n][k], At[m][k], acc[ai][bj][m][n], 0, 0, 0); __builtin_amdgcn_s_setprio(0); } while (0)
; #define PG8_WAIT_V(n) asm volatile("s_waitcnt vmcnt(" #n ")" ::: "memory")
; #define PG8_WAIT_L(n) asm volatile("s_waitcnt lgkmcnt(" #n ")" ::: "memory")
; #define PG8_BAR __builtin_amdgcn_s_barrier()
; #define PG8_SCHED __builtin_amdgcn_sched_barrier(0)
; template <class Epi, class Sched, bool ALIGN_EPI = false, bool SP2 = false>
; __device__ __forceinline__ void gemm_phase(PG8_LAS unsigned char* lds, const Gemm g, const Sched& S, const Epi& E, const int wid) {
;     ...
;             PG8_WAIT_V(8); PG8_WAIT_L(0); PG8_BAR; PG8_MMA(1, 0, At, B0); PG8_MMA(1, 1, At, B1); PG8_BAR; PG8_SCHED;
;             PG8_LDB(B0, 1, 0); PG8_LDB(B1, 1, 1); PG8_SCHED; PG8_LDA(At, 1, 0); PG8_STAGE(PG8_SA(0, 1), a2 + hsA, voffA);
;             PG8_WAIT_V(8); PG8_WAIT_L(0); PG8_BAR; PG8_MMA(0, 0, At, B0); PG8_MMA(0, 1, At, B1); PG8_BAR; PG8_SCHED;
	v_mfma_f32_16x16x32_bf16 v[60:63], v[128:131], v[160:163], v[60:63]
	v_mfma_f32_16x16x32_bf16 v[56:59], v[136:139], v[160:163], v[56:59]
	v_mfma_f32_16x16x32_bf16 v[44:47], v[128:131], v[186:189], v[44:47]
	v_mfma_f32_16x16x32_bf16 v[40:43], v[136:139], v[186:189], v[40:43]
	v_mfma_f32_16x16x32_bf16 v[28:31], v[128:131], v[194:197], v[28:31]
	v_mfma_f32_16x16x32_bf16 v[24:27], v[136:139], v[194:197], v[24:27]
	v_mfma_f32_16x16x32_bf16 v[12:15], v[128:131], v[202:205], v[12:15]
	v_mfma_f32_16x16x32_bf16 v[8:11], v[136:139], v[202:205], v[8:11]
	v_mfma_f32_16x16x32_bf16 v[60:63], v[132:135], v[164:167], v[60:63]
	v_mfma_f32_16x16x32_bf16 v[56:59], v[140:143], v[164:167], v[56:59]
	v_mfma_f32_16x16x32_bf16 v[44:47], v[132:135], v[190:193], v[44:47]
	v_mfma_f32_16x16x32_bf16 v[40:43], v[140:143], v[190:193], v[40:43]
	v_mfma_f32_16x16x32_bf16 v[28:31], v[132:135], v[198:201], v[28:31]
	v_mfma_f32_16x16x32_bf16 v[24:27], v[140:143], v[198:201], v[24:27]
	v_mfma_f32_16x16x32_bf16 v[12:15], v[132:135], v[206:209], v[12:15]
	v_mfma_f32_16x16x32_bf16 v[8:11], v[140:143], v[206:209], v[8:11]
	s_setprio 0
	s_setprio 1
	v_mfma_f32_16x16x32_bf16 v[52:55], v[144:147], v[160:163], v[52:55]
	v_mfma_f32_16x16x32_bf16 v[48:51], v[152:155], v[160:163], v[48:51]
	v_mfma_f32_16x16x32_bf16 v[36:39], v[144:147], v[186:189], v[36:39]
	v_mfma_f32_16x16x32_bf16 v[32:35], v[152:155], v[186:189], v[32:35]
	v_mfma_f32_16x16x32_bf16 v[20:23], v[144:147], v[194:197], v[20:23]
	v_mfma_f32_16x16x32_bf16 v[16:19], v[152:155], v[194:197], v[16:19]
	v_mfma_f32_16x16x32_bf16 v[4:7], v[144:147], v[202:205], v[4:7]
	v_mfma_f32_16x16x32_bf16 v[0:3], v[152:155], v[202:205], v[0:3]
	v_mfma_f32_16x16x32_bf16 v[52:55], v[148:151], v[164:167], v[52:55]
	v_mfma_f32_16x16x32_bf16 v[48:51], v[156:159], v[164:167], v[48:51]
	v_mfma_f32_16x16x32_bf16 v[36:39], v[148:151], v[190:193], v[36:39]
	v_mfma_f32_16x16x32_bf16 v[32:35], v[156:159], v[190:193], v[32:35]
	v_mfma_f32_16x16x32_bf16 v[20:23], v[148:151], v[198:201], v[20:23]
	v_mfma_f32_16x16x32_bf16 v[16:19], v[156:159], v[198:201], v[16:19]
	v_mfma_f32_16x16x32_bf16 v[4:7], v[148:151], v[206:209], v[4:7]
	v_mfma_f32_16x16x32_bf16 v[0:3], v[156:159], v[206:209], v[0:3]
	s_barrier
	s_setprio 0
	s_add_i32 s88, 0, 0x18000
	s_add_i32 s89, 0, 0x1c000
	v_add_u32_e32 v140, s88, v236
	v_add_u32_e32 v156, s89, v236
	ds_read_b128 v[128:131], v140
	ds_read_b128 v[132:135], v140 offset:1024
	ds_read_b128 v[136:139], v140 offset:2048
	ds_read_b128 v[140:143], v140 offset:3072
	ds_read_b128 v[144:147], v156
	ds_read_b128 v[148:151], v156 offset:1024
	ds_read_b128 v[152:155], v156 offset:2048
	ds_read_b128 v[156:159], v156 offset:3072
	s_add_u32 s52, s52, 0x80000
	s_addc_u32 s53, s53, 0
	s_mov_b32 m0, s61
	v_lshl_add_u64 v[218:219], s[52:53], 0, v[168:169]
	ds_read_b128 v[160:163], v239 offset:32768
	ds_read_b128 v[164:167], v239 offset:33792
	ds_read_b128 v[186:189], v239 offset:34816
	ds_read_b128 v[190:193], v239 offset:35840
	ds_read_b128 v[194:197], v239 offset:36864
	ds_read_b128 v[198:201], v239 offset:37888
	ds_read_b128 v[202:205], v239 offset:38912
	ds_read_b128 v[206:209], v239 offset:39936
	global_load_lds_dwordx4 v[218:219], off
	v_lshl_add_u64 v[218:219], s[52:53], 0, v[172:173]
	s_mov_b32 m0, s62
	s_nop 0
	global_load_lds_dwordx4 v[218:219], off
	s_waitcnt vmcnt(8)
	s_waitcnt lgkmcnt(0)
	s_setprio 1
	s_barrier
	v_mfma_f32_16x16x32_bf16 v[124:127], v[128:131], v[160:163], v[124:127]
	v_mfma_f32_16x16x32_bf16 v[120:123], v[136:139], v[160:163], v[120:123]
	v_mfma_f32_16x16x32_bf16 v[108:111], v[128:131], v[186:189], v[108:111]
	v_mfma_f32_16x16x32_bf16 v[104:107], v[136:139], v[186:189], v[104:107]
	v_mfma_f32_16x16x32_bf16 v[92:95], v[128:131], v[194:197], v[92:95]
	v_mfma_f32_16x16x32_bf16 v[88:91], v[136:139], v[194:197], v[88:91]
	v_mfma_f32_16x16x32_bf16 v[76:79], v[128:131], v[202:205], v[76:79]
	v_mfma_f32_16x16x32_bf16 v[72:75], v[136:139], v[202:205], v[72:75]
	v_mfma_f32_16x16x32_bf16 v[124:127], v[132:135], v[164:167], v[124:127]
	v_mfma_f32_16x16x32_bf16 v[120:123], v[140:143], v[164:167], v[120:123]
	v_mfma_f32_16x16x32_bf16 v[108:111], v[132:135], v[190:193], v[108:111]
	v_mfma_f32_16x16x32_bf16 v[104:107], v[140:143], v[190:193], v[104:107]
	v_mfma_f32_16x16x32_bf16 v[92:95], v[132:135], v[198:201], v[92:95]
	v_mfma_f32_16x16x32_bf16 v[88:91], v[140:143], v[198:201], v[88:91]
	v_mfma_f32_16x16x32_bf16 v[76:79], v[132:135], v[206:209], v[76:79]
	v_mfma_f32_16x16x32_bf16 v[72:75], v[140:143], v[206:209], v[72:75]
	s_setprio 0
	s_setprio 1
	v_mfma_f32_16x16x32_bf16 v[116:119], v[144:147], v[160:163], v[116:119]
	v_mfma_f32_16x16x32_bf16 v[112:115], v[152:155], v[160:163], v[112:115]
	v_mfma_f32_16x16x32_bf16 v[100:103], v[144:147], v[186:189], v[100:103]
	v_mfma_f32_16x16x32_bf16 v[96:99], v[152:155], v[186:189], v[96:99]
	v_mfma_f32_16x16x32_bf16 v[84:87], v[144:147], v[194:197], v[84:87]
	v_mfma_f32_16x16x32_bf16 v[80:83], v[152:155], v[194:197], v[80:83]
	v_mfma_f32_16x16x32_bf16 v[68:71], v[144:147], v[202:205], v[68:71]
	v_mfma_f32_16x16x32_bf16 v[64:67], v[152:155], v[202:205], v[64:67]
	v_mfma_f32_16x16x32_bf16 v[116:119], v[148:151], v[164:167], v[116:119]
	v_mfma_f32_16x16x32_bf16 v[112:115], v[156:159], v[164:167], v[112:115]
	v_mfma_f32_16x16x32_bf16 v[100:103], v[148:151], v[190:193], v[100:103]
	v_mfma_f32_16x16x32_bf16 v[96:99], v[156:159], v[190:193], v[96:99]
	v_mfma_f32_16x16x32_bf16 v[84:87], v[148:151], v[198:201], v[84:87]
	v_mfma_f32_16x16x32_bf16 v[80:83], v[156:159], v[198:201], v[80:83]
	v_mfma_f32_16x16x32_bf16 v[68:71], v[148:151], v[206:209], v[68:71]
	v_mfma_f32_16x16x32_bf16 v[64:67], v[156:159], v[206:209], v[64:67]
	s_barrier
; #define PG8_STAGE(bufoff, gbase, voff) do { _Pragma("unroll") for (int _i = 0; _i < 2; ++_i) \
;         __builtin_amdgcn_global_load_lds((const unsigned*)((const char*)(gbase) + (voff)[_i]), (PG8_LAS unsigned*)(lds + (bufoff) + ldsw + _i * 8192), 16, 0, 0); } while (0)
; #define PG8_LDA(dst, b, h) do { _Pragma("unroll") for (int m = 0; m < 4; ++m) _Pragma("unroll") for (int k = 0; k < 2; ++k) dst[m][k] = *(const PG8_LAS bf16x8*)(lds + PG8_SA(b, h) + aoff + m * 2048 + k * 1024); } while (0)
; #define PG8_MMA(ai, bj, At, Bt) do { __builtin_amdgcn_s_setprio(1); _Pragma("unroll") for (int m = 0; m < 4; ++m) _Pragma("unroll") for (int n = 0; n < 2; ++n) _Pragma("unroll") for (int k = 0; k < 2; ++k) \
;         acc[ai][bj][m][n] = __builtin_amdgcn_mfma_f32_16x16x32_bf16(Bt[n][k], At[m][k], acc[ai][bj][m][n], 0, 0, 0); __builtin_amdgcn_s_setprio(0); } while (0)
; #define PG8_WAIT_V(n) asm volatile("s_waitcnt vmcnt(" #n ")" ::: "memory")
; #define PG8_WAIT_L(n) asm volatile("s_waitcnt lgkmcnt(" #n ")" ::: "memory")
; #define PG8_BAR __builtin_amdgcn_s_barrier()
; #define PG8_SCHED __builtin_amdgcn_sched_barrier(0)
; template <class Epi, class Sched, bool ALIGN_EPI = false, bool SP2 = false>
; __device__ __forceinline__ void gemm_phase(PG8_LAS unsigned char* lds, const Gemm g, const Sched& S, const Epi& E, const int wid) {
;     ...
;             PG8_LDA(At, 1, 1); PG8_STAGE(PG8_SB(1, 0), b3, voffB); PG8_STAGE(PG8_SB(1, 1), b3 + hsB, voffB); PG8_STAGE(PG8_SA(1, 0), a3, voffA);
;             PG8_WAIT_V(8); PG8_WAIT_L(0); PG8_BAR; PG8_MMA(1, 0, At, B0); PG8_MMA(1, 1, At, B1); PG8_BAR; PG8_SCHED;
;     ...
;         if constexpr (ALIGN_EPI) { if (wr == 0) PG8_BAR; }
	s_setprio 0
	s_add_i32 s52, s88, s58
	v_lshl_add_u64 v[210:211], v[210:211], 0, s[26:27]
	s_mov_b32 m0, s52
	ds_read_b128 v[160:163], v239 offset:49152
	ds_read_b128 v[164:167], v239 offset:50176
	ds_read_b128 v[186:189], v239 offset:51200
	ds_read_b128 v[190:193], v239 offset:52224
	ds_read_b128 v[194:197], v239 offset:53248
	ds_read_b128 v[198:201], v239 offset:54272
	ds_read_b128 v[202:205], v239 offset:55296
	ds_read_b128 v[206:209], v239 offset:56320
	global_load_lds_dwordx4 v[210:211], off
	s_add_i32 m0, s52, 0x2000
	s_add_u32 s8, s8, 0x80080
	v_lshl_add_u64 v[210:211], v[212:213], 0, s[26:27]
	s_addc_u32 s9, s9, 0
	s_add_i32 s52, s89, s58
	global_load_lds_dwordx4 v[210:211], off
	v_lshl_add_u64 v[210:211], s[8:9], 0, v[170:171]
	s_mov_b32 m0, s52
	s_nop 0
	global_load_lds_dwordx4 v[210:211], off
	v_lshl_add_u64 v[210:211], s[8:9], 0, v[174:175]
	s_add_i32 m0, s52, 0x2000
	s_nop 0
	global_load_lds_dwordx4 v[210:211], off
	v_lshl_add_u64 v[210:211], v[214:215], 0, s[26:27]
	s_mov_b32 m0, s73
	s_nop 0
	global_load_lds_dwordx4 v[210:211], off
	v_lshl_add_u64 v[210:211], v[216:217], 0, s[26:27]
	s_mov_b32 m0, s74
	s_nop 0
	global_load_lds_dwordx4 v[210:211], off
	s_waitcnt vmcnt(8)
	s_waitcnt lgkmcnt(0)
	s_setprio 1
	s_barrier
	v_mfma_f32_16x16x32_bf16 v[60:63], v[128:131], v[160:163], v[60:63]
	v_mfma_f32_16x16x32_bf16 v[56:59], v[136:139], v[160:163], v[56:59]
	v_mfma_f32_16x16x32_bf16 v[44:47], v[128:131], v[186:189], v[44:47]
	v_mfma_f32_16x16x32_bf16 v[40:43], v[136:139], v[186:189], v[40:43]
	v_mfma_f32_16x16x32_bf16 v[28:31], v[128:131], v[194:197], v[28:31]
	v_mfma_f32_16x16x32_bf16 v[24:27], v[136:139], v[194:197], v[24:27]
	v_mfma_f32_16x16x32_bf16 v[12:15], v[128:131], v[202:205], v[12:15]
	v_mfma_f32_16x16x32_bf16 v[8:11], v[136:139], v[202:205], v[8:11]
	v_mfma_f32_16x16x32_bf16 v[60:63], v[132:135], v[164:167], v[60:63]
	v_mfma_f32_16x16x32_bf16 v[56:59], v[140:143], v[164:167], v[56:59]
	v_mfma_f32_16x16x32_bf16 v[44:47], v[132:135], v[190:193], v[44:47]
	v_mfma_f32_16x16x32_bf16 v[40:43], v[140:143], v[190:193], v[40:43]
	v_mfma_f32_16x16x32_bf16 v[28:31], v[132:135], v[198:201], v[28:31]
	v_mfma_f32_16x16x32_bf16 v[24:27], v[140:143], v[198:201], v[24:27]
	v_mfma_f32_16x16x32_bf16 v[12:15], v[132:135], v[206:209], v[12:15]
	v_mfma_f32_16x16x32_bf16 v[8:11], v[140:143], v[206:209], v[8:11]
	s_setprio 0
	s_setprio 1
	v_mfma_f32_16x16x32_bf16 v[52:55], v[144:147], v[160:163], v[52:55]
	v_mfma_f32_16x16x32_bf16 v[48:51], v[152:155], v[160:163], v[48:51]
	v_mfma_f32_16x16x32_bf16 v[36:39], v[144:147], v[186:189], v[36:39]
	v_mfma_f32_16x16x32_bf16 v[32:35], v[152:155], v[186:189], v[32:35]
	v_mfma_f32_16x16x32_bf16 v[20:23], v[144:147], v[194:197], v[20:23]
	v_mfma_f32_16x16x32_bf16 v[16:19], v[152:155], v[194:197], v[16:19]
	v_mfma_f32_16x16x32_bf16 v[4:7], v[144:147], v[202:205], v[4:7]
	v_mfma_f32_16x16x32_bf16 v[0:3], v[152:155], v[202:205], v[0:3]
	v_mfma_f32_16x16x32_bf16 v[52:55], v[148:151], v[164:167], v[52:55]
	v_mfma_f32_16x16x32_bf16 v[48:51], v[156:159], v[164:167], v[48:51]
	v_mfma_f32_16x16x32_bf16 v[36:39], v[148:151], v[190:193], v[36:39]
	v_mfma_f32_16x16x32_bf16 v[32:35], v[156:159], v[190:193], v[32:35]
	v_mfma_f32_16x16x32_bf16 v[20:23], v[148:151], v[198:201], v[20:23]
	v_mfma_f32_16x16x32_bf16 v[16:19], v[156:159], v[198:201], v[16:19]
	v_mfma_f32_16x16x32_bf16 v[4:7], v[148:151], v[206:209], v[4:7]
	v_mfma_f32_16x16x32_bf16 v[0:3], v[156:159], v[206:209], v[0:3]
	s_barrier
	s_setprio 0
	s_add_i32 s87, s87, 2
	s_add_u32 s55, s55, 0x100
	s_addc_u32 s86, s86, 0
	s_add_u32 s6, s6, 0x100
	s_addc_u32 s7, s7, 0
	s_cmp_gt_u32 s87, 29
	s_cbranch_scc0 .LBB0_588
	s_and_b64 vcc, exec, s[28:29]
	s_cbranch_vccz .LBB0_591
	s_barrier

; #define PG8_STAGE(bufoff, gbase, voff) do { _Pragma("unroll") for (int _i = 0; _i < 2; ++_i) \
;         __builtin_amdgcn_global_load_lds((const unsigned*)((const char*)(gbase) + (voff)[_i]), (PG8_LAS unsigned*)(lds + (bufoff) + ldsw + _i * 8192), 16, 0, 0); } while (0)
; #define PG8_LDA(dst, b, h) do { _Pragma("unroll") for (int m = 0; m < 4; ++m) _Pragma("unroll") for (int k = 0; k < 2; ++k) dst[m][k] = *(const PG8_LAS bf16x8*)(lds + PG8_SA(b, h) + aoff + m * 2048 + k * 1024); } while (0)
; #define PG8_LDB(dst, b, h) do { _Pragma("unroll") for (int n = 0; n < 2; ++n) _Pragma("unroll") for (int k = 0; k < 2; ++k) dst[n][k] = *(const PG8_LAS bf16x8*)(lds + PG8_SB(b, h) + boff + n * 2048 + k * 1024); } while (0)
; #define PG8_MMA(ai, bj, At, Bt) do { __builtin_amdgcn_s_setprio(1); _Pragma("unroll") for (int m = 0; m < 4; ++m) _Pragma("unroll") for (int n = 0; n < 2; ++n) _Pragma("unroll") for (int k = 0; k < 2; ++k) \
;         acc[ai][bj][m][n] = __builtin_amdgcn_mfma_f32_16x16x32_bf16(Bt[n][k], At[m][k], acc[ai][bj][m][n], 0, 0, 0); __builtin_amdgcn_s_setprio(0); } while (0)
; #define PG8_WAIT_V(n) asm volatile("s_waitcnt vmcnt(" #n ")" ::: "memory")
; #define PG8_WAIT_L(n) asm volatile("s_waitcnt lgkmcnt(" #n ")" ::: "memory")
; #define PG8_BAR __builtin_amdgcn_s_barrier()
; #define PG8_SCHED __builtin_amdgcn_sched_barrier(0)
; template <class Epi, class Sched, bool ALIGN_EPI = false, bool SP2 = false>
; __device__ __forceinline__ void gemm_phase(PG8_LAS unsigned char* lds, const Gemm g, const Sched& S, const Epi& E, const int wid) {
;     ...
;             PG8_LDB(B0, 0, 0); PG8_LDB(B1, 0, 1); PG8_SCHED; PG8_LDA(At, 0, 0); PG8_STAGE(PG8_SA(1, 1), a1 + hsA, voffA);
;             PG8_WAIT_V(8); PG8_WAIT_L(0); PG8_BAR; PG8_MMA(0, 0, At, B0); PG8_MMA(0, 1, At, B1); PG8_BAR; PG8_SCHED;
;             PG8_LDA(At, 0, 1); PG8_STAGE(PG8_SB(0, 0), b2, voffB); PG8_STAGE(PG8_SB(0, 1), b2 + hsB, voffB); PG8_STAGE(PG8_SA(0, 0), a2, voffA);
.LBB0_773:
	ds_read_b128 v[150:153], v147
	ds_read_b128 v[154:157], v147 offset:1024
	ds_read_b128 v[158:161], v147 offset:2048
	ds_read_b128 v[162:165], v147 offset:3072
	ds_read_b128 v[166:169], v148
	ds_read_b128 v[170:173], v148 offset:1024
	ds_read_b128 v[174:177], v148 offset:2048
	ds_read_b128 v[178:181], v148 offset:3072
	s_add_u32 s28, s26, 0x100
	s_addc_u32 s29, s27, 0
	s_cmp_eq_u32 s60, 8
	s_cselect_b32 s35, s5, s29
	s_cselect_b32 s34, s4, s28
	s_cselect_b32 s31, s25, s59
	s_cselect_b32 s30, s24, s58
	v_lshl_add_u64 v[214:215], s[26:27], 0, v[138:139]
	s_add_i32 m0, s40, 0xc000
	ds_read_b128 v[182:185], v149
	ds_read_b128 v[186:189], v149 offset:1024
	ds_read_b128 v[190:193], v149 offset:2048
	ds_read_b128 v[194:197], v149 offset:3072
	ds_read_b128 v[198:201], v149 offset:4096
	ds_read_b128 v[202:205], v149 offset:5120
	ds_read_b128 v[206:209], v149 offset:6144
	ds_read_b128 v[210:213], v149 offset:7168
	global_load_lds_dwordx4 v[214:215], off
	v_lshl_add_u64 v[214:215], s[26:27], 0, v[136:137]
	s_add_i32 m0, s40, 0xe000
	s_nop 0
	global_load_lds_dwordx4 v[214:215], off
	s_waitcnt vmcnt(8)
	s_waitcnt lgkmcnt(0)
	s_setprio 1
	s_barrier
	v_mfma_f32_16x16x32_bf16 v[124:127], v[150:153], v[182:185], v[124:127]
	v_mfma_f32_16x16x32_bf16 v[120:123], v[158:161], v[182:185], v[120:123]
	v_mfma_f32_16x16x32_bf16 v[116:119], v[150:153], v[190:193], v[116:119]
	v_mfma_f32_16x16x32_bf16 v[112:115], v[158:161], v[190:193], v[112:115]
	v_mfma_f32_16x16x32_bf16 v[104:107], v[150:153], v[198:201], v[104:107]
	v_mfma_f32_16x16x32_bf16 v[96:99], v[158:161], v[198:201], v[96:99]
	v_mfma_f32_16x16x32_bf16 v[88:91], v[150:153], v[206:209], v[88:91]
	v_mfma_f32_16x16x32_bf16 v[80:83], v[158:161], v[206:209], v[80:83]
	v_mfma_f32_16x16x32_bf16 v[124:127], v[154:157], v[186:189], v[124:127]
	v_mfma_f32_16x16x32_bf16 v[120:123], v[162:165], v[186:189], v[120:123]
	v_mfma_f32_16x16x32_bf16 v[116:119], v[154:157], v[194:197], v[116:119]
	v_mfma_f32_16x16x32_bf16 v[112:115], v[162:165], v[194:197], v[112:115]
	v_mfma_f32_16x16x32_bf16 v[104:107], v[154:157], v[202:205], v[104:107]
	v_mfma_f32_16x16x32_bf16 v[96:99], v[162:165], v[202:205], v[96:99]
	v_mfma_f32_16x16x32_bf16 v[88:91], v[154:157], v[210:213], v[88:91]
	v_mfma_f32_16x16x32_bf16 v[80:83], v[162:165], v[210:213], v[80:83]
	s_setprio 0
	s_setprio 1
	v_mfma_f32_16x16x32_bf16 v[108:111], v[166:169], v[182:185], v[108:111]
	v_mfma_f32_16x16x32_bf16 v[100:103], v[174:177], v[182:185], v[100:103]
	v_mfma_f32_16x16x32_bf16 v[92:95], v[166:169], v[190:193], v[92:95]
	v_mfma_f32_16x16x32_bf16 v[84:87], v[174:177], v[190:193], v[84:87]
	v_mfma_f32_16x16x32_bf16 v[76:79], v[166:169], v[198:201], v[76:79]
	v_mfma_f32_16x16x32_bf16 v[72:75], v[174:177], v[198:201], v[72:75]
	v_mfma_f32_16x16x32_bf16 v[68:71], v[166:169], v[206:209], v[68:71]
	v_mfma_f32_16x16x32_bf16 v[64:67], v[174:177], v[206:209], v[64:67]
	v_mfma_f32_16x16x32_bf16 v[108:111], v[170:173], v[186:189], v[108:111]
	v_mfma_f32_16x16x32_bf16 v[100:103], v[178:181], v[186:189], v[100:103]
	v_mfma_f32_16x16x32_bf16 v[92:95], v[170:173], v[194:197], v[92:95]
	v_mfma_f32_16x16x32_bf16 v[84:87], v[178:181], v[194:197], v[84:87]
	v_mfma_f32_16x16x32_bf16 v[76:79], v[170:173], v[202:205], v[76:79]
	v_mfma_f32_16x16x32_bf16 v[72:75], v[178:181], v[202:205], v[72:75]
	v_mfma_f32_16x16x32_bf16 v[68:71], v[170:173], v[210:213], v[68:71]
	v_mfma_f32_16x16x32_bf16 v[64:67], v[178:181], v[210:213], v[64:67]
	s_barrier
	s_setprio 0
	s_add_i32 s26, s51, s38
	v_lshl_add_u64 v[214:215], s[30:31], 0, v[132:133]
	s_mov_b32 m0, s26
	ds_read_b128 v[182:185], v149 offset:16384
	ds_read_b128 v[186:189], v149 offset:17408
	ds_read_b128 v[190:193], v149 offset:18432
	ds_read_b128 v[194:197], v149 offset:19456
	ds_read_b128 v[198:201], v149 offset:20480
	ds_read_b128 v[202:205], v149 offset:21504
	ds_read_b128 v[206:209], v149 offset:22528
	ds_read_b128 v[210:213], v149 offset:23552
	global_load_lds_dwordx4 v[214:215], off
	s_add_i32 m0, s26, 0x2000
	s_add_u32 s26, s30, 0x30000
	v_lshl_add_u64 v[216:217], s[30:31], 0, v[128:129]
	s_addc_u32 s27, s31, 0
	s_add_i32 s61, s52, s38
	global_load_lds_dwordx4 v[216:217], off
	v_lshl_add_u64 v[218:219], s[26:27], 0, v[132:133]
	s_mov_b32 m0, s61
	v_lshl_add_u64 v[220:221], s[34:35], 0, v[130:131]
	global_load_lds_dwordx4 v[218:219], off
	v_lshl_add_u64 v[218:219], s[26:27], 0, v[128:129]
	s_add_i32 m0, s61, 0x2000
	s_nop 0
	global_load_lds_dwordx4 v[218:219], off
	v_lshl_add_u64 v[218:219], s[34:35], 0, v[134:135]
	s_mov_b32 m0, s40
	s_nop 0
	global_load_lds_dwordx4 v[218:219], off
	s_mov_b32 m0, s41
	s_nop 0
	global_load_lds_dwordx4 v[220:221], off
	s_waitcnt vmcnt(8)
	s_waitcnt lgkmcnt(0)
	s_setprio 1
	s_barrier
; #define PG8_STAGE(bufoff, gbase, voff) do { _Pragma("unroll") for (int _i = 0; _i < 2; ++_i) \
;         __builtin_amdgcn_global_load_lds((const unsigned*)((const char*)(gbase) + (voff)[_i]), (PG8_LAS unsigned*)(lds + (bufoff) + ldsw + _i * 8192), 16, 0, 0); } while (0)
; #define PG8_LDA(dst, b, h) do { _Pragma("unroll") for (int m = 0; m < 4; ++m) _Pragma("unroll") for (int k = 0; k < 2; ++k) dst[m][k] = *(const PG8_LAS bf16x8*)(lds + PG8_SA(b, h) + aoff + m * 2048 + k * 1024); } while (0)
; #define PG8_LDB(dst, b, h) do { _Pragma("unroll") for (int n = 0; n < 2; ++n) _Pragma("unroll") for (int k = 0; k < 2; ++k) dst[n][k] = *(const PG8_LAS bf16x8*)(lds + PG8_SB(b, h) + boff + n * 2048 + k * 1024); } while (0)
; #define PG8_MMA(ai, bj, At, Bt) do { __builtin_amdgcn_s_setprio(1); _Pragma("unroll") for (int m = 0; m < 4; ++m) _Pragma("unroll") for (int n = 0; n < 2; ++n) _Pragma("unroll") for (int k = 0; k < 2; ++k) \
;         acc[ai][bj][m][n] = __builtin_amdgcn_mfma_f32_16x16x32_bf16(Bt[n][k], At[m][k], acc[ai][bj][m][n], 0, 0, 0); __builtin_amdgcn_s_setprio(0); } while (0)
; #define PG8_WAIT_V(n) asm volatile("s_waitcnt vmcnt(" #n ")" ::: "memory")
; #define PG8_WAIT_L(n) asm volatile("s_waitcnt lgkmcnt(" #n ")" ::: "memory")
; #define PG8_BAR __builtin_amdgcn_s_barrier()
; #define PG8_SCHED __builtin_amdgcn_sched_barrier(0)
; template <class Epi, class Sched, bool ALIGN_EPI = false, bool SP2 = false>
; __device__ __forceinline__ void gemm_phase(PG8_LAS unsigned char* lds, const Gemm g, const Sched& S, const Epi& E, const int wid) {
;     ...
;             PG8_WAIT_V(8); PG8_WAIT_L(0); PG8_BAR; PG8_MMA(1, 0, At, B0); PG8_MMA(1, 1, At, B1); PG8_BAR; PG8_SCHED;
;             PG8_LDB(B0, 1, 0); PG8_LDB(B1, 1, 1); PG8_SCHED; PG8_LDA(At, 1, 0); PG8_STAGE(PG8_SA(0, 1), a2 + hsA, voffA);
;             PG8_WAIT_V(8); PG8_WAIT_L(0); PG8_BAR; PG8_MMA(0, 0, At, B0); PG8_MMA(0, 1, At, B1); PG8_BAR; PG8_SCHED;
	v_mfma_f32_16x16x32_bf16 v[60:63], v[150:153], v[182:185], v[60:63]
	v_mfma_f32_16x16x32_bf16 v[56:59], v[158:161], v[182:185], v[56:59]
	v_mfma_f32_16x16x32_bf16 v[52:55], v[150:153], v[190:193], v[52:55]
	v_mfma_f32_16x16x32_bf16 v[48:51], v[158:161], v[190:193], v[48:51]
	v_mfma_f32_16x16x32_bf16 v[40:43], v[150:153], v[198:201], v[40:43]
	v_mfma_f32_16x16x32_bf16 v[32:35], v[158:161], v[198:201], v[32:35]
	v_mfma_f32_16x16x32_bf16 v[24:27], v[150:153], v[206:209], v[24:27]
	v_mfma_f32_16x16x32_bf16 v[16:19], v[158:161], v[206:209], v[16:19]
	v_mfma_f32_16x16x32_bf16 v[60:63], v[154:157], v[186:189], v[60:63]
	v_mfma_f32_16x16x32_bf16 v[56:59], v[162:165], v[186:189], v[56:59]
	v_mfma_f32_16x16x32_bf16 v[52:55], v[154:157], v[194:197], v[52:55]
	v_mfma_f32_16x16x32_bf16 v[48:51], v[162:165], v[194:197], v[48:51]
	v_mfma_f32_16x16x32_bf16 v[40:43], v[154:157], v[202:205], v[40:43]
	v_mfma_f32_16x16x32_bf16 v[32:35], v[162:165], v[202:205], v[32:35]
	v_mfma_f32_16x16x32_bf16 v[24:27], v[154:157], v[210:213], v[24:27]
	v_mfma_f32_16x16x32_bf16 v[16:19], v[162:165], v[210:213], v[16:19]
	s_setprio 0
	s_setprio 1
	v_mfma_f32_16x16x32_bf16 v[44:47], v[166:169], v[182:185], v[44:47]
	v_mfma_f32_16x16x32_bf16 v[36:39], v[174:177], v[182:185], v[36:39]
	v_mfma_f32_16x16x32_bf16 v[28:31], v[166:169], v[190:193], v[28:31]
	v_mfma_f32_16x16x32_bf16 v[20:23], v[174:177], v[190:193], v[20:23]
	v_mfma_f32_16x16x32_bf16 v[12:15], v[166:169], v[198:201], v[12:15]
	v_mfma_f32_16x16x32_bf16 v[8:11], v[174:177], v[198:201], v[8:11]
	v_mfma_f32_16x16x32_bf16 v[4:7], v[166:169], v[206:209], v[4:7]
	v_mfma_f32_16x16x32_bf16 v[0:3], v[174:177], v[206:209], v[0:3]
	v_mfma_f32_16x16x32_bf16 v[44:47], v[170:173], v[186:189], v[44:47]
	v_mfma_f32_16x16x32_bf16 v[36:39], v[178:181], v[186:189], v[36:39]
	v_mfma_f32_16x16x32_bf16 v[28:31], v[170:173], v[194:197], v[28:31]
	v_mfma_f32_16x16x32_bf16 v[20:23], v[178:181], v[194:197], v[20:23]
	v_mfma_f32_16x16x32_bf16 v[12:15], v[170:173], v[202:205], v[12:15]
	v_mfma_f32_16x16x32_bf16 v[8:11], v[178:181], v[202:205], v[8:11]
	v_mfma_f32_16x16x32_bf16 v[4:7], v[170:173], v[210:213], v[4:7]
	v_mfma_f32_16x16x32_bf16 v[0:3], v[178:181], v[210:213], v[0:3]
	s_barrier
	s_setprio 0
	s_add_i32 s61, 0, 0x18000
	s_add_i32 s62, 0, 0x1c000
	v_add_u32_e32 v162, s61, v145
	v_add_u32_e32 v178, s62, v145
	ds_read_b128 v[150:153], v162
	ds_read_b128 v[154:157], v162 offset:1024
	ds_read_b128 v[158:161], v162 offset:2048
	ds_read_b128 v[162:165], v162 offset:3072
	ds_read_b128 v[166:169], v178
	ds_read_b128 v[170:173], v178 offset:1024
	ds_read_b128 v[174:177], v178 offset:2048
	ds_read_b128 v[178:181], v178 offset:3072
	s_add_u32 s26, s34, 0x600000
	s_addc_u32 s27, s35, 0
	s_mov_b32 m0, s42
	v_lshl_add_u64 v[222:223], s[26:27], 0, v[134:135]
	ds_read_b128 v[182:185], v149 offset:32768
	ds_read_b128 v[186:189], v149 offset:33792
	ds_read_b128 v[190:193], v149 offset:34816
	ds_read_b128 v[194:197], v149 offset:35840
	ds_read_b128 v[198:201], v149 offset:36864
	ds_read_b128 v[202:205], v149 offset:37888
	ds_read_b128 v[206:209], v149 offset:38912
	ds_read_b128 v[210:213], v149 offset:39936
	global_load_lds_dwordx4 v[222:223], off
	v_lshl_add_u64 v[222:223], s[26:27], 0, v[130:131]
	s_mov_b32 m0, s43
	s_nop 0
	global_load_lds_dwordx4 v[222:223], off
	s_waitcnt vmcnt(8)
	s_waitcnt lgkmcnt(0)
	s_setprio 1
	s_barrier
	v_mfma_f32_16x16x32_bf16 v[124:127], v[150:153], v[182:185], v[124:127]
	v_mfma_f32_16x16x32_bf16 v[120:123], v[158:161], v[182:185], v[120:123]
	v_mfma_f32_16x16x32_bf16 v[116:119], v[150:153], v[190:193], v[116:119]
	v_mfma_f32_16x16x32_bf16 v[112:115], v[158:161], v[190:193], v[112:115]
	v_mfma_f32_16x16x32_bf16 v[104:107], v[150:153], v[198:201], v[104:107]
	v_mfma_f32_16x16x32_bf16 v[96:99], v[158:161], v[198:201], v[96:99]
	v_mfma_f32_16x16x32_bf16 v[88:91], v[150:153], v[206:209], v[88:91]
	v_mfma_f32_16x16x32_bf16 v[80:83], v[158:161], v[206:209], v[80:83]
	v_mfma_f32_16x16x32_bf16 v[124:127], v[154:157], v[186:189], v[124:127]
	v_mfma_f32_16x16x32_bf16 v[120:123], v[162:165], v[186:189], v[120:123]
	v_mfma_f32_16x16x32_bf16 v[116:119], v[154:157], v[194:197], v[116:119]
	v_mfma_f32_16x16x32_bf16 v[112:115], v[162:165], v[194:197], v[112:115]
	v_mfma_f32_16x16x32_bf16 v[104:107], v[154:157], v[202:205], v[104:107]
	v_mfma_f32_16x16x32_bf16 v[96:99], v[162:165], v[202:205], v[96:99]
	v_mfma_f32_16x16x32_bf16 v[88:91], v[154:157], v[210:213], v[88:91]
	v_mfma_f32_16x16x32_bf16 v[80:83], v[162:165], v[210:213], v[80:83]
	s_setprio 0
	s_setprio 1
	v_mfma_f32_16x16x32_bf16 v[108:111], v[166:169], v[182:185], v[108:111]
	v_mfma_f32_16x16x32_bf16 v[100:103], v[174:177], v[182:185], v[100:103]
	v_mfma_f32_16x16x32_bf16 v[92:95], v[166:169], v[190:193], v[92:95]
	v_mfma_f32_16x16x32_bf16 v[84:87], v[174:177], v[190:193], v[84:87]
	v_mfma_f32_16x16x32_bf16 v[76:79], v[166:169], v[198:201], v[76:79]
	v_mfma_f32_16x16x32_bf16 v[72:75], v[174:177], v[198:201], v[72:75]
	v_mfma_f32_16x16x32_bf16 v[68:71], v[166:169], v[206:209], v[68:71]
	v_mfma_f32_16x16x32_bf16 v[64:67], v[174:177], v[206:209], v[64:67]
	v_mfma_f32_16x16x32_bf16 v[108:111], v[170:173], v[186:189], v[108:111]
	v_mfma_f32_16x16x32_bf16 v[100:103], v[178:181], v[186:189], v[100:103]
	v_mfma_f32_16x16x32_bf16 v[92:95], v[170:173], v[194:197], v[92:95]
	v_mfma_f32_16x16x32_bf16 v[84:87], v[178:181], v[194:197], v[84:87]
	v_mfma_f32_16x16x32_bf16 v[76:79], v[170:173], v[202:205], v[76:79]
	v_mfma_f32_16x16x32_bf16 v[72:75], v[178:181], v[202:205], v[72:75]
	v_mfma_f32_16x16x32_bf16 v[68:71], v[170:173], v[210:213], v[68:71]
	v_mfma_f32_16x16x32_bf16 v[64:67], v[178:181], v[210:213], v[64:67]
	s_barrier
; #define PG8_STAGE(bufoff, gbase, voff) do { _Pragma("unroll") for (int _i = 0; _i < 2; ++_i) \
;         __builtin_amdgcn_global_load_lds((const unsigned*)((const char*)(gbase) + (voff)[_i]), (PG8_LAS unsigned*)(lds + (bufoff) + ldsw + _i * 8192), 16, 0, 0); } while (0)
; #define PG8_LDA(dst, b, h) do { _Pragma("unroll") for (int m = 0; m < 4; ++m) _Pragma("unroll") for (int k = 0; k < 2; ++k) dst[m][k] = *(const PG8_LAS bf16x8*)(lds + PG8_SA(b, h) + aoff + m * 2048 + k * 1024); } while (0)
; #define PG8_MMA(ai, bj, At, Bt) do { __builtin_amdgcn_s_setprio(1); _Pragma("unroll") for (int m = 0; m < 4; ++m) _Pragma("unroll") for (int n = 0; n < 2; ++n) _Pragma("unroll") for (int k = 0; k < 2; ++k) \
;         acc[ai][bj][m][n] = __builtin_amdgcn_mfma_f32_16x16x32_bf16(Bt[n][k], At[m][k], acc[ai][bj][m][n], 0, 0, 0); __builtin_amdgcn_s_setprio(0); } while (0)
; #define PG8_WAIT_V(n) asm volatile("s_waitcnt vmcnt(" #n ")" ::: "memory")
; #define PG8_WAIT_L(n) asm volatile("s_waitcnt lgkmcnt(" #n ")" ::: "memory")
; #define PG8_BAR __builtin_amdgcn_s_barrier()
; #define PG8_SCHED __builtin_amdgcn_sched_barrier(0)
; template <class Epi, class Sched, bool ALIGN_EPI = false, bool SP2 = false>
; __device__ __forceinline__ void gemm_phase(PG8_LAS unsigned char* lds, const Gemm g, const Sched& S, const Epi& E, const int wid) {
;     ...
;             PG8_LDA(At, 1, 1); PG8_STAGE(PG8_SB(1, 0), b3, voffB); PG8_STAGE(PG8_SB(1, 1), b3 + hsB, voffB); PG8_STAGE(PG8_SA(1, 0), a3, voffA);
;             PG8_WAIT_V(8); PG8_WAIT_L(0); PG8_BAR; PG8_MMA(1, 0, At, B0); PG8_MMA(1, 1, At, B1); PG8_BAR; PG8_SCHED;
;     ...
;         if constexpr (ALIGN_EPI) { if (wr == 0) PG8_BAR; }
	s_setprio 0
	s_add_i32 s26, s61, s38
	v_lshl_add_u64 v[214:215], v[214:215], 0, s[12:13]
	s_mov_b32 m0, s26
	ds_read_b128 v[182:185], v149 offset:49152
	ds_read_b128 v[186:189], v149 offset:50176
	ds_read_b128 v[190:193], v149 offset:51200
	ds_read_b128 v[194:197], v149 offset:52224
	ds_read_b128 v[198:201], v149 offset:53248
	ds_read_b128 v[202:205], v149 offset:54272
	ds_read_b128 v[206:209], v149 offset:55296
	ds_read_b128 v[210:213], v149 offset:56320
	global_load_lds_dwordx4 v[214:215], off
	s_add_i32 m0, s26, 0x2000
	s_add_u32 s26, s30, 0x30080
	v_lshl_add_u64 v[214:215], v[216:217], 0, s[12:13]
	s_addc_u32 s27, s31, 0
	s_add_i32 s30, s62, s38
	global_load_lds_dwordx4 v[214:215], off
	v_lshl_add_u64 v[214:215], s[26:27], 0, v[132:133]
	s_mov_b32 m0, s30
	s_nop 0
	global_load_lds_dwordx4 v[214:215], off
	v_lshl_add_u64 v[214:215], s[26:27], 0, v[128:129]
	s_add_i32 m0, s30, 0x2000
	s_nop 0
	global_load_lds_dwordx4 v[214:215], off
	v_lshl_add_u64 v[214:215], v[218:219], 0, s[12:13]
	s_mov_b32 m0, s46
	s_nop 0
	global_load_lds_dwordx4 v[214:215], off
	v_lshl_add_u64 v[214:215], v[220:221], 0, s[12:13]
	s_mov_b32 m0, s47
	s_nop 0
	global_load_lds_dwordx4 v[214:215], off
	s_waitcnt vmcnt(8)
	s_waitcnt lgkmcnt(0)
	s_setprio 1
	s_barrier
	v_mfma_f32_16x16x32_bf16 v[60:63], v[150:153], v[182:185], v[60:63]
	v_mfma_f32_16x16x32_bf16 v[56:59], v[158:161], v[182:185], v[56:59]
	v_mfma_f32_16x16x32_bf16 v[52:55], v[150:153], v[190:193], v[52:55]
	v_mfma_f32_16x16x32_bf16 v[48:51], v[158:161], v[190:193], v[48:51]
	v_mfma_f32_16x16x32_bf16 v[40:43], v[150:153], v[198:201], v[40:43]
	v_mfma_f32_16x16x32_bf16 v[32:35], v[158:161], v[198:201], v[32:35]
	v_mfma_f32_16x16x32_bf16 v[24:27], v[150:153], v[206:209], v[24:27]
	v_mfma_f32_16x16x32_bf16 v[16:19], v[158:161], v[206:209], v[16:19]
	v_mfma_f32_16x16x32_bf16 v[60:63], v[154:157], v[186:189], v[60:63]
	v_mfma_f32_16x16x32_bf16 v[56:59], v[162:165], v[186:189], v[56:59]
	v_mfma_f32_16x16x32_bf16 v[52:55], v[154:157], v[194:197], v[52:55]
	v_mfma_f32_16x16x32_bf16 v[48:51], v[162:165], v[194:197], v[48:51]
	v_mfma_f32_16x16x32_bf16 v[40:43], v[154:157], v[202:205], v[40:43]
	v_mfma_f32_16x16x32_bf16 v[32:35], v[162:165], v[202:205], v[32:35]
	v_mfma_f32_16x16x32_bf16 v[24:27], v[154:157], v[210:213], v[24:27]
	v_mfma_f32_16x16x32_bf16 v[16:19], v[162:165], v[210:213], v[16:19]
	s_setprio 0
	s_setprio 1
	v_mfma_f32_16x16x32_bf16 v[44:47], v[166:169], v[182:185], v[44:47]
	v_mfma_f32_16x16x32_bf16 v[36:39], v[174:177], v[182:185], v[36:39]
	v_mfma_f32_16x16x32_bf16 v[28:31], v[166:169], v[190:193], v[28:31]
	v_mfma_f32_16x16x32_bf16 v[20:23], v[174:177], v[190:193], v[20:23]
	v_mfma_f32_16x16x32_bf16 v[12:15], v[166:169], v[198:201], v[12:15]
	v_mfma_f32_16x16x32_bf16 v[8:11], v[174:177], v[198:201], v[8:11]
	v_mfma_f32_16x16x32_bf16 v[4:7], v[166:169], v[206:209], v[4:7]
	v_mfma_f32_16x16x32_bf16 v[0:3], v[174:177], v[206:209], v[0:3]
	v_mfma_f32_16x16x32_bf16 v[44:47], v[170:173], v[186:189], v[44:47]
	v_mfma_f32_16x16x32_bf16 v[36:39], v[178:181], v[186:189], v[36:39]
	v_mfma_f32_16x16x32_bf16 v[28:31], v[170:173], v[194:197], v[28:31]
	v_mfma_f32_16x16x32_bf16 v[20:23], v[178:181], v[194:197], v[20:23]
	v_mfma_f32_16x16x32_bf16 v[12:15], v[170:173], v[202:205], v[12:15]
	v_mfma_f32_16x16x32_bf16 v[8:11], v[178:181], v[202:205], v[8:11]
	v_mfma_f32_16x16x32_bf16 v[4:7], v[170:173], v[210:213], v[4:7]
	v_mfma_f32_16x16x32_bf16 v[0:3], v[178:181], v[210:213], v[0:3]
	s_barrier
	s_setprio 0
	s_add_i32 s60, s60, 2
	s_add_u32 s58, s58, 0x100
	s_addc_u32 s59, s59, 0
	s_cmp_gt_u32 s60, 9
	s_mov_b64 s[26:27], s[28:29]
	s_cbranch_scc0 .LBB0_773
	s_and_b64 vcc, exec, s[14:15]
	s_cbranch_vccz .LBB0_776
	s_barrier

; #define PG8_STAGE(bufoff, gbase, voff) do { _Pragma("unroll") for (int _i = 0; _i < 2; ++_i) \
;         __builtin_amdgcn_global_load_lds((const unsigned*)((const char*)(gbase) + (voff)[_i]), (PG8_LAS unsigned*)(lds + (bufoff) + ldsw + _i * 8192), 16, 0, 0); } while (0)
; #define PG8_LDA(dst, b, h) do { _Pragma("unroll") for (int m = 0; m < 4; ++m) _Pragma("unroll") for (int k = 0; k < 2; ++k) dst[m][k] = *(const PG8_LAS bf16x8*)(lds + PG8_SA(b, h) + aoff + m * 2048 + k * 1024); } while (0)
; #define PG8_LDB(dst, b, h) do { _Pragma("unroll") for (int n = 0; n < 2; ++n) _Pragma("unroll") for (int k = 0; k < 2; ++k) dst[n][k] = *(const PG8_LAS bf16x8*)(lds + PG8_SB(b, h) + boff + n * 2048 + k * 1024); } while (0)
; #define PG8_MMA(ai, bj, At, Bt) do { __builtin_amdgcn_s_setprio(1); _Pragma("unroll") for (int m = 0; m < 4; ++m) _Pragma("unroll") for (int n = 0; n < 2; ++n) _Pragma("unroll") for (int k = 0; k < 2; ++k) \
;         acc[ai][bj][m][n] = __builtin_amdgcn_mfma_f32_16x16x32_bf16(Bt[n][k], At[m][k], acc[ai][bj][m][n], 0, 0, 0); __builtin_amdgcn_s_setprio(0); } while (0)
; #define PG8_WAIT_V(n) asm volatile("s_waitcnt vmcnt(" #n ")" ::: "memory")
; #define PG8_WAIT_L(n) asm volatile("s_waitcnt lgkmcnt(" #n ")" ::: "memory")
; template <class Epi, class Sched, bool ALIGN_EPI = false, bool SP2 = false>
; __device__ __forceinline__ void gemm_phase(PG8_LAS unsigned char* lds, const Gemm g, const Sched& S, const Epi& E, const int wid) {
;     ...
;         for (int t = 0; t < nt; t += 2) {
;             const bool last = (t == nt - 2);
;             const char* a1 = cA + (size_t)(t + 1) * kstep;
;             const char* a2 = last ? nA : cA + (size_t)(t + 2) * kstep; const char* b2 = last ? nB : cB + (size_t)(t + 2) * kstep;
;             const char* a3 = a2 + kstep; const char* b3 = b2 + kstep;
;             if constexpr (SP2) {
;             PG8_LDB(B0, 0, 0); PG8_LDB(B1, 0, 1); PG8_SCHED; PG8_LDA(At, 0, 0); PG8_STAGE(PG8_SA(1, 1), a1 + hsA, voffA);
;             PG8_WAIT_V(8); PG8_WAIT_L(0); PG8_BAR; PG8_MMA(0, 0, At, B0); PG8_MMA(0, 1, At, B1); PG8_BAR; PG8_SCHED;
;             PG8_LDA(At, 0, 1); PG8_STAGE(PG8_SB(0, 0), b2, voffB); PG8_STAGE(PG8_SB(0, 1), b2 + hsB, voffB); PG8_STAGE(PG8_SA(0, 0), a2, voffA);
;             PG8_WAIT_V(8); PG8_WAIT_L(0); PG8_BAR; PG8_MMA(1, 0, At, B0); PG8_MMA(1, 1, At, B1); PG8_BAR; PG8_SCHED;
.LBB0_1177:
	ds_read_b128 v[128:131], v205
	ds_read_b128 v[132:135], v205 offset:1024
	ds_read_b128 v[136:139], v205 offset:2048
	ds_read_b128 v[140:143], v205 offset:3072
	ds_read_b128 v[144:147], v206
	ds_read_b128 v[148:151], v206 offset:1024
	ds_read_b128 v[152:155], v206 offset:2048
	ds_read_b128 v[156:159], v206 offset:3072
	s_add_u32 s40, s38, 0xfffc0080
	s_addc_u32 s41, s39, -1
	s_cmp_eq_u32 s64, 12
	s_cselect_b32 s43, s29, s41
	s_cselect_b32 s42, s60, s40
	s_cselect_b32 s41, s27, s63
	s_cselect_b32 s40, s61, s62
	v_lshl_add_u64 v[200:201], s[38:39], 0, v[170:171]
	s_add_i32 m0, s37, 0xc000
	ds_read_b128 v[176:179], v207
	ds_read_b128 v[180:183], v207 offset:1024
	ds_read_b128 v[184:187], v207 offset:2048
	ds_read_b128 v[188:191], v207 offset:3072
	ds_read_b128 v[192:195], v207 offset:4096
	ds_read_b128 v[196:199], v207 offset:5120
	ds_read_b128 v[208:211], v207 offset:6144
	ds_read_b128 v[212:215], v207 offset:7168
	global_load_lds_dwordx4 v[200:201], off
	v_lshl_add_u64 v[200:201], s[38:39], 0, v[168:169]
	s_add_i32 m0, s37, 0xe000
	s_nop 0
	global_load_lds_dwordx4 v[200:201], off
	s_waitcnt vmcnt(8)
	s_waitcnt lgkmcnt(0)
	s_setprio 1
	s_barrier
	v_mfma_f32_16x16x32_bf16 v[124:127], v[128:131], v[176:179], v[124:127]
	v_mfma_f32_16x16x32_bf16 v[120:123], v[136:139], v[176:179], v[120:123]
	v_mfma_f32_16x16x32_bf16 v[116:119], v[128:131], v[184:187], v[116:119]
	v_mfma_f32_16x16x32_bf16 v[112:115], v[136:139], v[184:187], v[112:115]
	v_mfma_f32_16x16x32_bf16 v[108:111], v[128:131], v[192:195], v[108:111]
	v_mfma_f32_16x16x32_bf16 v[104:107], v[136:139], v[192:195], v[104:107]
	v_mfma_f32_16x16x32_bf16 v[100:103], v[128:131], v[208:211], v[100:103]
	v_mfma_f32_16x16x32_bf16 v[96:99], v[136:139], v[208:211], v[96:99]
	v_mfma_f32_16x16x32_bf16 v[124:127], v[132:135], v[180:183], v[124:127]
	v_mfma_f32_16x16x32_bf16 v[120:123], v[140:143], v[180:183], v[120:123]
	v_mfma_f32_16x16x32_bf16 v[116:119], v[132:135], v[188:191], v[116:119]
	v_mfma_f32_16x16x32_bf16 v[112:115], v[140:143], v[188:191], v[112:115]
	v_mfma_f32_16x16x32_bf16 v[108:111], v[132:135], v[196:199], v[108:111]
	v_mfma_f32_16x16x32_bf16 v[104:107], v[140:143], v[196:199], v[104:107]
	v_mfma_f32_16x16x32_bf16 v[100:103], v[132:135], v[212:215], v[100:103]
	v_mfma_f32_16x16x32_bf16 v[96:99], v[140:143], v[212:215], v[96:99]
	s_setprio 0
	s_setprio 1
	v_mfma_f32_16x16x32_bf16 v[60:63], v[144:147], v[176:179], v[60:63]
	v_mfma_f32_16x16x32_bf16 v[56:59], v[152:155], v[176:179], v[56:59]
	v_mfma_f32_16x16x32_bf16 v[52:55], v[144:147], v[184:187], v[52:55]
	v_mfma_f32_16x16x32_bf16 v[48:51], v[152:155], v[184:187], v[48:51]
	v_mfma_f32_16x16x32_bf16 v[44:47], v[144:147], v[192:195], v[44:47]
	v_mfma_f32_16x16x32_bf16 v[40:43], v[152:155], v[192:195], v[40:43]
	v_mfma_f32_16x16x32_bf16 v[36:39], v[144:147], v[208:211], v[36:39]
	v_mfma_f32_16x16x32_bf16 v[32:35], v[152:155], v[208:211], v[32:35]
	v_mfma_f32_16x16x32_bf16 v[60:63], v[148:151], v[180:183], v[60:63]
	v_mfma_f32_16x16x32_bf16 v[56:59], v[156:159], v[180:183], v[56:59]
	v_mfma_f32_16x16x32_bf16 v[52:55], v[148:151], v[188:191], v[52:55]
	v_mfma_f32_16x16x32_bf16 v[48:51], v[156:159], v[188:191], v[48:51]
	v_mfma_f32_16x16x32_bf16 v[44:47], v[148:151], v[196:199], v[44:47]
	v_mfma_f32_16x16x32_bf16 v[40:43], v[156:159], v[196:199], v[40:43]
	v_mfma_f32_16x16x32_bf16 v[36:39], v[148:151], v[212:215], v[36:39]
	v_mfma_f32_16x16x32_bf16 v[32:35], v[156:159], v[212:215], v[32:35]
	s_barrier
	s_setprio 0
	s_add_i32 s65, s54, s45
	v_lshl_add_u64 v[200:201], s[40:41], 0, v[162:163]
	s_mov_b32 m0, s65
	ds_read_b128 v[176:179], v207 offset:16384
	ds_read_b128 v[180:183], v207 offset:17408
	ds_read_b128 v[184:187], v207 offset:18432
	ds_read_b128 v[188:191], v207 offset:19456
	ds_read_b128 v[192:195], v207 offset:20480
	ds_read_b128 v[196:199], v207 offset:21504
	ds_read_b128 v[208:211], v207 offset:22528
	ds_read_b128 v[212:215], v207 offset:23552
	global_load_lds_dwordx4 v[200:201], off
	s_add_i32 m0, s65, 0x2000
	s_add_u32 s66, s40, 0x40000
	v_lshl_add_u64 v[216:217], s[40:41], 0, v[166:167]
	s_addc_u32 s67, s41, 0
	s_add_i32 s65, s55, s45
	global_load_lds_dwordx4 v[216:217], off
	v_lshl_add_u64 v[218:219], s[66:67], 0, v[162:163]
	s_mov_b32 m0, s65
	v_lshl_add_u64 v[220:221], s[42:43], 0, v[164:165]
	global_load_lds_dwordx4 v[218:219], off
	v_lshl_add_u64 v[218:219], s[66:67], 0, v[166:167]
	s_add_i32 m0, s65, 0x2000
	s_nop 0
	global_load_lds_dwordx4 v[218:219], off
	v_lshl_add_u64 v[218:219], s[42:43], 0, v[160:161]
	s_mov_b32 m0, s37
	s_nop 0
	global_load_lds_dwordx4 v[218:219], off
	s_mov_b32 m0, s46
	s_nop 0
	global_load_lds_dwordx4 v[220:221], off
	s_waitcnt vmcnt(8)
	s_waitcnt lgkmcnt(0)
	s_setprio 1
	s_barrier
; #define PG8_STAGE(bufoff, gbase, voff) do { _Pragma("unroll") for (int _i = 0; _i < 2; ++_i) \
;         __builtin_amdgcn_global_load_lds((const unsigned*)((const char*)(gbase) + (voff)[_i]), (PG8_LAS unsigned*)(lds + (bufoff) + ldsw + _i * 8192), 16, 0, 0); } while (0)
; #define PG8_LDA(dst, b, h) do { _Pragma("unroll") for (int m = 0; m < 4; ++m) _Pragma("unroll") for (int k = 0; k < 2; ++k) dst[m][k] = *(const PG8_LAS bf16x8*)(lds + PG8_SA(b, h) + aoff + m * 2048 + k * 1024); } while (0)
; #define PG8_LDB(dst, b, h) do { _Pragma("unroll") for (int n = 0; n < 2; ++n) _Pragma("unroll") for (int k = 0; k < 2; ++k) dst[n][k] = *(const PG8_LAS bf16x8*)(lds + PG8_SB(b, h) + boff + n * 2048 + k * 1024); } while (0)
; #define PG8_MMA(ai, bj, At, Bt) do { __builtin_amdgcn_s_setprio(1); _Pragma("unroll") for (int m = 0; m < 4; ++m) _Pragma("unroll") for (int n = 0; n < 2; ++n) _Pragma("unroll") for (int k = 0; k < 2; ++k) \
;         acc[ai][bj][m][n] = __builtin_amdgcn_mfma_f32_16x16x32_bf16(Bt[n][k], At[m][k], acc[ai][bj][m][n], 0, 0, 0); __builtin_amdgcn_s_setprio(0); } while (0)
; #define PG8_WAIT_V(n) asm volatile("s_waitcnt vmcnt(" #n ")" ::: "memory")
; #define PG8_WAIT_L(n) asm volatile("s_waitcnt lgkmcnt(" #n ")" ::: "memory")
; #define PG8_BAR __builtin_amdgcn_s_barrier()
; #define PG8_SCHED __builtin_amdgcn_sched_barrier(0)
; template <class Epi, class Sched, bool ALIGN_EPI = false, bool SP2 = false>
; __device__ __forceinline__ void gemm_phase(PG8_LAS unsigned char* lds, const Gemm g, const Sched& S, const Epi& E, const int wid) {
;     ...
;             PG8_WAIT_V(8); PG8_WAIT_L(0); PG8_BAR; PG8_MMA(1, 0, At, B0); PG8_MMA(1, 1, At, B1); PG8_BAR; PG8_SCHED;
;             PG8_LDB(B0, 1, 0); PG8_LDB(B1, 1, 1); PG8_SCHED; PG8_LDA(At, 1, 0); PG8_STAGE(PG8_SA(0, 1), a2 + hsA, voffA);
;             PG8_WAIT_V(8); PG8_WAIT_L(0); PG8_BAR; PG8_MMA(0, 0, At, B0); PG8_MMA(0, 1, At, B1); PG8_BAR; PG8_SCHED;
	v_mfma_f32_16x16x32_bf16 v[92:95], v[128:131], v[176:179], v[92:95]
	v_mfma_f32_16x16x32_bf16 v[88:91], v[136:139], v[176:179], v[88:91]
	v_mfma_f32_16x16x32_bf16 v[84:87], v[128:131], v[184:187], v[84:87]
	v_mfma_f32_16x16x32_bf16 v[80:83], v[136:139], v[184:187], v[80:83]
	v_mfma_f32_16x16x32_bf16 v[76:79], v[128:131], v[192:195], v[76:79]
	v_mfma_f32_16x16x32_bf16 v[72:75], v[136:139], v[192:195], v[72:75]
	v_mfma_f32_16x16x32_bf16 v[68:71], v[128:131], v[208:211], v[68:71]
	v_mfma_f32_16x16x32_bf16 v[64:67], v[136:139], v[208:211], v[64:67]
	v_mfma_f32_16x16x32_bf16 v[92:95], v[132:135], v[180:183], v[92:95]
	v_mfma_f32_16x16x32_bf16 v[88:91], v[140:143], v[180:183], v[88:91]
	v_mfma_f32_16x16x32_bf16 v[84:87], v[132:135], v[188:191], v[84:87]
	v_mfma_f32_16x16x32_bf16 v[80:83], v[140:143], v[188:191], v[80:83]
	v_mfma_f32_16x16x32_bf16 v[76:79], v[132:135], v[196:199], v[76:79]
	v_mfma_f32_16x16x32_bf16 v[72:75], v[140:143], v[196:199], v[72:75]
	v_mfma_f32_16x16x32_bf16 v[68:71], v[132:135], v[212:215], v[68:71]
	v_mfma_f32_16x16x32_bf16 v[64:67], v[140:143], v[212:215], v[64:67]
	s_setprio 0
	s_setprio 1
	v_mfma_f32_16x16x32_bf16 v[28:31], v[144:147], v[176:179], v[28:31]
	v_mfma_f32_16x16x32_bf16 v[24:27], v[152:155], v[176:179], v[24:27]
	v_mfma_f32_16x16x32_bf16 v[20:23], v[144:147], v[184:187], v[20:23]
	v_mfma_f32_16x16x32_bf16 v[16:19], v[152:155], v[184:187], v[16:19]
	v_mfma_f32_16x16x32_bf16 v[12:15], v[144:147], v[192:195], v[12:15]
	v_mfma_f32_16x16x32_bf16 v[8:11], v[152:155], v[192:195], v[8:11]
	v_mfma_f32_16x16x32_bf16 v[4:7], v[144:147], v[208:211], v[4:7]
	v_mfma_f32_16x16x32_bf16 v[0:3], v[152:155], v[208:211], v[0:3]
	v_mfma_f32_16x16x32_bf16 v[28:31], v[148:151], v[180:183], v[28:31]
	v_mfma_f32_16x16x32_bf16 v[24:27], v[156:159], v[180:183], v[24:27]
	v_mfma_f32_16x16x32_bf16 v[20:23], v[148:151], v[188:191], v[20:23]
	v_mfma_f32_16x16x32_bf16 v[16:19], v[156:159], v[188:191], v[16:19]
	v_mfma_f32_16x16x32_bf16 v[12:15], v[148:151], v[196:199], v[12:15]
	v_mfma_f32_16x16x32_bf16 v[8:11], v[156:159], v[196:199], v[8:11]
	v_mfma_f32_16x16x32_bf16 v[4:7], v[148:151], v[212:215], v[4:7]
	v_mfma_f32_16x16x32_bf16 v[0:3], v[156:159], v[212:215], v[0:3]
	s_barrier
	s_setprio 0
	s_add_i32 s65, 0, 0x18000
	s_add_i32 s66, 0, 0x1c000
	v_add_u32_e32 v140, s65, v203
	v_add_u32_e32 v156, s66, v203
	ds_read_b128 v[128:131], v140
	ds_read_b128 v[132:135], v140 offset:1024
	ds_read_b128 v[136:139], v140 offset:2048
	ds_read_b128 v[140:143], v140 offset:3072
	ds_read_b128 v[144:147], v156
	ds_read_b128 v[148:151], v156 offset:1024
	ds_read_b128 v[152:155], v156 offset:2048
	ds_read_b128 v[156:159], v156 offset:3072
	s_add_u32 s42, s42, 0x40000
	s_addc_u32 s43, s43, 0
	s_mov_b32 m0, s47
	v_lshl_add_u64 v[222:223], s[42:43], 0, v[160:161]
	ds_read_b128 v[176:179], v207 offset:32768
	ds_read_b128 v[180:183], v207 offset:33792
	ds_read_b128 v[184:187], v207 offset:34816
	ds_read_b128 v[188:191], v207 offset:35840
	ds_read_b128 v[192:195], v207 offset:36864
	ds_read_b128 v[196:199], v207 offset:37888
	ds_read_b128 v[208:211], v207 offset:38912
	ds_read_b128 v[212:215], v207 offset:39936
	global_load_lds_dwordx4 v[222:223], off
	v_lshl_add_u64 v[222:223], s[42:43], 0, v[164:165]
	s_mov_b32 m0, s48
	s_nop 0
	global_load_lds_dwordx4 v[222:223], off
	s_waitcnt vmcnt(8)
	s_waitcnt lgkmcnt(0)
	s_setprio 1
	s_barrier
	v_mfma_f32_16x16x32_bf16 v[124:127], v[128:131], v[176:179], v[124:127]
	v_mfma_f32_16x16x32_bf16 v[120:123], v[136:139], v[176:179], v[120:123]
	v_mfma_f32_16x16x32_bf16 v[116:119], v[128:131], v[184:187], v[116:119]
	v_mfma_f32_16x16x32_bf16 v[112:115], v[136:139], v[184:187], v[112:115]
	v_mfma_f32_16x16x32_bf16 v[108:111], v[128:131], v[192:195], v[108:111]
	v_mfma_f32_16x16x32_bf16 v[104:107], v[136:139], v[192:195], v[104:107]
	v_mfma_f32_16x16x32_bf16 v[100:103], v[128:131], v[208:211], v[100:103]
	v_mfma_f32_16x16x32_bf16 v[96:99], v[136:139], v[208:211], v[96:99]
	v_mfma_f32_16x16x32_bf16 v[124:127], v[132:135], v[180:183], v[124:127]
	v_mfma_f32_16x16x32_bf16 v[120:123], v[140:143], v[180:183], v[120:123]
	v_mfma_f32_16x16x32_bf16 v[116:119], v[132:135], v[188:191], v[116:119]
	v_mfma_f32_16x16x32_bf16 v[112:115], v[140:143], v[188:191], v[112:115]
	v_mfma_f32_16x16x32_bf16 v[108:111], v[132:135], v[196:199], v[108:111]
	v_mfma_f32_16x16x32_bf16 v[104:107], v[140:143], v[196:199], v[104:107]
	v_mfma_f32_16x16x32_bf16 v[100:103], v[132:135], v[212:215], v[100:103]
	v_mfma_f32_16x16x32_bf16 v[96:99], v[140:143], v[212:215], v[96:99]
	s_setprio 0
	s_setprio 1
	v_mfma_f32_16x16x32_bf16 v[60:63], v[144:147], v[176:179], v[60:63]
	v_mfma_f32_16x16x32_bf16 v[56:59], v[152:155], v[176:179], v[56:59]
	v_mfma_f32_16x16x32_bf16 v[52:55], v[144:147], v[184:187], v[52:55]
	v_mfma_f32_16x16x32_bf16 v[48:51], v[152:155], v[184:187], v[48:51]
	v_mfma_f32_16x16x32_bf16 v[44:47], v[144:147], v[192:195], v[44:47]
	v_mfma_f32_16x16x32_bf16 v[40:43], v[152:155], v[192:195], v[40:43]
	v_mfma_f32_16x16x32_bf16 v[36:39], v[144:147], v[208:211], v[36:39]
	v_mfma_f32_16x16x32_bf16 v[32:35], v[152:155], v[208:211], v[32:35]
	v_mfma_f32_16x16x32_bf16 v[60:63], v[148:151], v[180:183], v[60:63]
	v_mfma_f32_16x16x32_bf16 v[56:59], v[156:159], v[180:183], v[56:59]
	v_mfma_f32_16x16x32_bf16 v[52:55], v[148:151], v[188:191], v[52:55]
	v_mfma_f32_16x16x32_bf16 v[48:51], v[156:159], v[188:191], v[48:51]
	v_mfma_f32_16x16x32_bf16 v[44:47], v[148:151], v[196:199], v[44:47]
	v_mfma_f32_16x16x32_bf16 v[40:43], v[156:159], v[196:199], v[40:43]
	v_mfma_f32_16x16x32_bf16 v[36:39], v[148:151], v[212:215], v[36:39]
	v_mfma_f32_16x16x32_bf16 v[32:35], v[156:159], v[212:215], v[32:35]
	s_barrier
; #define PG8_STAGE(bufoff, gbase, voff) do { _Pragma("unroll") for (int _i = 0; _i < 2; ++_i) \
;         __builtin_amdgcn_global_load_lds((const unsigned*)((const char*)(gbase) + (voff)[_i]), (PG8_LAS unsigned*)(lds + (bufoff) + ldsw + _i * 8192), 16, 0, 0); } while (0)
; #define PG8_LDA(dst, b, h) do { _Pragma("unroll") for (int m = 0; m < 4; ++m) _Pragma("unroll") for (int k = 0; k < 2; ++k) dst[m][k] = *(const PG8_LAS bf16x8*)(lds + PG8_SA(b, h) + aoff + m * 2048 + k * 1024); } while (0)
; #define PG8_MMA(ai, bj, At, Bt) do { __builtin_amdgcn_s_setprio(1); _Pragma("unroll") for (int m = 0; m < 4; ++m) _Pragma("unroll") for (int n = 0; n < 2; ++n) _Pragma("unroll") for (int k = 0; k < 2; ++k) \
;         acc[ai][bj][m][n] = __builtin_amdgcn_mfma_f32_16x16x32_bf16(Bt[n][k], At[m][k], acc[ai][bj][m][n], 0, 0, 0); __builtin_amdgcn_s_setprio(0); } while (0)
; #define PG8_WAIT_V(n) asm volatile("s_waitcnt vmcnt(" #n ")" ::: "memory")
; #define PG8_WAIT_L(n) asm volatile("s_waitcnt lgkmcnt(" #n ")" ::: "memory")
; #define PG8_BAR __builtin_amdgcn_s_barrier()
; #define PG8_SCHED __builtin_amdgcn_sched_barrier(0)
; template <class Epi, class Sched, bool ALIGN_EPI = false, bool SP2 = false>
; __device__ __forceinline__ void gemm_phase(PG8_LAS unsigned char* lds, const Gemm g, const Sched& S, const Epi& E, const int wid) {
;     ...
;             PG8_LDA(At, 1, 1); PG8_STAGE(PG8_SB(1, 0), b3, voffB); PG8_STAGE(PG8_SB(1, 1), b3 + hsB, voffB); PG8_STAGE(PG8_SA(1, 0), a3, voffA);
;             PG8_WAIT_V(8); PG8_WAIT_L(0); PG8_BAR; PG8_MMA(1, 0, At, B0); PG8_MMA(1, 1, At, B1); PG8_BAR; PG8_SCHED;
	s_setprio 0
	s_add_i32 s42, s65, s45
	v_lshl_add_u64 v[200:201], v[200:201], 0, s[16:17]
	s_mov_b32 m0, s42
	ds_read_b128 v[176:179], v207 offset:49152
	ds_read_b128 v[180:183], v207 offset:50176
	ds_read_b128 v[184:187], v207 offset:51200
	ds_read_b128 v[188:191], v207 offset:52224
	ds_read_b128 v[192:195], v207 offset:53248
	ds_read_b128 v[196:199], v207 offset:54272
	ds_read_b128 v[208:211], v207 offset:55296
	ds_read_b128 v[212:215], v207 offset:56320
	global_load_lds_dwordx4 v[200:201], off
	s_add_i32 m0, s42, 0x2000
	s_add_u32 s40, s40, 0x40080
	v_lshl_add_u64 v[200:201], v[216:217], 0, s[16:17]
	s_addc_u32 s41, s41, 0
	s_add_i32 s42, s66, s45
	global_load_lds_dwordx4 v[200:201], off
	v_lshl_add_u64 v[200:201], s[40:41], 0, v[162:163]
	s_mov_b32 m0, s42
	s_nop 0
	global_load_lds_dwordx4 v[200:201], off
	v_lshl_add_u64 v[200:201], s[40:41], 0, v[166:167]
	s_add_i32 m0, s42, 0x2000
	s_nop 0
	global_load_lds_dwordx4 v[200:201], off
	v_lshl_add_u64 v[200:201], v[218:219], 0, s[16:17]
	s_mov_b32 m0, s50
	s_nop 0
	global_load_lds_dwordx4 v[200:201], off
	v_lshl_add_u64 v[200:201], v[220:221], 0, s[16:17]
	s_mov_b32 m0, s51
	s_nop 0
	global_load_lds_dwordx4 v[200:201], off
	s_waitcnt vmcnt(8)
	s_waitcnt lgkmcnt(0)
	s_setprio 1
	s_barrier
	v_mfma_f32_16x16x32_bf16 v[92:95], v[128:131], v[176:179], v[92:95]
	v_mfma_f32_16x16x32_bf16 v[88:91], v[136:139], v[176:179], v[88:91]
	v_mfma_f32_16x16x32_bf16 v[84:87], v[128:131], v[184:187], v[84:87]
	v_mfma_f32_16x16x32_bf16 v[80:83], v[136:139], v[184:187], v[80:83]
	v_mfma_f32_16x16x32_bf16 v[76:79], v[128:131], v[192:195], v[76:79]
	v_mfma_f32_16x16x32_bf16 v[72:75], v[136:139], v[192:195], v[72:75]
	v_mfma_f32_16x16x32_bf16 v[68:71], v[128:131], v[208:211], v[68:71]
	v_mfma_f32_16x16x32_bf16 v[64:67], v[136:139], v[208:211], v[64:67]
	v_mfma_f32_16x16x32_bf16 v[92:95], v[132:135], v[180:183], v[92:95]
	v_mfma_f32_16x16x32_bf16 v[88:91], v[140:143], v[180:183], v[88:91]
	v_mfma_f32_16x16x32_bf16 v[84:87], v[132:135], v[188:191], v[84:87]
	v_mfma_f32_16x16x32_bf16 v[80:83], v[140:143], v[188:191], v[80:83]
	v_mfma_f32_16x16x32_bf16 v[76:79], v[132:135], v[196:199], v[76:79]
	v_mfma_f32_16x16x32_bf16 v[72:75], v[140:143], v[196:199], v[72:75]
	v_mfma_f32_16x16x32_bf16 v[68:71], v[132:135], v[212:215], v[68:71]
	v_mfma_f32_16x16x32_bf16 v[64:67], v[140:143], v[212:215], v[64:67]
	s_setprio 0
	s_setprio 1
	v_mfma_f32_16x16x32_bf16 v[28:31], v[144:147], v[176:179], v[28:31]
	v_mfma_f32_16x16x32_bf16 v[24:27], v[152:155], v[176:179], v[24:27]
	v_mfma_f32_16x16x32_bf16 v[20:23], v[144:147], v[184:187], v[20:23]
	v_mfma_f32_16x16x32_bf16 v[16:19], v[152:155], v[184:187], v[16:19]
	v_mfma_f32_16x16x32_bf16 v[12:15], v[144:147], v[192:195], v[12:15]
	v_mfma_f32_16x16x32_bf16 v[8:11], v[152:155], v[192:195], v[8:11]
	v_mfma_f32_16x16x32_bf16 v[4:7], v[144:147], v[208:211], v[4:7]
	v_mfma_f32_16x16x32_bf16 v[0:3], v[152:155], v[208:211], v[0:3]
	v_mfma_f32_16x16x32_bf16 v[28:31], v[148:151], v[180:183], v[28:31]
	v_mfma_f32_16x16x32_bf16 v[24:27], v[156:159], v[180:183], v[24:27]
	v_mfma_f32_16x16x32_bf16 v[20:23], v[148:151], v[188:191], v[20:23]
	v_mfma_f32_16x16x32_bf16 v[16:19], v[156:159], v[188:191], v[16:19]
	v_mfma_f32_16x16x32_bf16 v[12:15], v[148:151], v[196:199], v[12:15]
	v_mfma_f32_16x16x32_bf16 v[8:11], v[156:159], v[196:199], v[8:11]
	v_mfma_f32_16x16x32_bf16 v[4:7], v[148:151], v[212:215], v[4:7]
	v_mfma_f32_16x16x32_bf16 v[0:3], v[156:159], v[212:215], v[0:3]
	s_barrier
	s_setprio 0
	s_add_i32 s64, s64, 2
	s_add_u32 s62, s62, 0x100
	s_addc_u32 s63, s63, 0
	s_add_u32 s38, s38, 0x100
	s_addc_u32 s39, s39, 0
	s_cmp_gt_u32 s64, 13
	s_cbranch_scc0 .LBB0_1177
	s_and_b64 vcc, exec, s[18:19]
	s_cbranch_vccz .LBB0_1180
	s_barrier

; #define PG8_STAGE(bufoff, gbase, voff) do { _Pragma("unroll") for (int _i = 0; _i < 2; ++_i) \
;         __builtin_amdgcn_global_load_lds((const unsigned*)((const char*)(gbase) + (voff)[_i]), (PG8_LAS unsigned*)(lds + (bufoff) + ldsw + _i * 8192), 16, 0, 0); } while (0)
; #define PG8_LDA(dst, b, h) do { _Pragma("unroll") for (int m = 0; m < 4; ++m) _Pragma("unroll") for (int k = 0; k < 2; ++k) dst[m][k] = *(const PG8_LAS bf16x8*)(lds + PG8_SA(b, h) + aoff + m * 2048 + k * 1024); } while (0)
; #define PG8_LDB(dst, b, h) do { _Pragma("unroll") for (int n = 0; n < 2; ++n) _Pragma("unroll") for (int k = 0; k < 2; ++k) dst[n][k] = *(const PG8_LAS bf16x8*)(lds + PG8_SB(b, h) + boff + n * 2048 + k * 1024); } while (0)
; #define PG8_MMA(ai, bj, At, Bt) do { __builtin_amdgcn_s_setprio(1); _Pragma("unroll") for (int m = 0; m < 4; ++m) _Pragma("unroll") for (int n = 0; n < 2; ++n) _Pragma("unroll") for (int k = 0; k < 2; ++k) \
;         acc[ai][bj][m][n] = __builtin_amdgcn_mfma_f32_16x16x32_bf16(Bt[n][k], At[m][k], acc[ai][bj][m][n], 0, 0, 0); __builtin_amdgcn_s_setprio(0); } while (0)
; #define PG8_WAIT_V(n) asm volatile("s_waitcnt vmcnt(" #n ")" ::: "memory")
; #define PG8_WAIT_L(n) asm volatile("s_waitcnt lgkmcnt(" #n ")" ::: "memory")
; template <class Epi, class Sched, bool ALIGN_EPI = false, bool SP2 = false>
; __device__ __forceinline__ void gemm_phase(PG8_LAS unsigned char* lds, const Gemm g, const Sched& S, const Epi& E, const int wid) {
;     ...
;         for (int t = 0; t < nt; t += 2) {
;             const bool last = (t == nt - 2);
;             const char* a1 = cA + (size_t)(t + 1) * kstep;
;             const char* a2 = last ? nA : cA + (size_t)(t + 2) * kstep; const char* b2 = last ? nB : cB + (size_t)(t + 2) * kstep;
;             const char* a3 = a2 + kstep; const char* b3 = b2 + kstep;
;             if constexpr (SP2) {
;             PG8_LDB(B0, 0, 0); PG8_LDB(B1, 0, 1); PG8_SCHED; PG8_LDA(At, 0, 0); PG8_STAGE(PG8_SA(1, 1), a1 + hsA, voffA);
;             PG8_WAIT_V(8); PG8_WAIT_L(0); PG8_BAR; PG8_MMA(0, 0, At, B0); PG8_MMA(0, 1, At, B1); PG8_BAR; PG8_SCHED;
;             PG8_LDA(At, 0, 1); PG8_STAGE(PG8_SB(0, 0), b2, voffB); PG8_STAGE(PG8_SB(0, 1), b2 + hsB, voffB); PG8_STAGE(PG8_SA(0, 0), a2, voffA);
;             PG8_WAIT_V(8); PG8_WAIT_L(0); PG8_BAR; PG8_MMA(1, 0, At, B0); PG8_MMA(1, 1, At, B1); PG8_BAR; PG8_SCHED;
.LBB0_1304:
	ds_read_b128 v[64:67], v199
	ds_read_b128 v[72:75], v199 offset:1024
	ds_read_b128 v[80:83], v199 offset:2048
	ds_read_b128 v[84:87], v199 offset:3072
	ds_read_b128 v[88:91], v200
	ds_read_b128 v[92:95], v200 offset:1024
	ds_read_b128 v[100:103], v200 offset:2048
	ds_read_b128 v[104:107], v200 offset:3072
	s_add_u32 s38, s36, 0xfff80080
	s_addc_u32 s39, s37, -1
	s_cmp_eq_u32 s61, 28
	s_cselect_b32 s41, s5, s39
	s_cselect_b32 s40, s27, s38
	s_cselect_b32 s39, s25, s60
	s_cselect_b32 s38, s58, s59
	v_lshl_add_u64 v[196:197], s[36:37], 0, v[182:183]
	s_add_i32 m0, s35, 0xc000
	ds_read_b128 v[160:163], v201
	ds_read_b128 v[164:167], v201 offset:1024
	ds_read_b128 v[168:171], v201 offset:2048
	ds_read_b128 v[172:175], v201 offset:3072
	ds_read_b128 v[188:191], v201 offset:4096
	ds_read_b128 v[192:195], v201 offset:5120
	ds_read_b128 v[204:207], v201 offset:6144
	ds_read_b128 v[208:211], v201 offset:7168
	global_load_lds_dwordx4 v[196:197], off
	v_lshl_add_u64 v[196:197], s[36:37], 0, v[180:181]
	s_add_i32 m0, s35, 0xe000
	s_nop 0
	global_load_lds_dwordx4 v[196:197], off
	s_waitcnt vmcnt(8)
	s_waitcnt lgkmcnt(0)
	s_setprio 1
	s_barrier
	v_mfma_f32_16x16x32_bf16 v[156:159], v[64:67], v[160:163], v[156:159]
	v_mfma_f32_16x16x32_bf16 v[152:155], v[80:83], v[160:163], v[152:155]
	v_mfma_f32_16x16x32_bf16 v[140:143], v[64:67], v[168:171], v[140:143]
	v_mfma_f32_16x16x32_bf16 v[136:139], v[80:83], v[168:171], v[136:139]
	v_mfma_f32_16x16x32_bf16 v[124:127], v[64:67], v[188:191], v[124:127]
	v_mfma_f32_16x16x32_bf16 v[120:123], v[80:83], v[188:191], v[120:123]
	v_mfma_f32_16x16x32_bf16 v[108:111], v[64:67], v[204:207], v[108:111]
	v_mfma_f32_16x16x32_bf16 v[96:99], v[80:83], v[204:207], v[96:99]
	v_mfma_f32_16x16x32_bf16 v[156:159], v[72:75], v[164:167], v[156:159]
	v_mfma_f32_16x16x32_bf16 v[152:155], v[84:87], v[164:167], v[152:155]
	v_mfma_f32_16x16x32_bf16 v[140:143], v[72:75], v[172:175], v[140:143]
	v_mfma_f32_16x16x32_bf16 v[136:139], v[84:87], v[172:175], v[136:139]
	v_mfma_f32_16x16x32_bf16 v[124:127], v[72:75], v[192:195], v[124:127]
	v_mfma_f32_16x16x32_bf16 v[120:123], v[84:87], v[192:195], v[120:123]
	v_mfma_f32_16x16x32_bf16 v[108:111], v[72:75], v[208:211], v[108:111]
	v_mfma_f32_16x16x32_bf16 v[96:99], v[84:87], v[208:211], v[96:99]
	s_setprio 0
	s_setprio 1
	v_mfma_f32_16x16x32_bf16 v[148:151], v[88:91], v[160:163], v[148:151]
	v_mfma_f32_16x16x32_bf16 v[144:147], v[100:103], v[160:163], v[144:147]
	v_mfma_f32_16x16x32_bf16 v[132:135], v[88:91], v[168:171], v[132:135]
	v_mfma_f32_16x16x32_bf16 v[128:131], v[100:103], v[168:171], v[128:131]
	v_mfma_f32_16x16x32_bf16 v[116:119], v[88:91], v[188:191], v[116:119]
	v_mfma_f32_16x16x32_bf16 v[112:115], v[100:103], v[188:191], v[112:115]
	v_mfma_f32_16x16x32_bf16 v[76:79], v[88:91], v[204:207], v[76:79]
	v_mfma_f32_16x16x32_bf16 v[68:71], v[100:103], v[204:207], v[68:71]
	v_mfma_f32_16x16x32_bf16 v[148:151], v[92:95], v[164:167], v[148:151]
	v_mfma_f32_16x16x32_bf16 v[144:147], v[104:107], v[164:167], v[144:147]
	v_mfma_f32_16x16x32_bf16 v[132:135], v[92:95], v[172:175], v[132:135]
	v_mfma_f32_16x16x32_bf16 v[128:131], v[104:107], v[172:175], v[128:131]
	v_mfma_f32_16x16x32_bf16 v[116:119], v[92:95], v[192:195], v[116:119]
	v_mfma_f32_16x16x32_bf16 v[112:115], v[104:107], v[192:195], v[112:115]
	v_mfma_f32_16x16x32_bf16 v[76:79], v[92:95], v[208:211], v[76:79]
	v_mfma_f32_16x16x32_bf16 v[68:71], v[104:107], v[208:211], v[68:71]
	s_barrier
	s_setprio 0
	s_add_i32 s62, s56, s44
	v_lshl_add_u64 v[196:197], s[38:39], 0, v[176:177]
	s_mov_b32 m0, s62
	ds_read_b128 v[160:163], v201 offset:16384
	ds_read_b128 v[164:167], v201 offset:17408
	ds_read_b128 v[168:171], v201 offset:18432
	ds_read_b128 v[172:175], v201 offset:19456
	ds_read_b128 v[188:191], v201 offset:20480
	ds_read_b128 v[192:195], v201 offset:21504
	ds_read_b128 v[204:207], v201 offset:22528
	ds_read_b128 v[208:211], v201 offset:23552
	global_load_lds_dwordx4 v[196:197], off
	s_add_i32 m0, s62, 0x2000
	s_add_u32 s62, s38, 0x80000
	v_lshl_add_u64 v[212:213], s[38:39], 0, v[178:179]
	s_addc_u32 s63, s39, 0
	s_add_i32 s64, s57, s44
	global_load_lds_dwordx4 v[212:213], off
	v_lshl_add_u64 v[214:215], s[62:63], 0, v[176:177]
	s_mov_b32 m0, s64
	v_lshl_add_u64 v[216:217], s[40:41], 0, v[178:179]
	global_load_lds_dwordx4 v[214:215], off
	v_lshl_add_u64 v[214:215], s[62:63], 0, v[178:179]
	s_add_i32 m0, s64, 0x2000
	s_nop 0
	global_load_lds_dwordx4 v[214:215], off
	v_lshl_add_u64 v[214:215], s[40:41], 0, v[176:177]
	s_mov_b32 m0, s35
	s_nop 0
	global_load_lds_dwordx4 v[214:215], off
	s_mov_b32 m0, s45
	s_nop 0
	global_load_lds_dwordx4 v[216:217], off
	s_waitcnt vmcnt(8)
	s_waitcnt lgkmcnt(0)
	s_setprio 1
	s_barrier
; #define PG8_STAGE(bufoff, gbase, voff) do { _Pragma("unroll") for (int _i = 0; _i < 2; ++_i) \
;         __builtin_amdgcn_global_load_lds((const unsigned*)((const char*)(gbase) + (voff)[_i]), (PG8_LAS unsigned*)(lds + (bufoff) + ldsw + _i * 8192), 16, 0, 0); } while (0)
; #define PG8_LDA(dst, b, h) do { _Pragma("unroll") for (int m = 0; m < 4; ++m) _Pragma("unroll") for (int k = 0; k < 2; ++k) dst[m][k] = *(const PG8_LAS bf16x8*)(lds + PG8_SA(b, h) + aoff + m * 2048 + k * 1024); } while (0)
; #define PG8_LDB(dst, b, h) do { _Pragma("unroll") for (int n = 0; n < 2; ++n) _Pragma("unroll") for (int k = 0; k < 2; ++k) dst[n][k] = *(const PG8_LAS bf16x8*)(lds + PG8_SB(b, h) + boff + n * 2048 + k * 1024); } while (0)
; #define PG8_MMA(ai, bj, At, Bt) do { __builtin_amdgcn_s_setprio(1); _Pragma("unroll") for (int m = 0; m < 4; ++m) _Pragma("unroll") for (int n = 0; n < 2; ++n) _Pragma("unroll") for (int k = 0; k < 2; ++k) \
;         acc[ai][bj][m][n] = __builtin_amdgcn_mfma_f32_16x16x32_bf16(Bt[n][k], At[m][k], acc[ai][bj][m][n], 0, 0, 0); __builtin_amdgcn_s_setprio(0); } while (0)
; #define PG8_WAIT_V(n) asm volatile("s_waitcnt vmcnt(" #n ")" ::: "memory")
; #define PG8_WAIT_L(n) asm volatile("s_waitcnt lgkmcnt(" #n ")" ::: "memory")
; #define PG8_BAR __builtin_amdgcn_s_barrier()
; #define PG8_SCHED __builtin_amdgcn_sched_barrier(0)
; template <class Epi, class Sched, bool ALIGN_EPI = false, bool SP2 = false>
; __device__ __forceinline__ void gemm_phase(PG8_LAS unsigned char* lds, const Gemm g, const Sched& S, const Epi& E, const int wid) {
;     ...
;             PG8_WAIT_V(8); PG8_WAIT_L(0); PG8_BAR; PG8_MMA(1, 0, At, B0); PG8_MMA(1, 1, At, B1); PG8_BAR; PG8_SCHED;
;             PG8_LDB(B0, 1, 0); PG8_LDB(B1, 1, 1); PG8_SCHED; PG8_LDA(At, 1, 0); PG8_STAGE(PG8_SA(0, 1), a2 + hsA, voffA);
;             PG8_WAIT_V(8); PG8_WAIT_L(0); PG8_BAR; PG8_MMA(0, 0, At, B0); PG8_MMA(0, 1, At, B1); PG8_BAR; PG8_SCHED;
	v_mfma_f32_16x16x32_bf16 v[60:63], v[64:67], v[160:163], v[60:63]
	v_mfma_f32_16x16x32_bf16 v[56:59], v[80:83], v[160:163], v[56:59]
	v_mfma_f32_16x16x32_bf16 v[44:47], v[64:67], v[168:171], v[44:47]
	v_mfma_f32_16x16x32_bf16 v[40:43], v[80:83], v[168:171], v[40:43]
	v_mfma_f32_16x16x32_bf16 v[28:31], v[64:67], v[188:191], v[28:31]
	v_mfma_f32_16x16x32_bf16 v[24:27], v[80:83], v[188:191], v[24:27]
	v_mfma_f32_16x16x32_bf16 v[12:15], v[64:67], v[204:207], v[12:15]
	v_mfma_f32_16x16x32_bf16 v[8:11], v[80:83], v[204:207], v[8:11]
	v_mfma_f32_16x16x32_bf16 v[60:63], v[72:75], v[164:167], v[60:63]
	v_mfma_f32_16x16x32_bf16 v[56:59], v[84:87], v[164:167], v[56:59]
	v_mfma_f32_16x16x32_bf16 v[44:47], v[72:75], v[172:175], v[44:47]
	v_mfma_f32_16x16x32_bf16 v[40:43], v[84:87], v[172:175], v[40:43]
	v_mfma_f32_16x16x32_bf16 v[28:31], v[72:75], v[192:195], v[28:31]
	v_mfma_f32_16x16x32_bf16 v[24:27], v[84:87], v[192:195], v[24:27]
	v_mfma_f32_16x16x32_bf16 v[12:15], v[72:75], v[208:211], v[12:15]
	v_mfma_f32_16x16x32_bf16 v[8:11], v[84:87], v[208:211], v[8:11]
	s_setprio 0
	s_setprio 1
	v_mfma_f32_16x16x32_bf16 v[52:55], v[88:91], v[160:163], v[52:55]
	v_mfma_f32_16x16x32_bf16 v[48:51], v[100:103], v[160:163], v[48:51]
	v_mfma_f32_16x16x32_bf16 v[36:39], v[88:91], v[168:171], v[36:39]
	v_mfma_f32_16x16x32_bf16 v[32:35], v[100:103], v[168:171], v[32:35]
	v_mfma_f32_16x16x32_bf16 v[20:23], v[88:91], v[188:191], v[20:23]
	v_mfma_f32_16x16x32_bf16 v[16:19], v[100:103], v[188:191], v[16:19]
	v_mfma_f32_16x16x32_bf16 v[4:7], v[88:91], v[204:207], v[4:7]
	v_mfma_f32_16x16x32_bf16 v[0:3], v[100:103], v[204:207], v[0:3]
	v_mfma_f32_16x16x32_bf16 v[52:55], v[92:95], v[164:167], v[52:55]
	v_mfma_f32_16x16x32_bf16 v[48:51], v[104:107], v[164:167], v[48:51]
	v_mfma_f32_16x16x32_bf16 v[36:39], v[92:95], v[172:175], v[36:39]
	v_mfma_f32_16x16x32_bf16 v[32:35], v[104:107], v[172:175], v[32:35]
	v_mfma_f32_16x16x32_bf16 v[20:23], v[92:95], v[192:195], v[20:23]
	v_mfma_f32_16x16x32_bf16 v[16:19], v[104:107], v[192:195], v[16:19]
	v_mfma_f32_16x16x32_bf16 v[4:7], v[92:95], v[208:211], v[4:7]
	v_mfma_f32_16x16x32_bf16 v[0:3], v[104:107], v[208:211], v[0:3]
	s_barrier
	s_setprio 0
	s_add_i32 s62, 0, 0x18000
	s_add_i32 s63, 0, 0x1c000
	v_add_u32_e32 v84, s62, v198
	v_add_u32_e32 v104, s63, v198
	ds_read_b128 v[64:67], v84
	ds_read_b128 v[72:75], v84 offset:1024
	ds_read_b128 v[80:83], v84 offset:2048
	ds_read_b128 v[84:87], v84 offset:3072
	ds_read_b128 v[88:91], v104
	ds_read_b128 v[92:95], v104 offset:1024
	ds_read_b128 v[100:103], v104 offset:2048
	ds_read_b128 v[104:107], v104 offset:3072
	s_add_u32 s40, s40, 0x80000
	s_addc_u32 s41, s41, 0
	s_mov_b32 m0, s46
	v_lshl_add_u64 v[218:219], s[40:41], 0, v[176:177]
	ds_read_b128 v[160:163], v201 offset:32768
	ds_read_b128 v[164:167], v201 offset:33792
	ds_read_b128 v[168:171], v201 offset:34816
	ds_read_b128 v[172:175], v201 offset:35840
	ds_read_b128 v[188:191], v201 offset:36864
	ds_read_b128 v[192:195], v201 offset:37888
	ds_read_b128 v[204:207], v201 offset:38912
	ds_read_b128 v[208:211], v201 offset:39936
	global_load_lds_dwordx4 v[218:219], off
	v_lshl_add_u64 v[218:219], s[40:41], 0, v[178:179]
	s_mov_b32 m0, s47
	s_nop 0
	global_load_lds_dwordx4 v[218:219], off
	s_waitcnt vmcnt(8)
	s_waitcnt lgkmcnt(0)
	s_setprio 1
	s_barrier
	v_mfma_f32_16x16x32_bf16 v[156:159], v[64:67], v[160:163], v[156:159]
	v_mfma_f32_16x16x32_bf16 v[152:155], v[80:83], v[160:163], v[152:155]
	v_mfma_f32_16x16x32_bf16 v[140:143], v[64:67], v[168:171], v[140:143]
	v_mfma_f32_16x16x32_bf16 v[136:139], v[80:83], v[168:171], v[136:139]
	v_mfma_f32_16x16x32_bf16 v[124:127], v[64:67], v[188:191], v[124:127]
	v_mfma_f32_16x16x32_bf16 v[120:123], v[80:83], v[188:191], v[120:123]
	v_mfma_f32_16x16x32_bf16 v[108:111], v[64:67], v[204:207], v[108:111]
	v_mfma_f32_16x16x32_bf16 v[96:99], v[80:83], v[204:207], v[96:99]
	v_mfma_f32_16x16x32_bf16 v[156:159], v[72:75], v[164:167], v[156:159]
	v_mfma_f32_16x16x32_bf16 v[152:155], v[84:87], v[164:167], v[152:155]
	v_mfma_f32_16x16x32_bf16 v[140:143], v[72:75], v[172:175], v[140:143]
	v_mfma_f32_16x16x32_bf16 v[136:139], v[84:87], v[172:175], v[136:139]
	v_mfma_f32_16x16x32_bf16 v[124:127], v[72:75], v[192:195], v[124:127]
	v_mfma_f32_16x16x32_bf16 v[120:123], v[84:87], v[192:195], v[120:123]
	v_mfma_f32_16x16x32_bf16 v[108:111], v[72:75], v[208:211], v[108:111]
	v_mfma_f32_16x16x32_bf16 v[96:99], v[84:87], v[208:211], v[96:99]
	s_setprio 0
	s_setprio 1
	v_mfma_f32_16x16x32_bf16 v[148:151], v[88:91], v[160:163], v[148:151]
	v_mfma_f32_16x16x32_bf16 v[144:147], v[100:103], v[160:163], v[144:147]
	v_mfma_f32_16x16x32_bf16 v[132:135], v[88:91], v[168:171], v[132:135]
	v_mfma_f32_16x16x32_bf16 v[128:131], v[100:103], v[168:171], v[128:131]
	v_mfma_f32_16x16x32_bf16 v[116:119], v[88:91], v[188:191], v[116:119]
	v_mfma_f32_16x16x32_bf16 v[112:115], v[100:103], v[188:191], v[112:115]
	v_mfma_f32_16x16x32_bf16 v[76:79], v[88:91], v[204:207], v[76:79]
	v_mfma_f32_16x16x32_bf16 v[68:71], v[100:103], v[204:207], v[68:71]
	v_mfma_f32_16x16x32_bf16 v[148:151], v[92:95], v[164:167], v[148:151]
	v_mfma_f32_16x16x32_bf16 v[144:147], v[104:107], v[164:167], v[144:147]
	v_mfma_f32_16x16x32_bf16 v[132:135], v[92:95], v[172:175], v[132:135]
	v_mfma_f32_16x16x32_bf16 v[128:131], v[104:107], v[172:175], v[128:131]
	v_mfma_f32_16x16x32_bf16 v[116:119], v[92:95], v[192:195], v[116:119]
	v_mfma_f32_16x16x32_bf16 v[112:115], v[104:107], v[192:195], v[112:115]
	v_mfma_f32_16x16x32_bf16 v[76:79], v[92:95], v[208:211], v[76:79]
	v_mfma_f32_16x16x32_bf16 v[68:71], v[104:107], v[208:211], v[68:71]
	s_barrier
; #define PG8_STAGE(bufoff, gbase, voff) do { _Pragma("unroll") for (int _i = 0; _i < 2; ++_i) \
;         __builtin_amdgcn_global_load_lds((const unsigned*)((const char*)(gbase) + (voff)[_i]), (PG8_LAS unsigned*)(lds + (bufoff) + ldsw + _i * 8192), 16, 0, 0); } while (0)
; #define PG8_LDA(dst, b, h) do { _Pragma("unroll") for (int m = 0; m < 4; ++m) _Pragma("unroll") for (int k = 0; k < 2; ++k) dst[m][k] = *(const PG8_LAS bf16x8*)(lds + PG8_SA(b, h) + aoff + m * 2048 + k * 1024); } while (0)
; #define PG8_MMA(ai, bj, At, Bt) do { __builtin_amdgcn_s_setprio(1); _Pragma("unroll") for (int m = 0; m < 4; ++m) _Pragma("unroll") for (int n = 0; n < 2; ++n) _Pragma("unroll") for (int k = 0; k < 2; ++k) \
;         acc[ai][bj][m][n] = __builtin_amdgcn_mfma_f32_16x16x32_bf16(Bt[n][k], At[m][k], acc[ai][bj][m][n], 0, 0, 0); __builtin_amdgcn_s_setprio(0); } while (0)
; #define PG8_WAIT_V(n) asm volatile("s_waitcnt vmcnt(" #n ")" ::: "memory")
; #define PG8_WAIT_L(n) asm volatile("s_waitcnt lgkmcnt(" #n ")" ::: "memory")
; #define PG8_BAR __builtin_amdgcn_s_barrier()
; #define PG8_SCHED __builtin_amdgcn_sched_barrier(0)
; template <class Epi, class Sched, bool ALIGN_EPI = false, bool SP2 = false>
; __device__ __forceinline__ void gemm_phase(PG8_LAS unsigned char* lds, const Gemm g, const Sched& S, const Epi& E, const int wid) {
;     ...
;             PG8_LDA(At, 1, 1); PG8_STAGE(PG8_SB(1, 0), b3, voffB); PG8_STAGE(PG8_SB(1, 1), b3 + hsB, voffB); PG8_STAGE(PG8_SA(1, 0), a3, voffA);
;             PG8_WAIT_V(8); PG8_WAIT_L(0); PG8_BAR; PG8_MMA(1, 0, At, B0); PG8_MMA(1, 1, At, B1); PG8_BAR; PG8_SCHED;
	s_setprio 0
	s_add_i32 s40, s62, s44
	v_lshl_add_u64 v[196:197], v[196:197], 0, s[20:21]
	s_mov_b32 m0, s40
	ds_read_b128 v[160:163], v201 offset:49152
	ds_read_b128 v[164:167], v201 offset:50176
	ds_read_b128 v[168:171], v201 offset:51200
	ds_read_b128 v[172:175], v201 offset:52224
	ds_read_b128 v[188:191], v201 offset:53248
	ds_read_b128 v[192:195], v201 offset:54272
	ds_read_b128 v[204:207], v201 offset:55296
	ds_read_b128 v[208:211], v201 offset:56320
	global_load_lds_dwordx4 v[196:197], off
	s_add_i32 m0, s40, 0x2000
	s_add_u32 s38, s38, 0x80080
	v_lshl_add_u64 v[196:197], v[212:213], 0, s[20:21]
	s_addc_u32 s39, s39, 0
	s_add_i32 s40, s63, s44
	global_load_lds_dwordx4 v[196:197], off
	v_lshl_add_u64 v[196:197], s[38:39], 0, v[176:177]
	s_mov_b32 m0, s40
	s_nop 0
	global_load_lds_dwordx4 v[196:197], off
	v_lshl_add_u64 v[196:197], s[38:39], 0, v[178:179]
	s_add_i32 m0, s40, 0x2000
	s_nop 0
	global_load_lds_dwordx4 v[196:197], off
	v_lshl_add_u64 v[196:197], v[214:215], 0, s[20:21]
	s_mov_b32 m0, s51
	s_nop 0
	global_load_lds_dwordx4 v[196:197], off
	v_lshl_add_u64 v[196:197], v[216:217], 0, s[20:21]
	s_mov_b32 m0, s52
	s_nop 0
	global_load_lds_dwordx4 v[196:197], off
	s_waitcnt vmcnt(8)
	s_waitcnt lgkmcnt(0)
	s_setprio 1
	s_barrier
	v_mfma_f32_16x16x32_bf16 v[60:63], v[64:67], v[160:163], v[60:63]
	v_mfma_f32_16x16x32_bf16 v[56:59], v[80:83], v[160:163], v[56:59]
	v_mfma_f32_16x16x32_bf16 v[44:47], v[64:67], v[168:171], v[44:47]
	v_mfma_f32_16x16x32_bf16 v[40:43], v[80:83], v[168:171], v[40:43]
	v_mfma_f32_16x16x32_bf16 v[28:31], v[64:67], v[188:191], v[28:31]
	v_mfma_f32_16x16x32_bf16 v[24:27], v[80:83], v[188:191], v[24:27]
	v_mfma_f32_16x16x32_bf16 v[12:15], v[64:67], v[204:207], v[12:15]
	v_mfma_f32_16x16x32_bf16 v[8:11], v[80:83], v[204:207], v[8:11]
	v_mfma_f32_16x16x32_bf16 v[60:63], v[72:75], v[164:167], v[60:63]
	v_mfma_f32_16x16x32_bf16 v[56:59], v[84:87], v[164:167], v[56:59]
	v_mfma_f32_16x16x32_bf16 v[44:47], v[72:75], v[172:175], v[44:47]
	v_mfma_f32_16x16x32_bf16 v[40:43], v[84:87], v[172:175], v[40:43]
	v_mfma_f32_16x16x32_bf16 v[28:31], v[72:75], v[192:195], v[28:31]
	v_mfma_f32_16x16x32_bf16 v[24:27], v[84:87], v[192:195], v[24:27]
	v_mfma_f32_16x16x32_bf16 v[12:15], v[72:75], v[208:211], v[12:15]
	v_mfma_f32_16x16x32_bf16 v[8:11], v[84:87], v[208:211], v[8:11]
	s_setprio 0
	s_setprio 1
	v_mfma_f32_16x16x32_bf16 v[52:55], v[88:91], v[160:163], v[52:55]
	v_mfma_f32_16x16x32_bf16 v[48:51], v[100:103], v[160:163], v[48:51]
	v_mfma_f32_16x16x32_bf16 v[36:39], v[88:91], v[168:171], v[36:39]
	v_mfma_f32_16x16x32_bf16 v[32:35], v[100:103], v[168:171], v[32:35]
	v_mfma_f32_16x16x32_bf16 v[20:23], v[88:91], v[188:191], v[20:23]
	v_mfma_f32_16x16x32_bf16 v[16:19], v[100:103], v[188:191], v[16:19]
	v_mfma_f32_16x16x32_bf16 v[4:7], v[88:91], v[204:207], v[4:7]
	v_mfma_f32_16x16x32_bf16 v[0:3], v[100:103], v[204:207], v[0:3]
	v_mfma_f32_16x16x32_bf16 v[52:55], v[92:95], v[164:167], v[52:55]
	v_mfma_f32_16x16x32_bf16 v[48:51], v[104:107], v[164:167], v[48:51]
	v_mfma_f32_16x16x32_bf16 v[36:39], v[92:95], v[172:175], v[36:39]
	v_mfma_f32_16x16x32_bf16 v[32:35], v[104:107], v[172:175], v[32:35]
	v_mfma_f32_16x16x32_bf16 v[20:23], v[92:95], v[192:195], v[20:23]
	v_mfma_f32_16x16x32_bf16 v[16:19], v[104:107], v[192:195], v[16:19]
	v_mfma_f32_16x16x32_bf16 v[4:7], v[92:95], v[208:211], v[4:7]
	v_mfma_f32_16x16x32_bf16 v[0:3], v[104:107], v[208:211], v[0:3]
	s_barrier
	s_setprio 0
	s_add_i32 s61, s61, 2
	s_add_u32 s59, s59, 0x100
	s_addc_u32 s60, s60, 0
	s_add_u32 s36, s36, 0x100
	s_addc_u32 s37, s37, 0
	s_cmp_gt_u32 s61, 29
	s_cbranch_scc0 .LBB0_1304
	s_and_b64 vcc, exec, s[22:23]
	s_cbranch_vccz .LBB0_1307
	s_barrier

; #define PG8_STAGE(bufoff, gbase, voff) do { _Pragma("unroll") for (int _i = 0; _i < 2; ++_i) \
;         __builtin_amdgcn_global_load_lds((const unsigned*)((const char*)(gbase) + (voff)[_i]), (PG8_LAS unsigned*)(lds + (bufoff) + ldsw + _i * 8192), 16, 0, 0); } while (0)
; #define PG8_LDA(dst, b, h) do { _Pragma("unroll") for (int m = 0; m < 4; ++m) _Pragma("unroll") for (int k = 0; k < 2; ++k) dst[m][k] = *(const PG8_LAS bf16x8*)(lds + PG8_SA(b, h) + aoff + m * 2048 + k * 1024); } while (0)
; #define PG8_LDB(dst, b, h) do { _Pragma("unroll") for (int n = 0; n < 2; ++n) _Pragma("unroll") for (int k = 0; k < 2; ++k) dst[n][k] = *(const PG8_LAS bf16x8*)(lds + PG8_SB(b, h) + boff + n * 2048 + k * 1024); } while (0)
; #define PG8_MMA(ai, bj, At, Bt) do { __builtin_amdgcn_s_setprio(1); _Pragma("unroll") for (int m = 0; m < 4; ++m) _Pragma("unroll") for (int n = 0; n < 2; ++n) _Pragma("unroll") for (int k = 0; k < 2; ++k) \
;         acc[ai][bj][m][n] = __builtin_amdgcn_mfma_f32_16x16x32_bf16(Bt[n][k], At[m][k], acc[ai][bj][m][n], 0, 0, 0); __builtin_amdgcn_s_setprio(0); } while (0)
; #define PG8_WAIT_V(n) asm volatile("s_waitcnt vmcnt(" #n ")" ::: "memory")
; #define PG8_WAIT_L(n) asm volatile("s_waitcnt lgkmcnt(" #n ")" ::: "memory")
; template <class Epi, class Sched, bool ALIGN_EPI = false, bool SP2 = false>
; __device__ __forceinline__ void gemm_phase(PG8_LAS unsigned char* lds, const Gemm g, const Sched& S, const Epi& E, const int wid) {
;     ...
;         for (int t = 0; t < nt; t += 2) {
;             const bool last = (t == nt - 2);
;             const char* a1 = cA + (size_t)(t + 1) * kstep;
;             const char* a2 = last ? nA : cA + (size_t)(t + 2) * kstep; const char* b2 = last ? nB : cB + (size_t)(t + 2) * kstep;
;             const char* a3 = a2 + kstep; const char* b3 = b2 + kstep;
;             if constexpr (SP2) {
;             PG8_LDB(B0, 0, 0); PG8_LDB(B1, 0, 1); PG8_SCHED; PG8_LDA(At, 0, 0); PG8_STAGE(PG8_SA(1, 1), a1 + hsA, voffA);
;             PG8_WAIT_V(8); PG8_WAIT_L(0); PG8_BAR; PG8_MMA(0, 0, At, B0); PG8_MMA(0, 1, At, B1); PG8_BAR; PG8_SCHED;
;             PG8_LDA(At, 0, 1); PG8_STAGE(PG8_SB(0, 0), b2, voffB); PG8_STAGE(PG8_SB(0, 1), b2 + hsB, voffB); PG8_STAGE(PG8_SA(0, 0), a2, voffA);
;             PG8_WAIT_V(8); PG8_WAIT_L(0); PG8_BAR; PG8_MMA(1, 0, At, B0); PG8_MMA(1, 1, At, B1); PG8_BAR; PG8_SCHED;
.LBB0_1385:
	ds_read_b128 v[128:131], v171
	ds_read_b128 v[132:135], v171 offset:1024
	ds_read_b128 v[136:139], v171 offset:2048
	ds_read_b128 v[140:143], v171 offset:3072
	ds_read_b128 v[160:163], v173
	ds_read_b128 v[164:167], v173 offset:1024
	ds_read_b128 v[180:183], v173 offset:2048
	ds_read_b128 v[184:187], v173 offset:3072
	s_add_u32 s8, s6, 0xfff80080
	s_addc_u32 s9, s7, -1
	s_cmp_eq_u32 s60, 28
	s_cselect_b32 s31, s5, s9
	s_cselect_b32 s30, s25, s8
	s_cselect_b32 s9, s23, s59
	s_cselect_b32 s8, s57, s58
	v_lshl_add_u64 v[220:221], s[6:7], 0, v[154:155]
	s_add_i32 m0, s39, 0xc000
	ds_read_b128 v[188:191], v175
	ds_read_b128 v[192:195], v175 offset:1024
	ds_read_b128 v[196:199], v175 offset:2048
	ds_read_b128 v[200:203], v175 offset:3072
	ds_read_b128 v[204:207], v175 offset:4096
	ds_read_b128 v[208:211], v175 offset:5120
	ds_read_b128 v[212:215], v175 offset:6144
	ds_read_b128 v[216:219], v175 offset:7168
	global_load_lds_dwordx4 v[220:221], off
	v_lshl_add_u64 v[220:221], s[6:7], 0, v[152:153]
	s_add_i32 m0, s39, 0xe000
	s_nop 0
	global_load_lds_dwordx4 v[220:221], off
	s_waitcnt vmcnt(8)
	s_waitcnt lgkmcnt(0)
	s_setprio 1
	s_barrier
	v_mfma_f32_16x16x32_bf16 v[124:127], v[128:131], v[188:191], v[124:127]
	v_mfma_f32_16x16x32_bf16 v[120:123], v[136:139], v[188:191], v[120:123]
	v_mfma_f32_16x16x32_bf16 v[108:111], v[128:131], v[196:199], v[108:111]
	v_mfma_f32_16x16x32_bf16 v[104:107], v[136:139], v[196:199], v[104:107]
	v_mfma_f32_16x16x32_bf16 v[92:95], v[128:131], v[204:207], v[92:95]
	v_mfma_f32_16x16x32_bf16 v[88:91], v[136:139], v[204:207], v[88:91]
	v_mfma_f32_16x16x32_bf16 v[76:79], v[128:131], v[212:215], v[76:79]
	v_mfma_f32_16x16x32_bf16 v[72:75], v[136:139], v[212:215], v[72:75]
	v_mfma_f32_16x16x32_bf16 v[124:127], v[132:135], v[192:195], v[124:127]
	v_mfma_f32_16x16x32_bf16 v[120:123], v[140:143], v[192:195], v[120:123]
	v_mfma_f32_16x16x32_bf16 v[108:111], v[132:135], v[200:203], v[108:111]
	v_mfma_f32_16x16x32_bf16 v[104:107], v[140:143], v[200:203], v[104:107]
	v_mfma_f32_16x16x32_bf16 v[92:95], v[132:135], v[208:211], v[92:95]
	v_mfma_f32_16x16x32_bf16 v[88:91], v[140:143], v[208:211], v[88:91]
	v_mfma_f32_16x16x32_bf16 v[76:79], v[132:135], v[216:219], v[76:79]
	v_mfma_f32_16x16x32_bf16 v[72:75], v[140:143], v[216:219], v[72:75]
	s_setprio 0
	s_setprio 1
	v_mfma_f32_16x16x32_bf16 v[116:119], v[160:163], v[188:191], v[116:119]
	v_mfma_f32_16x16x32_bf16 v[112:115], v[180:183], v[188:191], v[112:115]
	v_mfma_f32_16x16x32_bf16 v[100:103], v[160:163], v[196:199], v[100:103]
	v_mfma_f32_16x16x32_bf16 v[96:99], v[180:183], v[196:199], v[96:99]
	v_mfma_f32_16x16x32_bf16 v[84:87], v[160:163], v[204:207], v[84:87]
	v_mfma_f32_16x16x32_bf16 v[80:83], v[180:183], v[204:207], v[80:83]
	v_mfma_f32_16x16x32_bf16 v[68:71], v[160:163], v[212:215], v[68:71]
	v_mfma_f32_16x16x32_bf16 v[64:67], v[180:183], v[212:215], v[64:67]
	v_mfma_f32_16x16x32_bf16 v[116:119], v[164:167], v[192:195], v[116:119]
	v_mfma_f32_16x16x32_bf16 v[112:115], v[184:187], v[192:195], v[112:115]
	v_mfma_f32_16x16x32_bf16 v[100:103], v[164:167], v[200:203], v[100:103]
	v_mfma_f32_16x16x32_bf16 v[96:99], v[184:187], v[200:203], v[96:99]
	v_mfma_f32_16x16x32_bf16 v[84:87], v[164:167], v[208:211], v[84:87]
	v_mfma_f32_16x16x32_bf16 v[80:83], v[184:187], v[208:211], v[80:83]
	v_mfma_f32_16x16x32_bf16 v[68:71], v[164:167], v[216:219], v[68:71]
	v_mfma_f32_16x16x32_bf16 v[64:67], v[184:187], v[216:219], v[64:67]
	s_barrier
	s_setprio 0
	s_add_i32 s61, s52, s36
	v_lshl_add_u64 v[220:221], s[8:9], 0, v[148:149]
	s_mov_b32 m0, s61
	ds_read_b128 v[188:191], v175 offset:16384
	ds_read_b128 v[192:195], v175 offset:17408
	ds_read_b128 v[196:199], v175 offset:18432
	ds_read_b128 v[200:203], v175 offset:19456
	ds_read_b128 v[204:207], v175 offset:20480
	ds_read_b128 v[208:211], v175 offset:21504
	ds_read_b128 v[212:215], v175 offset:22528
	ds_read_b128 v[216:219], v175 offset:23552
	global_load_lds_dwordx4 v[220:221], off
	s_add_i32 m0, s61, 0x2000
	s_add_u32 s62, s8, 0x80000
	v_lshl_add_u64 v[222:223], s[8:9], 0, v[144:145]
	s_addc_u32 s63, s9, 0
	s_add_i32 s61, s53, s36
	global_load_lds_dwordx4 v[222:223], off
	v_lshl_add_u64 v[224:225], s[62:63], 0, v[148:149]
	s_mov_b32 m0, s61
	v_lshl_add_u64 v[226:227], s[30:31], 0, v[146:147]
	global_load_lds_dwordx4 v[224:225], off
	v_lshl_add_u64 v[224:225], s[62:63], 0, v[144:145]
	s_add_i32 m0, s61, 0x2000
	s_nop 0
	global_load_lds_dwordx4 v[224:225], off
	v_lshl_add_u64 v[224:225], s[30:31], 0, v[150:151]
	s_mov_b32 m0, s39
	s_nop 0
	global_load_lds_dwordx4 v[224:225], off
	s_mov_b32 m0, s40
	s_nop 0
	global_load_lds_dwordx4 v[226:227], off
	s_waitcnt vmcnt(8)
	s_waitcnt lgkmcnt(0)
	s_setprio 1
	s_barrier
; #define PG8_STAGE(bufoff, gbase, voff) do { _Pragma("unroll") for (int _i = 0; _i < 2; ++_i) \
;         __builtin_amdgcn_global_load_lds((const unsigned*)((const char*)(gbase) + (voff)[_i]), (PG8_LAS unsigned*)(lds + (bufoff) + ldsw + _i * 8192), 16, 0, 0); } while (0)
; #define PG8_LDA(dst, b, h) do { _Pragma("unroll") for (int m = 0; m < 4; ++m) _Pragma("unroll") for (int k = 0; k < 2; ++k) dst[m][k] = *(const PG8_LAS bf16x8*)(lds + PG8_SA(b, h) + aoff + m * 2048 + k * 1024); } while (0)
; #define PG8_LDB(dst, b, h) do { _Pragma("unroll") for (int n = 0; n < 2; ++n) _Pragma("unroll") for (int k = 0; k < 2; ++k) dst[n][k] = *(const PG8_LAS bf16x8*)(lds + PG8_SB(b, h) + boff + n * 2048 + k * 1024); } while (0)
; #define PG8_MMA(ai, bj, At, Bt) do { __builtin_amdgcn_s_setprio(1); _Pragma("unroll") for (int m = 0; m < 4; ++m) _Pragma("unroll") for (int n = 0; n < 2; ++n) _Pragma("unroll") for (int k = 0; k < 2; ++k) \
;         acc[ai][bj][m][n] = __builtin_amdgcn_mfma_f32_16x16x32_bf16(Bt[n][k], At[m][k], acc[ai][bj][m][n], 0, 0, 0); __builtin_amdgcn_s_setprio(0); } while (0)
; #define PG8_WAIT_V(n) asm volatile("s_waitcnt vmcnt(" #n ")" ::: "memory")
; #define PG8_WAIT_L(n) asm volatile("s_waitcnt lgkmcnt(" #n ")" ::: "memory")
; #define PG8_BAR __builtin_amdgcn_s_barrier()
; #define PG8_SCHED __builtin_amdgcn_sched_barrier(0)
; template <class Epi, class Sched, bool ALIGN_EPI = false, bool SP2 = false>
; __device__ __forceinline__ void gemm_phase(PG8_LAS unsigned char* lds, const Gemm g, const Sched& S, const Epi& E, const int wid) {
;     ...
;             PG8_WAIT_V(8); PG8_WAIT_L(0); PG8_BAR; PG8_MMA(1, 0, At, B0); PG8_MMA(1, 1, At, B1); PG8_BAR; PG8_SCHED;
;             PG8_LDB(B0, 1, 0); PG8_LDB(B1, 1, 1); PG8_SCHED; PG8_LDA(At, 1, 0); PG8_STAGE(PG8_SA(0, 1), a2 + hsA, voffA);
;             PG8_WAIT_V(8); PG8_WAIT_L(0); PG8_BAR; PG8_MMA(0, 0, At, B0); PG8_MMA(0, 1, At, B1); PG8_BAR; PG8_SCHED;
	v_mfma_f32_16x16x32_bf16 v[60:63], v[128:131], v[188:191], v[60:63]
	v_mfma_f32_16x16x32_bf16 v[56:59], v[136:139], v[188:191], v[56:59]
	v_mfma_f32_16x16x32_bf16 v[44:47], v[128:131], v[196:199], v[44:47]
	v_mfma_f32_16x16x32_bf16 v[40:43], v[136:139], v[196:199], v[40:43]
	v_mfma_f32_16x16x32_bf16 v[28:31], v[128:131], v[204:207], v[28:31]
	v_mfma_f32_16x16x32_bf16 v[24:27], v[136:139], v[204:207], v[24:27]
	v_mfma_f32_16x16x32_bf16 v[12:15], v[128:131], v[212:215], v[12:15]
	v_mfma_f32_16x16x32_bf16 v[8:11], v[136:139], v[212:215], v[8:11]
	v_mfma_f32_16x16x32_bf16 v[60:63], v[132:135], v[192:195], v[60:63]
	v_mfma_f32_16x16x32_bf16 v[56:59], v[140:143], v[192:195], v[56:59]
	v_mfma_f32_16x16x32_bf16 v[44:47], v[132:135], v[200:203], v[44:47]
	v_mfma_f32_16x16x32_bf16 v[40:43], v[140:143], v[200:203], v[40:43]
	v_mfma_f32_16x16x32_bf16 v[28:31], v[132:135], v[208:211], v[28:31]
	v_mfma_f32_16x16x32_bf16 v[24:27], v[140:143], v[208:211], v[24:27]
	v_mfma_f32_16x16x32_bf16 v[12:15], v[132:135], v[216:219], v[12:15]
	v_mfma_f32_16x16x32_bf16 v[8:11], v[140:143], v[216:219], v[8:11]
	s_setprio 0
	s_setprio 1
	v_mfma_f32_16x16x32_bf16 v[52:55], v[160:163], v[188:191], v[52:55]
	v_mfma_f32_16x16x32_bf16 v[48:51], v[180:183], v[188:191], v[48:51]
	v_mfma_f32_16x16x32_bf16 v[36:39], v[160:163], v[196:199], v[36:39]
	v_mfma_f32_16x16x32_bf16 v[32:35], v[180:183], v[196:199], v[32:35]
	v_mfma_f32_16x16x32_bf16 v[20:23], v[160:163], v[204:207], v[20:23]
	v_mfma_f32_16x16x32_bf16 v[16:19], v[180:183], v[204:207], v[16:19]
	v_mfma_f32_16x16x32_bf16 v[4:7], v[160:163], v[212:215], v[4:7]
	v_mfma_f32_16x16x32_bf16 v[0:3], v[180:183], v[212:215], v[0:3]
	v_mfma_f32_16x16x32_bf16 v[52:55], v[164:167], v[192:195], v[52:55]
	v_mfma_f32_16x16x32_bf16 v[48:51], v[184:187], v[192:195], v[48:51]
	v_mfma_f32_16x16x32_bf16 v[36:39], v[164:167], v[200:203], v[36:39]
	v_mfma_f32_16x16x32_bf16 v[32:35], v[184:187], v[200:203], v[32:35]
	v_mfma_f32_16x16x32_bf16 v[20:23], v[164:167], v[208:211], v[20:23]
	v_mfma_f32_16x16x32_bf16 v[16:19], v[184:187], v[208:211], v[16:19]
	v_mfma_f32_16x16x32_bf16 v[4:7], v[164:167], v[216:219], v[4:7]
	v_mfma_f32_16x16x32_bf16 v[0:3], v[184:187], v[216:219], v[0:3]
	s_barrier
	s_setprio 0
	s_add_i32 s61, 0, 0x18000
	s_add_i32 s62, 0, 0x1c000
	v_add_u32_e32 v140, s61, v169
	v_add_u32_e32 v168, s62, v169
	ds_read_b128 v[128:131], v140
	ds_read_b128 v[132:135], v140 offset:1024
	ds_read_b128 v[136:139], v140 offset:2048
	ds_read_b128 v[140:143], v140 offset:3072
	ds_read_b128 v[160:163], v168
	ds_read_b128 v[164:167], v168 offset:1024
	ds_read_b128 v[180:183], v168 offset:2048
	ds_read_b128 v[184:187], v168 offset:3072
	s_add_u32 s30, s30, 0x80000
	s_addc_u32 s31, s31, 0
	s_mov_b32 m0, s41
	v_lshl_add_u64 v[228:229], s[30:31], 0, v[150:151]
	ds_read_b128 v[188:191], v175 offset:32768
	ds_read_b128 v[192:195], v175 offset:33792
	ds_read_b128 v[196:199], v175 offset:34816
	ds_read_b128 v[200:203], v175 offset:35840
	ds_read_b128 v[204:207], v175 offset:36864
	ds_read_b128 v[208:211], v175 offset:37888
	ds_read_b128 v[212:215], v175 offset:38912
	ds_read_b128 v[216:219], v175 offset:39936
	global_load_lds_dwordx4 v[228:229], off
	v_lshl_add_u64 v[228:229], s[30:31], 0, v[146:147]
	s_mov_b32 m0, s42
	s_nop 0
	global_load_lds_dwordx4 v[228:229], off
	s_waitcnt vmcnt(8)
	s_waitcnt lgkmcnt(0)
	s_setprio 1
	s_barrier
	v_mfma_f32_16x16x32_bf16 v[124:127], v[128:131], v[188:191], v[124:127]
	v_mfma_f32_16x16x32_bf16 v[120:123], v[136:139], v[188:191], v[120:123]
	v_mfma_f32_16x16x32_bf16 v[108:111], v[128:131], v[196:199], v[108:111]
	v_mfma_f32_16x16x32_bf16 v[104:107], v[136:139], v[196:199], v[104:107]
	v_mfma_f32_16x16x32_bf16 v[92:95], v[128:131], v[204:207], v[92:95]
	v_mfma_f32_16x16x32_bf16 v[88:91], v[136:139], v[204:207], v[88:91]
	v_mfma_f32_16x16x32_bf16 v[76:79], v[128:131], v[212:215], v[76:79]
	v_mfma_f32_16x16x32_bf16 v[72:75], v[136:139], v[212:215], v[72:75]
	v_mfma_f32_16x16x32_bf16 v[124:127], v[132:135], v[192:195], v[124:127]
	v_mfma_f32_16x16x32_bf16 v[120:123], v[140:143], v[192:195], v[120:123]
	v_mfma_f32_16x16x32_bf16 v[108:111], v[132:135], v[200:203], v[108:111]
	v_mfma_f32_16x16x32_bf16 v[104:107], v[140:143], v[200:203], v[104:107]
	v_mfma_f32_16x16x32_bf16 v[92:95], v[132:135], v[208:211], v[92:95]
	v_mfma_f32_16x16x32_bf16 v[88:91], v[140:143], v[208:211], v[88:91]
	v_mfma_f32_16x16x32_bf16 v[76:79], v[132:135], v[216:219], v[76:79]
	v_mfma_f32_16x16x32_bf16 v[72:75], v[140:143], v[216:219], v[72:75]
	s_setprio 0
	s_setprio 1
	v_mfma_f32_16x16x32_bf16 v[116:119], v[160:163], v[188:191], v[116:119]
	v_mfma_f32_16x16x32_bf16 v[112:115], v[180:183], v[188:191], v[112:115]
	v_mfma_f32_16x16x32_bf16 v[100:103], v[160:163], v[196:199], v[100:103]
	v_mfma_f32_16x16x32_bf16 v[96:99], v[180:183], v[196:199], v[96:99]
	v_mfma_f32_16x16x32_bf16 v[84:87], v[160:163], v[204:207], v[84:87]
	v_mfma_f32_16x16x32_bf16 v[80:83], v[180:183], v[204:207], v[80:83]
	v_mfma_f32_16x16x32_bf16 v[68:71], v[160:163], v[212:215], v[68:71]
	v_mfma_f32_16x16x32_bf16 v[64:67], v[180:183], v[212:215], v[64:67]
	v_mfma_f32_16x16x32_bf16 v[116:119], v[164:167], v[192:195], v[116:119]
	v_mfma_f32_16x16x32_bf16 v[112:115], v[184:187], v[192:195], v[112:115]
	v_mfma_f32_16x16x32_bf16 v[100:103], v[164:167], v[200:203], v[100:103]
	v_mfma_f32_16x16x32_bf16 v[96:99], v[184:187], v[200:203], v[96:99]
	v_mfma_f32_16x16x32_bf16 v[84:87], v[164:167], v[208:211], v[84:87]
	v_mfma_f32_16x16x32_bf16 v[80:83], v[184:187], v[208:211], v[80:83]
	v_mfma_f32_16x16x32_bf16 v[68:71], v[164:167], v[216:219], v[68:71]
	v_mfma_f32_16x16x32_bf16 v[64:67], v[184:187], v[216:219], v[64:67]
	s_barrier
; #define PG8_STAGE(bufoff, gbase, voff) do { _Pragma("unroll") for (int _i = 0; _i < 2; ++_i) \
;         __builtin_amdgcn_global_load_lds((const unsigned*)((const char*)(gbase) + (voff)[_i]), (PG8_LAS unsigned*)(lds + (bufoff) + ldsw + _i * 8192), 16, 0, 0); } while (0)
; #define PG8_LDA(dst, b, h) do { _Pragma("unroll") for (int m = 0; m < 4; ++m) _Pragma("unroll") for (int k = 0; k < 2; ++k) dst[m][k] = *(const PG8_LAS bf16x8*)(lds + PG8_SA(b, h) + aoff + m * 2048 + k * 1024); } while (0)
; #define PG8_MMA(ai, bj, At, Bt) do { __builtin_amdgcn_s_setprio(1); _Pragma("unroll") for (int m = 0; m < 4; ++m) _Pragma("unroll") for (int n = 0; n < 2; ++n) _Pragma("unroll") for (int k = 0; k < 2; ++k) \
;         acc[ai][bj][m][n] = __builtin_amdgcn_mfma_f32_16x16x32_bf16(Bt[n][k], At[m][k], acc[ai][bj][m][n], 0, 0, 0); __builtin_amdgcn_s_setprio(0); } while (0)
; #define PG8_WAIT_V(n) asm volatile("s_waitcnt vmcnt(" #n ")" ::: "memory")
; #define PG8_WAIT_L(n) asm volatile("s_waitcnt lgkmcnt(" #n ")" ::: "memory")
; #define PG8_BAR __builtin_amdgcn_s_barrier()
; #define PG8_SCHED __builtin_amdgcn_sched_barrier(0)
; template <class Epi, class Sched, bool ALIGN_EPI = false, bool SP2 = false>
; __device__ __forceinline__ void gemm_phase(PG8_LAS unsigned char* lds, const Gemm g, const Sched& S, const Epi& E, const int wid) {
;     ...
;             PG8_LDA(At, 1, 1); PG8_STAGE(PG8_SB(1, 0), b3, voffB); PG8_STAGE(PG8_SB(1, 1), b3 + hsB, voffB); PG8_STAGE(PG8_SA(1, 0), a3, voffA);
;             PG8_WAIT_V(8); PG8_WAIT_L(0); PG8_BAR; PG8_MMA(1, 0, At, B0); PG8_MMA(1, 1, At, B1); PG8_BAR; PG8_SCHED;
	s_setprio 0
	s_add_i32 s30, s61, s36
	v_lshl_add_u64 v[220:221], v[220:221], 0, s[18:19]
	s_mov_b32 m0, s30
	ds_read_b128 v[188:191], v175 offset:49152
	ds_read_b128 v[192:195], v175 offset:50176
	ds_read_b128 v[196:199], v175 offset:51200
	ds_read_b128 v[200:203], v175 offset:52224
	ds_read_b128 v[204:207], v175 offset:53248
	ds_read_b128 v[208:211], v175 offset:54272
	ds_read_b128 v[212:215], v175 offset:55296
	ds_read_b128 v[216:219], v175 offset:56320
	global_load_lds_dwordx4 v[220:221], off
	s_add_i32 m0, s30, 0x2000
	s_add_u32 s8, s8, 0x80080
	v_lshl_add_u64 v[220:221], v[222:223], 0, s[18:19]
	s_addc_u32 s9, s9, 0
	s_add_i32 s30, s62, s36
	global_load_lds_dwordx4 v[220:221], off
	v_lshl_add_u64 v[220:221], s[8:9], 0, v[148:149]
	s_mov_b32 m0, s30
	s_nop 0
	global_load_lds_dwordx4 v[220:221], off
	v_lshl_add_u64 v[220:221], s[8:9], 0, v[144:145]
	s_add_i32 m0, s30, 0x2000
	s_nop 0
	global_load_lds_dwordx4 v[220:221], off
	v_lshl_add_u64 v[220:221], v[224:225], 0, s[18:19]
	s_mov_b32 m0, s45
	s_nop 0
	global_load_lds_dwordx4 v[220:221], off
	v_lshl_add_u64 v[220:221], v[226:227], 0, s[18:19]
	s_mov_b32 m0, s46
	s_nop 0
	global_load_lds_dwordx4 v[220:221], off
	s_waitcnt vmcnt(8)
	s_waitcnt lgkmcnt(0)
	s_setprio 1
	s_barrier
	v_mfma_f32_16x16x32_bf16 v[60:63], v[128:131], v[188:191], v[60:63]
	v_mfma_f32_16x16x32_bf16 v[56:59], v[136:139], v[188:191], v[56:59]
	v_mfma_f32_16x16x32_bf16 v[44:47], v[128:131], v[196:199], v[44:47]
	v_mfma_f32_16x16x32_bf16 v[40:43], v[136:139], v[196:199], v[40:43]
	v_mfma_f32_16x16x32_bf16 v[28:31], v[128:131], v[204:207], v[28:31]
	v_mfma_f32_16x16x32_bf16 v[24:27], v[136:139], v[204:207], v[24:27]
	v_mfma_f32_16x16x32_bf16 v[12:15], v[128:131], v[212:215], v[12:15]
	v_mfma_f32_16x16x32_bf16 v[8:11], v[136:139], v[212:215], v[8:11]
	v_mfma_f32_16x16x32_bf16 v[60:63], v[132:135], v[192:195], v[60:63]
	v_mfma_f32_16x16x32_bf16 v[56:59], v[140:143], v[192:195], v[56:59]
	v_mfma_f32_16x16x32_bf16 v[44:47], v[132:135], v[200:203], v[44:47]
	v_mfma_f32_16x16x32_bf16 v[40:43], v[140:143], v[200:203], v[40:43]
	v_mfma_f32_16x16x32_bf16 v[28:31], v[132:135], v[208:211], v[28:31]
	v_mfma_f32_16x16x32_bf16 v[24:27], v[140:143], v[208:211], v[24:27]
	v_mfma_f32_16x16x32_bf16 v[12:15], v[132:135], v[216:219], v[12:15]
	v_mfma_f32_16x16x32_bf16 v[8:11], v[140:143], v[216:219], v[8:11]
	s_setprio 0
	s_setprio 1
	v_mfma_f32_16x16x32_bf16 v[52:55], v[160:163], v[188:191], v[52:55]
	v_mfma_f32_16x16x32_bf16 v[48:51], v[180:183], v[188:191], v[48:51]
	v_mfma_f32_16x16x32_bf16 v[36:39], v[160:163], v[196:199], v[36:39]
	v_mfma_f32_16x16x32_bf16 v[32:35], v[180:183], v[196:199], v[32:35]
	v_mfma_f32_16x16x32_bf16 v[20:23], v[160:163], v[204:207], v[20:23]
	v_mfma_f32_16x16x32_bf16 v[16:19], v[180:183], v[204:207], v[16:19]
	v_mfma_f32_16x16x32_bf16 v[4:7], v[160:163], v[212:215], v[4:7]
	v_mfma_f32_16x16x32_bf16 v[0:3], v[180:183], v[212:215], v[0:3]
	v_mfma_f32_16x16x32_bf16 v[52:55], v[164:167], v[192:195], v[52:55]
	v_mfma_f32_16x16x32_bf16 v[48:51], v[184:187], v[192:195], v[48:51]
	v_mfma_f32_16x16x32_bf16 v[36:39], v[164:167], v[200:203], v[36:39]
	v_mfma_f32_16x16x32_bf16 v[32:35], v[184:187], v[200:203], v[32:35]
	v_mfma_f32_16x16x32_bf16 v[20:23], v[164:167], v[208:211], v[20:23]
	v_mfma_f32_16x16x32_bf16 v[16:19], v[184:187], v[208:211], v[16:19]
	v_mfma_f32_16x16x32_bf16 v[4:7], v[164:167], v[216:219], v[4:7]
	v_mfma_f32_16x16x32_bf16 v[0:3], v[184:187], v[216:219], v[0:3]
	s_barrier
	s_setprio 0
	s_add_i32 s60, s60, 2
	s_add_u32 s58, s58, 0x100
	s_addc_u32 s59, s59, 0
	s_add_u32 s6, s6, 0x100
	s_addc_u32 s7, s7, 0
	s_cmp_gt_u32 s60, 29
	s_cbranch_scc0 .LBB0_1385
	s_and_b64 vcc, exec, s[20:21]
	s_cbranch_vccz .LBB0_1388
	s_barrier

; #define PG8_STAGE(bufoff, gbase, voff) do { _Pragma("unroll") for (int _i = 0; _i < 2; ++_i) \
;         __builtin_amdgcn_global_load_lds((const unsigned*)((const char*)(gbase) + (voff)[_i]), (PG8_LAS unsigned*)(lds + (bufoff) + ldsw + _i * 8192), 16, 0, 0); } while (0)
; #define PG8_LDA(dst, b, h) do { _Pragma("unroll") for (int m = 0; m < 4; ++m) _Pragma("unroll") for (int k = 0; k < 2; ++k) dst[m][k] = *(const PG8_LAS bf16x8*)(lds + PG8_SA(b, h) + aoff + m * 2048 + k * 1024); } while (0)
; #define PG8_LDB(dst, b, h) do { _Pragma("unroll") for (int n = 0; n < 2; ++n) _Pragma("unroll") for (int k = 0; k < 2; ++k) dst[n][k] = *(const PG8_LAS bf16x8*)(lds + PG8_SB(b, h) + boff + n * 2048 + k * 1024); } while (0)
; #define PG8_MMA(ai, bj, At, Bt) do { __builtin_amdgcn_s_setprio(1); _Pragma("unroll") for (int m = 0; m < 4; ++m) _Pragma("unroll") for (int n = 0; n < 2; ++n) _Pragma("unroll") for (int k = 0; k < 2; ++k) \
;         acc[ai][bj][m][n] = __builtin_amdgcn_mfma_f32_16x16x32_bf16(Bt[n][k], At[m][k], acc[ai][bj][m][n], 0, 0, 0); __builtin_amdgcn_s_setprio(0); } while (0)
; #define PG8_WAIT_V(n) asm volatile("s_waitcnt vmcnt(" #n ")" ::: "memory")
; #define PG8_WAIT_L(n) asm volatile("s_waitcnt lgkmcnt(" #n ")" ::: "memory")
; template <class Epi, class Sched, bool ALIGN_EPI = false, bool SP2 = false>
; __device__ __forceinline__ void gemm_phase(PG8_LAS unsigned char* lds, const Gemm g, const Sched& S, const Epi& E, const int wid) {
;     ...
;         for (int t = 0; t < nt; t += 2) {
;             const bool last = (t == nt - 2);
;             const char* a1 = cA + (size_t)(t + 1) * kstep;
;             const char* a2 = last ? nA : cA + (size_t)(t + 2) * kstep; const char* b2 = last ? nB : cB + (size_t)(t + 2) * kstep;
;             const char* a3 = a2 + kstep; const char* b3 = b2 + kstep;
;             if constexpr (SP2) {
;             PG8_LDB(B0, 0, 0); PG8_LDB(B1, 0, 1); PG8_SCHED; PG8_LDA(At, 0, 0); PG8_STAGE(PG8_SA(1, 1), a1 + hsA, voffA);
;             PG8_WAIT_V(8); PG8_WAIT_L(0); PG8_BAR; PG8_MMA(0, 0, At, B0); PG8_MMA(0, 1, At, B1); PG8_BAR; PG8_SCHED;
;             PG8_LDA(At, 0, 1); PG8_STAGE(PG8_SB(0, 0), b2, voffB); PG8_STAGE(PG8_SB(0, 1), b2 + hsB, voffB); PG8_STAGE(PG8_SA(0, 0), a2, voffA);
;             PG8_WAIT_V(8); PG8_WAIT_L(0); PG8_BAR; PG8_MMA(1, 0, At, B0); PG8_MMA(1, 1, At, B1); PG8_BAR; PG8_SCHED;
.LBB0_1462:
	ds_read_b128 v[128:131], v163
	ds_read_b128 v[132:135], v163 offset:1024
	ds_read_b128 v[136:139], v163 offset:2048
	ds_read_b128 v[140:143], v163 offset:3072
	ds_read_b128 v[156:159], v164
	ds_read_b128 v[166:169], v164 offset:1024
	ds_read_b128 v[170:173], v164 offset:2048
	ds_read_b128 v[174:177], v164 offset:3072
	s_add_u32 s28, s26, 0x100
	s_addc_u32 s29, s27, 0
	s_cmpk_eq_i32 s58, 0x54
	s_cselect_b32 s35, s5, s29
	s_cselect_b32 s34, s4, s28
	s_cselect_b32 s31, s25, s57
	s_cselect_b32 s30, s24, s56
	v_lshl_add_u64 v[160:161], s[26:27], 0, v[150:151]
	s_add_i32 m0, s40, 0xc000
	ds_read_b128 v[178:181], v165
	ds_read_b128 v[182:185], v165 offset:1024
	ds_read_b128 v[186:189], v165 offset:2048
	ds_read_b128 v[190:193], v165 offset:3072
	ds_read_b128 v[194:197], v165 offset:4096
	ds_read_b128 v[198:201], v165 offset:5120
	ds_read_b128 v[202:205], v165 offset:6144
	ds_read_b128 v[206:209], v165 offset:7168
	global_load_lds_dwordx4 v[160:161], off
	v_lshl_add_u64 v[160:161], s[26:27], 0, v[148:149]
	s_add_i32 m0, s40, 0xe000
	s_nop 0
	global_load_lds_dwordx4 v[160:161], off
	s_waitcnt vmcnt(8)
	s_waitcnt lgkmcnt(0)
	s_setprio 1
	s_barrier
	v_mfma_f32_16x16x32_bf16 v[124:127], v[128:131], v[178:181], v[124:127]
	v_mfma_f32_16x16x32_bf16 v[120:123], v[136:139], v[178:181], v[120:123]
	v_mfma_f32_16x16x32_bf16 v[116:119], v[128:131], v[186:189], v[116:119]
	v_mfma_f32_16x16x32_bf16 v[112:115], v[136:139], v[186:189], v[112:115]
	v_mfma_f32_16x16x32_bf16 v[92:95], v[128:131], v[194:197], v[92:95]
	v_mfma_f32_16x16x32_bf16 v[88:91], v[136:139], v[194:197], v[88:91]
	v_mfma_f32_16x16x32_bf16 v[84:87], v[128:131], v[202:205], v[84:87]
	v_mfma_f32_16x16x32_bf16 v[80:83], v[136:139], v[202:205], v[80:83]
	v_mfma_f32_16x16x32_bf16 v[124:127], v[132:135], v[182:185], v[124:127]
	v_mfma_f32_16x16x32_bf16 v[120:123], v[140:143], v[182:185], v[120:123]
	v_mfma_f32_16x16x32_bf16 v[116:119], v[132:135], v[190:193], v[116:119]
	v_mfma_f32_16x16x32_bf16 v[112:115], v[140:143], v[190:193], v[112:115]
	v_mfma_f32_16x16x32_bf16 v[92:95], v[132:135], v[198:201], v[92:95]
	v_mfma_f32_16x16x32_bf16 v[88:91], v[140:143], v[198:201], v[88:91]
	v_mfma_f32_16x16x32_bf16 v[84:87], v[132:135], v[206:209], v[84:87]
	v_mfma_f32_16x16x32_bf16 v[80:83], v[140:143], v[206:209], v[80:83]
	s_setprio 0
	s_setprio 1
	v_mfma_f32_16x16x32_bf16 v[108:111], v[156:159], v[178:181], v[108:111]
	v_mfma_f32_16x16x32_bf16 v[104:107], v[170:173], v[178:181], v[104:107]
	v_mfma_f32_16x16x32_bf16 v[100:103], v[156:159], v[186:189], v[100:103]
	v_mfma_f32_16x16x32_bf16 v[96:99], v[170:173], v[186:189], v[96:99]
	v_mfma_f32_16x16x32_bf16 v[76:79], v[156:159], v[194:197], v[76:79]
	v_mfma_f32_16x16x32_bf16 v[72:75], v[170:173], v[194:197], v[72:75]
	v_mfma_f32_16x16x32_bf16 v[68:71], v[156:159], v[202:205], v[68:71]
	v_mfma_f32_16x16x32_bf16 v[64:67], v[170:173], v[202:205], v[64:67]
	v_mfma_f32_16x16x32_bf16 v[108:111], v[166:169], v[182:185], v[108:111]
	v_mfma_f32_16x16x32_bf16 v[104:107], v[174:177], v[182:185], v[104:107]
	v_mfma_f32_16x16x32_bf16 v[100:103], v[166:169], v[190:193], v[100:103]
	v_mfma_f32_16x16x32_bf16 v[96:99], v[174:177], v[190:193], v[96:99]
	v_mfma_f32_16x16x32_bf16 v[76:79], v[166:169], v[198:201], v[76:79]
	v_mfma_f32_16x16x32_bf16 v[72:75], v[174:177], v[198:201], v[72:75]
	v_mfma_f32_16x16x32_bf16 v[68:71], v[166:169], v[206:209], v[68:71]
	v_mfma_f32_16x16x32_bf16 v[64:67], v[174:177], v[206:209], v[64:67]
	s_barrier
	s_setprio 0
	s_add_i32 s26, s50, s39
	v_lshl_add_u64 v[160:161], s[30:31], 0, v[144:145]
	s_mov_b32 m0, s26
	ds_read_b128 v[178:181], v165 offset:16384
	ds_read_b128 v[182:185], v165 offset:17408
	ds_read_b128 v[186:189], v165 offset:18432
	ds_read_b128 v[190:193], v165 offset:19456
	ds_read_b128 v[194:197], v165 offset:20480
	ds_read_b128 v[198:201], v165 offset:21504
	ds_read_b128 v[202:205], v165 offset:22528
	ds_read_b128 v[206:209], v165 offset:23552
	global_load_lds_dwordx4 v[160:161], off
	s_add_i32 m0, s26, 0x2000
	s_add_u32 s26, s30, 0x160000
	v_lshl_add_u64 v[210:211], s[30:31], 0, v[146:147]
	s_addc_u32 s27, s31, 0
	s_add_i32 s59, s51, s39
	global_load_lds_dwordx4 v[210:211], off
	v_lshl_add_u64 v[212:213], s[26:27], 0, v[144:145]
	s_mov_b32 m0, s59
	v_lshl_add_u64 v[214:215], s[34:35], 0, v[146:147]
	global_load_lds_dwordx4 v[212:213], off
	v_lshl_add_u64 v[212:213], s[26:27], 0, v[146:147]
	s_add_i32 m0, s59, 0x2000
	s_nop 0
	global_load_lds_dwordx4 v[212:213], off
	v_lshl_add_u64 v[212:213], s[34:35], 0, v[144:145]
	s_mov_b32 m0, s40
	s_nop 0
	global_load_lds_dwordx4 v[212:213], off
	s_mov_b32 m0, s41
	s_nop 0
	global_load_lds_dwordx4 v[214:215], off
	s_waitcnt vmcnt(8)
	s_waitcnt lgkmcnt(0)
	s_setprio 1
	s_barrier
; #define PG8_STAGE(bufoff, gbase, voff) do { _Pragma("unroll") for (int _i = 0; _i < 2; ++_i) \
;         __builtin_amdgcn_global_load_lds((const unsigned*)((const char*)(gbase) + (voff)[_i]), (PG8_LAS unsigned*)(lds + (bufoff) + ldsw + _i * 8192), 16, 0, 0); } while (0)
; #define PG8_LDA(dst, b, h) do { _Pragma("unroll") for (int m = 0; m < 4; ++m) _Pragma("unroll") for (int k = 0; k < 2; ++k) dst[m][k] = *(const PG8_LAS bf16x8*)(lds + PG8_SA(b, h) + aoff + m * 2048 + k * 1024); } while (0)
; #define PG8_LDB(dst, b, h) do { _Pragma("unroll") for (int n = 0; n < 2; ++n) _Pragma("unroll") for (int k = 0; k < 2; ++k) dst[n][k] = *(const PG8_LAS bf16x8*)(lds + PG8_SB(b, h) + boff + n * 2048 + k * 1024); } while (0)
; #define PG8_MMA(ai, bj, At, Bt) do { __builtin_amdgcn_s_setprio(1); _Pragma("unroll") for (int m = 0; m < 4; ++m) _Pragma("unroll") for (int n = 0; n < 2; ++n) _Pragma("unroll") for (int k = 0; k < 2; ++k) \
;         acc[ai][bj][m][n] = __builtin_amdgcn_mfma_f32_16x16x32_bf16(Bt[n][k], At[m][k], acc[ai][bj][m][n], 0, 0, 0); __builtin_amdgcn_s_setprio(0); } while (0)
; #define PG8_WAIT_V(n) asm volatile("s_waitcnt vmcnt(" #n ")" ::: "memory")
; #define PG8_WAIT_L(n) asm volatile("s_waitcnt lgkmcnt(" #n ")" ::: "memory")
; #define PG8_BAR __builtin_amdgcn_s_barrier()
; #define PG8_SCHED __builtin_amdgcn_sched_barrier(0)
; template <class Epi, class Sched, bool ALIGN_EPI = false, bool SP2 = false>
; __device__ __forceinline__ void gemm_phase(PG8_LAS unsigned char* lds, const Gemm g, const Sched& S, const Epi& E, const int wid) {
;     ...
;             PG8_WAIT_V(8); PG8_WAIT_L(0); PG8_BAR; PG8_MMA(1, 0, At, B0); PG8_MMA(1, 1, At, B1); PG8_BAR; PG8_SCHED;
;             PG8_LDB(B0, 1, 0); PG8_LDB(B1, 1, 1); PG8_SCHED; PG8_LDA(At, 1, 0); PG8_STAGE(PG8_SA(0, 1), a2 + hsA, voffA);
;             PG8_WAIT_V(8); PG8_WAIT_L(0); PG8_BAR; PG8_MMA(0, 0, At, B0); PG8_MMA(0, 1, At, B1); PG8_BAR; PG8_SCHED;
	v_mfma_f32_16x16x32_bf16 v[60:63], v[128:131], v[178:181], v[60:63]
	v_mfma_f32_16x16x32_bf16 v[56:59], v[136:139], v[178:181], v[56:59]
	v_mfma_f32_16x16x32_bf16 v[52:55], v[128:131], v[186:189], v[52:55]
	v_mfma_f32_16x16x32_bf16 v[48:51], v[136:139], v[186:189], v[48:51]
	v_mfma_f32_16x16x32_bf16 v[28:31], v[128:131], v[194:197], v[28:31]
	v_mfma_f32_16x16x32_bf16 v[24:27], v[136:139], v[194:197], v[24:27]
	v_mfma_f32_16x16x32_bf16 v[20:23], v[128:131], v[202:205], v[20:23]
	v_mfma_f32_16x16x32_bf16 v[16:19], v[136:139], v[202:205], v[16:19]
	v_mfma_f32_16x16x32_bf16 v[60:63], v[132:135], v[182:185], v[60:63]
	v_mfma_f32_16x16x32_bf16 v[56:59], v[140:143], v[182:185], v[56:59]
	v_mfma_f32_16x16x32_bf16 v[52:55], v[132:135], v[190:193], v[52:55]
	v_mfma_f32_16x16x32_bf16 v[48:51], v[140:143], v[190:193], v[48:51]
	v_mfma_f32_16x16x32_bf16 v[28:31], v[132:135], v[198:201], v[28:31]
	v_mfma_f32_16x16x32_bf16 v[24:27], v[140:143], v[198:201], v[24:27]
	v_mfma_f32_16x16x32_bf16 v[20:23], v[132:135], v[206:209], v[20:23]
	v_mfma_f32_16x16x32_bf16 v[16:19], v[140:143], v[206:209], v[16:19]
	s_setprio 0
	s_setprio 1
	v_mfma_f32_16x16x32_bf16 v[44:47], v[156:159], v[178:181], v[44:47]
	v_mfma_f32_16x16x32_bf16 v[40:43], v[170:173], v[178:181], v[40:43]
	v_mfma_f32_16x16x32_bf16 v[36:39], v[156:159], v[186:189], v[36:39]
	v_mfma_f32_16x16x32_bf16 v[32:35], v[170:173], v[186:189], v[32:35]
	v_mfma_f32_16x16x32_bf16 v[12:15], v[156:159], v[194:197], v[12:15]
	v_mfma_f32_16x16x32_bf16 v[8:11], v[170:173], v[194:197], v[8:11]
	v_mfma_f32_16x16x32_bf16 v[4:7], v[156:159], v[202:205], v[4:7]
	v_mfma_f32_16x16x32_bf16 v[0:3], v[170:173], v[202:205], v[0:3]
	v_mfma_f32_16x16x32_bf16 v[44:47], v[166:169], v[182:185], v[44:47]
	v_mfma_f32_16x16x32_bf16 v[40:43], v[174:177], v[182:185], v[40:43]
	v_mfma_f32_16x16x32_bf16 v[36:39], v[166:169], v[190:193], v[36:39]
	v_mfma_f32_16x16x32_bf16 v[32:35], v[174:177], v[190:193], v[32:35]
	v_mfma_f32_16x16x32_bf16 v[12:15], v[166:169], v[198:201], v[12:15]
	v_mfma_f32_16x16x32_bf16 v[8:11], v[174:177], v[198:201], v[8:11]
	v_mfma_f32_16x16x32_bf16 v[4:7], v[166:169], v[206:209], v[4:7]
	v_mfma_f32_16x16x32_bf16 v[0:3], v[174:177], v[206:209], v[0:3]
	s_barrier
	s_setprio 0
	s_add_i32 s59, 0, 0x18000
	s_add_i32 s60, 0, 0x1c000
	v_add_u32_e32 v140, s59, v162
	v_add_u32_e32 v174, s60, v162
	ds_read_b128 v[128:131], v140
	ds_read_b128 v[132:135], v140 offset:1024
	ds_read_b128 v[136:139], v140 offset:2048
	ds_read_b128 v[140:143], v140 offset:3072
	ds_read_b128 v[156:159], v174
	ds_read_b128 v[166:169], v174 offset:1024
	ds_read_b128 v[170:173], v174 offset:2048
	ds_read_b128 v[174:177], v174 offset:3072
	s_add_u32 s26, s34, 0x160000
	s_addc_u32 s27, s35, 0
	s_mov_b32 m0, s42
	v_lshl_add_u64 v[216:217], s[26:27], 0, v[144:145]
	ds_read_b128 v[178:181], v165 offset:32768
	ds_read_b128 v[182:185], v165 offset:33792
	ds_read_b128 v[186:189], v165 offset:34816
	ds_read_b128 v[190:193], v165 offset:35840
	ds_read_b128 v[194:197], v165 offset:36864
	ds_read_b128 v[198:201], v165 offset:37888
	ds_read_b128 v[202:205], v165 offset:38912
	ds_read_b128 v[206:209], v165 offset:39936
	global_load_lds_dwordx4 v[216:217], off
	v_lshl_add_u64 v[216:217], s[26:27], 0, v[146:147]
	s_mov_b32 m0, s43
	s_nop 0
	global_load_lds_dwordx4 v[216:217], off
	s_waitcnt vmcnt(8)
	s_waitcnt lgkmcnt(0)
	s_setprio 1
	s_barrier
	v_mfma_f32_16x16x32_bf16 v[124:127], v[128:131], v[178:181], v[124:127]
	v_mfma_f32_16x16x32_bf16 v[120:123], v[136:139], v[178:181], v[120:123]
	v_mfma_f32_16x16x32_bf16 v[116:119], v[128:131], v[186:189], v[116:119]
	v_mfma_f32_16x16x32_bf16 v[112:115], v[136:139], v[186:189], v[112:115]
	v_mfma_f32_16x16x32_bf16 v[92:95], v[128:131], v[194:197], v[92:95]
	v_mfma_f32_16x16x32_bf16 v[88:91], v[136:139], v[194:197], v[88:91]
	v_mfma_f32_16x16x32_bf16 v[84:87], v[128:131], v[202:205], v[84:87]
	v_mfma_f32_16x16x32_bf16 v[80:83], v[136:139], v[202:205], v[80:83]
	v_mfma_f32_16x16x32_bf16 v[124:127], v[132:135], v[182:185], v[124:127]
	v_mfma_f32_16x16x32_bf16 v[120:123], v[140:143], v[182:185], v[120:123]
	v_mfma_f32_16x16x32_bf16 v[116:119], v[132:135], v[190:193], v[116:119]
	v_mfma_f32_16x16x32_bf16 v[112:115], v[140:143], v[190:193], v[112:115]
	v_mfma_f32_16x16x32_bf16 v[92:95], v[132:135], v[198:201], v[92:95]
	v_mfma_f32_16x16x32_bf16 v[88:91], v[140:143], v[198:201], v[88:91]
	v_mfma_f32_16x16x32_bf16 v[84:87], v[132:135], v[206:209], v[84:87]
	v_mfma_f32_16x16x32_bf16 v[80:83], v[140:143], v[206:209], v[80:83]
	s_setprio 0
	s_setprio 1
	v_mfma_f32_16x16x32_bf16 v[108:111], v[156:159], v[178:181], v[108:111]
	v_mfma_f32_16x16x32_bf16 v[104:107], v[170:173], v[178:181], v[104:107]
	v_mfma_f32_16x16x32_bf16 v[100:103], v[156:159], v[186:189], v[100:103]
	v_mfma_f32_16x16x32_bf16 v[96:99], v[170:173], v[186:189], v[96:99]
	v_mfma_f32_16x16x32_bf16 v[76:79], v[156:159], v[194:197], v[76:79]
	v_mfma_f32_16x16x32_bf16 v[72:75], v[170:173], v[194:197], v[72:75]
	v_mfma_f32_16x16x32_bf16 v[68:71], v[156:159], v[202:205], v[68:71]
	v_mfma_f32_16x16x32_bf16 v[64:67], v[170:173], v[202:205], v[64:67]
	v_mfma_f32_16x16x32_bf16 v[108:111], v[166:169], v[182:185], v[108:111]
	v_mfma_f32_16x16x32_bf16 v[104:107], v[174:177], v[182:185], v[104:107]
	v_mfma_f32_16x16x32_bf16 v[100:103], v[166:169], v[190:193], v[100:103]
	v_mfma_f32_16x16x32_bf16 v[96:99], v[174:177], v[190:193], v[96:99]
	v_mfma_f32_16x16x32_bf16 v[76:79], v[166:169], v[198:201], v[76:79]
	v_mfma_f32_16x16x32_bf16 v[72:75], v[174:177], v[198:201], v[72:75]
	v_mfma_f32_16x16x32_bf16 v[68:71], v[166:169], v[206:209], v[68:71]
	v_mfma_f32_16x16x32_bf16 v[64:67], v[174:177], v[206:209], v[64:67]
	s_barrier
; #define PG8_STAGE(bufoff, gbase, voff) do { _Pragma("unroll") for (int _i = 0; _i < 2; ++_i) \
;         __builtin_amdgcn_global_load_lds((const unsigned*)((const char*)(gbase) + (voff)[_i]), (PG8_LAS unsigned*)(lds + (bufoff) + ldsw + _i * 8192), 16, 0, 0); } while (0)
; #define PG8_LDA(dst, b, h) do { _Pragma("unroll") for (int m = 0; m < 4; ++m) _Pragma("unroll") for (int k = 0; k < 2; ++k) dst[m][k] = *(const PG8_LAS bf16x8*)(lds + PG8_SA(b, h) + aoff + m * 2048 + k * 1024); } while (0)
; #define PG8_MMA(ai, bj, At, Bt) do { __builtin_amdgcn_s_setprio(1); _Pragma("unroll") for (int m = 0; m < 4; ++m) _Pragma("unroll") for (int n = 0; n < 2; ++n) _Pragma("unroll") for (int k = 0; k < 2; ++k) \
;         acc[ai][bj][m][n] = __builtin_amdgcn_mfma_f32_16x16x32_bf16(Bt[n][k], At[m][k], acc[ai][bj][m][n], 0, 0, 0); __builtin_amdgcn_s_setprio(0); } while (0)
; #define PG8_WAIT_V(n) asm volatile("s_waitcnt vmcnt(" #n ")" ::: "memory")
; #define PG8_WAIT_L(n) asm volatile("s_waitcnt lgkmcnt(" #n ")" ::: "memory")
; #define PG8_BAR __builtin_amdgcn_s_barrier()
; #define PG8_SCHED __builtin_amdgcn_sched_barrier(0)
; template <class Epi, class Sched, bool ALIGN_EPI = false, bool SP2 = false>
; __device__ __forceinline__ void gemm_phase(PG8_LAS unsigned char* lds, const Gemm g, const Sched& S, const Epi& E, const int wid) {
;     ...
;             PG8_LDA(At, 1, 1); PG8_STAGE(PG8_SB(1, 0), b3, voffB); PG8_STAGE(PG8_SB(1, 1), b3 + hsB, voffB); PG8_STAGE(PG8_SA(1, 0), a3, voffA);
;             PG8_WAIT_V(8); PG8_WAIT_L(0); PG8_BAR; PG8_MMA(1, 0, At, B0); PG8_MMA(1, 1, At, B1); PG8_BAR; PG8_SCHED;
	s_setprio 0
	s_add_i32 s26, s59, s39
	v_lshl_add_u64 v[160:161], v[160:161], 0, s[14:15]
	s_mov_b32 m0, s26
	ds_read_b128 v[178:181], v165 offset:49152
	ds_read_b128 v[182:185], v165 offset:50176
	ds_read_b128 v[186:189], v165 offset:51200
	ds_read_b128 v[190:193], v165 offset:52224
	ds_read_b128 v[194:197], v165 offset:53248
	ds_read_b128 v[198:201], v165 offset:54272
	ds_read_b128 v[202:205], v165 offset:55296
	ds_read_b128 v[206:209], v165 offset:56320
	global_load_lds_dwordx4 v[160:161], off
	s_add_i32 m0, s26, 0x2000
	s_add_u32 s26, s30, 0x160080
	v_lshl_add_u64 v[160:161], v[210:211], 0, s[14:15]
	s_addc_u32 s27, s31, 0
	s_add_i32 s30, s60, s39
	global_load_lds_dwordx4 v[160:161], off
	v_lshl_add_u64 v[160:161], s[26:27], 0, v[144:145]
	s_mov_b32 m0, s30
	s_nop 0
	global_load_lds_dwordx4 v[160:161], off
	v_lshl_add_u64 v[160:161], s[26:27], 0, v[146:147]
	s_add_i32 m0, s30, 0x2000
	s_nop 0
	global_load_lds_dwordx4 v[160:161], off
	v_lshl_add_u64 v[160:161], v[212:213], 0, s[14:15]
	s_mov_b32 m0, s47
	s_nop 0
	global_load_lds_dwordx4 v[160:161], off
	v_lshl_add_u64 v[160:161], v[214:215], 0, s[14:15]
	s_mov_b32 m0, s48
	s_nop 0
	global_load_lds_dwordx4 v[160:161], off
	s_waitcnt vmcnt(8)
	s_waitcnt lgkmcnt(0)
	s_setprio 1
	s_barrier
	v_mfma_f32_16x16x32_bf16 v[60:63], v[128:131], v[178:181], v[60:63]
	v_mfma_f32_16x16x32_bf16 v[56:59], v[136:139], v[178:181], v[56:59]
	v_mfma_f32_16x16x32_bf16 v[52:55], v[128:131], v[186:189], v[52:55]
	v_mfma_f32_16x16x32_bf16 v[48:51], v[136:139], v[186:189], v[48:51]
	v_mfma_f32_16x16x32_bf16 v[28:31], v[128:131], v[194:197], v[28:31]
	v_mfma_f32_16x16x32_bf16 v[24:27], v[136:139], v[194:197], v[24:27]
	v_mfma_f32_16x16x32_bf16 v[20:23], v[128:131], v[202:205], v[20:23]
	v_mfma_f32_16x16x32_bf16 v[16:19], v[136:139], v[202:205], v[16:19]
	v_mfma_f32_16x16x32_bf16 v[60:63], v[132:135], v[182:185], v[60:63]
	v_mfma_f32_16x16x32_bf16 v[56:59], v[140:143], v[182:185], v[56:59]
	v_mfma_f32_16x16x32_bf16 v[52:55], v[132:135], v[190:193], v[52:55]
	v_mfma_f32_16x16x32_bf16 v[48:51], v[140:143], v[190:193], v[48:51]
	v_mfma_f32_16x16x32_bf16 v[28:31], v[132:135], v[198:201], v[28:31]
	v_mfma_f32_16x16x32_bf16 v[24:27], v[140:143], v[198:201], v[24:27]
	v_mfma_f32_16x16x32_bf16 v[20:23], v[132:135], v[206:209], v[20:23]
	v_mfma_f32_16x16x32_bf16 v[16:19], v[140:143], v[206:209], v[16:19]
	s_setprio 0
	s_setprio 1
	v_mfma_f32_16x16x32_bf16 v[44:47], v[156:159], v[178:181], v[44:47]
	v_mfma_f32_16x16x32_bf16 v[40:43], v[170:173], v[178:181], v[40:43]
	v_mfma_f32_16x16x32_bf16 v[36:39], v[156:159], v[186:189], v[36:39]
	v_mfma_f32_16x16x32_bf16 v[32:35], v[170:173], v[186:189], v[32:35]
	v_mfma_f32_16x16x32_bf16 v[12:15], v[156:159], v[194:197], v[12:15]
	v_mfma_f32_16x16x32_bf16 v[8:11], v[170:173], v[194:197], v[8:11]
	v_mfma_f32_16x16x32_bf16 v[4:7], v[156:159], v[202:205], v[4:7]
	v_mfma_f32_16x16x32_bf16 v[0:3], v[170:173], v[202:205], v[0:3]
	v_mfma_f32_16x16x32_bf16 v[44:47], v[166:169], v[182:185], v[44:47]
	v_mfma_f32_16x16x32_bf16 v[40:43], v[174:177], v[182:185], v[40:43]
	v_mfma_f32_16x16x32_bf16 v[36:39], v[166:169], v[190:193], v[36:39]
	v_mfma_f32_16x16x32_bf16 v[32:35], v[174:177], v[190:193], v[32:35]
	v_mfma_f32_16x16x32_bf16 v[12:15], v[166:169], v[198:201], v[12:15]
	v_mfma_f32_16x16x32_bf16 v[8:11], v[174:177], v[198:201], v[8:11]
	v_mfma_f32_16x16x32_bf16 v[4:7], v[166:169], v[206:209], v[4:7]
	v_mfma_f32_16x16x32_bf16 v[0:3], v[174:177], v[206:209], v[0:3]
	s_barrier
	s_setprio 0
	s_add_i32 s58, s58, 2
	s_add_u32 s56, s56, 0x100
	s_addc_u32 s57, s57, 0
	s_cmpk_gt_u32 s58, 0x55
	s_mov_b64 s[26:27], s[28:29]
	s_cbranch_scc0 .LBB0_1462
	s_and_b64 vcc, exec, s[16:17]
	s_cbranch_vccz .LBB0_1465
	s_barrier
